# S5-output and GLU GEMM epilogues: per-row input loads hoisted in two batches, loop-invariant bias/skip loads loaded once instead of 16x
# speedup vs baseline: 1.0077x; 1.0077x over previous
; __device__ __forceinline__ unsigned cvt_pk_bf16(float lo, float hi) { unsigned r; asm volatile("v_cvt_pk_bf16_f32 %0, %1, %2" : "=v"(r) : "v"(lo), "v"(hi)); return r; }
; __device__ __forceinline__ float gelu_t(float x) { const float z = 1.5957691216f * (x + 0.044715f * x * x * x); return x * sigm(z); }
; __device__ __forceinline__ void UNPACK8(const u32x4 q, float (&f)[8]) { f[0] = bflo(q.x); f[1] = bfhi(q.x); f[2] = bflo(q.y); f[3] = bfhi(q.y); f[4] = bflo(q.z); f[5] = bfhi(q.z); f[6] = bflo(q.w); f[7] = bfhi(q.w); }
; #define EPI_FOR_ROWS() _Pragma("unroll") for (int ai = 0; ai < 2; ++ai) _Pragma("unroll") for (int m = 0; m < 4; ++m)
; __device__ __forceinline__ float sigm(float x) { return __builtin_amdgcn_rcpf(1.0f + __expf(-x)); }
;     __device__ __forceinline__ void operator()(const f32x4 (&acc)[2][2][4][2], const Unit& u, int wr, int wc, int fr, int fq) const {
;     ...
;         EPI_FOR_ROWS() {
;             const int gr = row0 + ai * 128 + m * 16, chunk = gr & 2047;
; #pragma unroll
;             for (int bj = 0; bj < 2; ++bj) { const int col = col0 + bj * 128, t = col >> 4, h0 = col & 15;
;                 const u32x4 uw = *(const u32x4*)(a2 + (size_t)gr * 384 + col); float uu[8]; UNPACK8(uw, uu);
;                 const f32x4 d0 = *(const f32x4*)(dsk + g * 16 + h0), d1 = *(const f32x4*)(dsk + g * 16 + h0 + 4); float o[8];
; #pragma unroll
;                 for (int e = 0; e < 4; ++e) { o[e] = gelu_t(acc[ai][bj][m][0][e] + d0[e] * uu[e]); o[4 + e] = gelu_t(acc[ai][bj][m][1][e] + d1[e] * uu[4 + e]); }
;                 u32x4 w; w.x = cvt_pk_bf16(o[0], o[1]); w.y = cvt_pk_bf16(o[2], o[3]); w.z = cvt_pk_bf16(o[4], o[5]); w.w = cvt_pk_bf16(o[6], o[7]);
;                 *(u32x4*)(yg + ((size_t)chunk * 16 + t) * 512 + g * 16 + h0) = w; }
.LBB0_801:
	v_lshl_add_u32 v158, s49, 8, v150
	v_lshlrev_b32_e32 v128, 4, v158
	v_mad_i64_i32 v[144:145], s[38:39], v158, s41, v[138:139]
	v_and_b32_e32 v159, 0x7cf0, v128
	s_lshl_b32 s4, s48, 4
	s_ashr_i32 s5, s4, 31
	v_lshl_add_u64 v[142:143], s[4:5], 2, v[136:137]
	s_lshl_b64 vcc, s[4:5], 1
	global_load_dwordx4 v[200:203], v[144:145], off
	global_load_dwordx4 v[192:195], v[142:143], off offset:16
	global_load_dwordx4 v[196:199], v[142:143], off
	global_load_dwordx4 v[214:217], v[144:145], off offset:256
	v_or_b32_e32 v180, 16, v158
	v_mad_i64_i32 v[182:183], s[4:5], v180, s41, v[138:139]
	global_load_dwordx4 v[218:221], v[182:183], off
	v_or_b32_e32 v180, 16, v158
	v_mad_i64_i32 v[182:183], s[4:5], v180, s41, v[138:139]
	global_load_dwordx4 v[222:225], v[182:183], off offset:256
	v_or_b32_e32 v180, 32, v158
	v_mad_i64_i32 v[182:183], s[4:5], v180, s41, v[138:139]
	global_load_dwordx4 v[226:229], v[182:183], off
	v_or_b32_e32 v180, 32, v158
	v_mad_i64_i32 v[182:183], s[4:5], v180, s41, v[138:139]
	global_load_dwordx4 v[230:233], v[182:183], off offset:256
	v_or_b32_e32 v180, 48, v158
	v_mad_i64_i32 v[182:183], s[4:5], v180, s41, v[138:139]
	global_load_dwordx4 v[234:237], v[182:183], off
	v_or_b32_e32 v180, 48, v158
	v_mad_i64_i32 v[182:183], s[4:5], v180, s41, v[138:139]
	global_load_dwordx4 v[238:241], v[182:183], off offset:256
	s_waitcnt vmcnt(0)
	v_mov_b32_e32 v128, v200
	v_mov_b32_e32 v129, v201
	v_mov_b32_e32 v130, v202
	v_mov_b32_e32 v131, v203
	v_lshlrev_b32_e32 v141, 16, v128
	v_and_b32_e32 v160, 0xffff0000, v128
	v_lshlrev_b32_e32 v166, 16, v129
	v_and_b32_e32 v167, 0xffff0000, v129
	v_lshlrev_b32_e32 v168, 16, v130
	v_and_b32_e32 v169, 0xffff0000, v130
	v_lshlrev_b32_e32 v178, 16, v131
	v_and_b32_e32 v179, 0xffff0000, v131
	v_mov_b32_e32 v128, v192
	v_mov_b32_e32 v129, v193
	v_mov_b32_e32 v130, v194
	v_mov_b32_e32 v131, v195
	v_mov_b32_e32 v132, v196
	v_mov_b32_e32 v133, v197
	v_mov_b32_e32 v134, v198
	v_mov_b32_e32 v135, v199
	v_fmac_f32_e32 v120, v128, v168
	v_mul_f32_e32 v128, 0x3d372713, v120
	v_mul_f32_e32 v128, v120, v128
	v_fma_f32 v128, v120, v128, v120
	v_mul_f32_e32 v128, 0x3fcc422a, v128
	v_mul_f32_e32 v128, 0xbfb8aa3b, v128
	v_exp_f32_e32 v128, v128
	v_fmac_f32_e32 v125, v133, v160
	v_fmac_f32_e32 v121, v129, v169
	v_fmac_f32_e32 v126, v134, v166
	v_add_f32_e32 v128, 1.0, v128
	v_rcp_f32_e32 v128, v128
	v_fmac_f32_e32 v122, v130, v178
	v_fmac_f32_e32 v127, v135, v167
	v_fmac_f32_e32 v124, v132, v141
	v_mul_f32_e32 v120, v120, v128
	v_mul_f32_e32 v128, 0x3d372713, v125
	v_mul_f32_e32 v128, v125, v128
	v_fma_f32 v128, v125, v128, v125
	v_mul_f32_e32 v128, 0x3fcc422a, v128
	v_mul_f32_e32 v128, 0xbfb8aa3b, v128
	v_exp_f32_e32 v128, v128
	v_mul_f32_e32 v132, 0x3d372713, v124
	v_fmac_f32_e32 v123, v131, v179
	v_mul_f32_e32 v132, v124, v132
	v_add_f32_e32 v128, 1.0, v128
	v_rcp_f32_e32 v128, v128
	v_fma_f32 v132, v124, v132, v124
	v_mul_f32_e32 v132, 0x3fcc422a, v132
	v_mul_f32_e32 v132, 0xbfb8aa3b, v132
	v_mul_f32_e32 v125, v125, v128
	v_mul_f32_e32 v128, 0x3d372713, v121
	v_mul_f32_e32 v128, v121, v128
	v_fma_f32 v128, v121, v128, v121
	v_mul_f32_e32 v128, 0x3fcc422a, v128
	v_mul_f32_e32 v128, 0xbfb8aa3b, v128
	v_exp_f32_e32 v128, v128
	v_exp_f32_e32 v132, v132
	v_mov_b32_e32 v141, v161
	v_add_f32_e32 v128, 1.0, v128
	v_rcp_f32_e32 v128, v128
	v_add_f32_e32 v132, 1.0, v132
	v_rcp_f32_e32 v132, v132
	v_mul_f32_e32 v121, v121, v128
	v_mul_f32_e32 v128, 0x3d372713, v126
	v_mul_f32_e32 v128, v126, v128
	v_fma_f32 v128, v126, v128, v126
	v_mul_f32_e32 v128, 0x3fcc422a, v128
	v_mul_f32_e32 v128, 0xbfb8aa3b, v128
	v_exp_f32_e32 v128, v128
	v_mul_f32_e32 v124, v124, v132
	v_add_f32_e32 v128, 1.0, v128
	v_rcp_f32_e32 v128, v128
	s_nop 0
	v_mul_f32_e32 v126, v126, v128
	v_mul_f32_e32 v128, 0x3d372713, v122
	v_mul_f32_e32 v128, v122, v128
	v_fma_f32 v128, v122, v128, v122
	v_mul_f32_e32 v128, 0x3fcc422a, v128
	v_mul_f32_e32 v128, 0xbfb8aa3b, v128
	v_exp_f32_e32 v128, v128
	s_nop 0
	v_add_f32_e32 v128, 1.0, v128
	v_rcp_f32_e32 v128, v128
	s_nop 0
	v_mul_f32_e32 v128, v122, v128
	v_mul_f32_e32 v122, 0x3d372713, v127
	v_mul_f32_e32 v122, v127, v122
	v_fma_f32 v122, v127, v122, v127
	v_mul_f32_e32 v122, 0x3fcc422a, v122
	v_mul_f32_e32 v122, 0xbfb8aa3b, v122
	v_exp_f32_e32 v122, v122
	s_nop 0
	v_add_f32_e32 v122, 1.0, v122
	v_rcp_f32_e32 v122, v122
	s_nop 0
	v_mul_f32_e32 v127, v127, v122
	v_mul_f32_e32 v122, 0x3d372713, v123
	v_mul_f32_e32 v122, v123, v122
	v_fma_f32 v122, v123, v122, v123
	v_mul_f32_e32 v122, 0x3fcc422a, v122
	v_mul_f32_e32 v122, 0xbfb8aa3b, v122
	v_exp_f32_e32 v122, v122
	s_nop 0
	v_add_f32_e32 v122, 1.0, v122
	v_rcp_f32_e32 v122, v122
	s_nop 0
	v_mul_f32_e32 v129, v123, v122
	v_cvt_pk_bf16_f32 v122, v124, v125
	v_cvt_pk_bf16_f32 v123, v126, v127
	v_cvt_pk_bf16_f32 v124, v120, v121
	v_or_b32_e32 v120, v159, v151
	v_lshlrev_b32_e32 v160, 10, v120
	v_lshl_add_u64 v[120:121], s[30:31], 0, v[160:161]
	v_lshl_add_u64 v[120:121], v[120:121], 0, vcc
	v_lshl_add_u64 v[120:121], v[120:121], 0, v[140:141]
	v_cvt_pk_bf16_f32 v125, v128, v129
	global_store_dwordx4 v[120:121], v[122:125], off
	v_mov_b32_e32 v120, v214
	v_mov_b32_e32 v121, v215
	v_mov_b32_e32 v122, v216
	v_mov_b32_e32 v123, v217
	v_lshlrev_b32_e32 v128, 16, v120
	v_and_b32_e32 v129, 0xffff0000, v120
	v_lshlrev_b32_e32 v130, 16, v121
	v_and_b32_e32 v131, 0xffff0000, v121
	v_lshlrev_b32_e32 v132, 16, v122
	v_and_b32_e32 v133, 0xffff0000, v122
	v_lshlrev_b32_e32 v134, 16, v123
	v_and_b32_e32 v135, 0xffff0000, v123
	v_mov_b32_e32 v120, v192
	v_mov_b32_e32 v121, v193
	v_mov_b32_e32 v122, v194
	v_mov_b32_e32 v123, v195
	v_mov_b32_e32 v124, v196
	v_mov_b32_e32 v125, v197
; __device__ __forceinline__ unsigned cvt_pk_bf16(float lo, float hi) { unsigned r; asm volatile("v_cvt_pk_bf16_f32 %0, %1, %2" : "=v"(r) : "v"(lo), "v"(hi)); return r; }
; __device__ __forceinline__ float gelu_t(float x) { const float z = 1.5957691216f * (x + 0.044715f * x * x * x); return x * sigm(z); }
; __device__ __forceinline__ void UNPACK8(const u32x4 q, float (&f)[8]) { f[0] = bflo(q.x); f[1] = bfhi(q.x); f[2] = bflo(q.y); f[3] = bfhi(q.y); f[4] = bflo(q.z); f[5] = bfhi(q.z); f[6] = bflo(q.w); f[7] = bfhi(q.w); }
; #define EPI_FOR_ROWS() _Pragma("unroll") for (int ai = 0; ai < 2; ++ai) _Pragma("unroll") for (int m = 0; m < 4; ++m)
; __device__ __forceinline__ float sigm(float x) { return __builtin_amdgcn_rcpf(1.0f + __expf(-x)); }
;     __device__ __forceinline__ void operator()(const f32x4 (&acc)[2][2][4][2], const Unit& u, int wr, int wc, int fr, int fq) const {
;     ...
;         EPI_FOR_ROWS() {
;             const int gr = row0 + ai * 128 + m * 16, chunk = gr & 2047;
; #pragma unroll
;             for (int bj = 0; bj < 2; ++bj) { const int col = col0 + bj * 128, t = col >> 4, h0 = col & 15;
;                 const u32x4 uw = *(const u32x4*)(a2 + (size_t)gr * 384 + col); float uu[8]; UNPACK8(uw, uu);
;                 const f32x4 d0 = *(const f32x4*)(dsk + g * 16 + h0), d1 = *(const f32x4*)(dsk + g * 16 + h0 + 4); float o[8];
; #pragma unroll
;                 for (int e = 0; e < 4; ++e) { o[e] = gelu_t(acc[ai][bj][m][0][e] + d0[e] * uu[e]); o[4 + e] = gelu_t(acc[ai][bj][m][1][e] + d1[e] * uu[4 + e]); }
;                 u32x4 w; w.x = cvt_pk_bf16(o[0], o[1]); w.y = cvt_pk_bf16(o[2], o[3]); w.z = cvt_pk_bf16(o[4], o[5]); w.w = cvt_pk_bf16(o[6], o[7]);
;                 *(u32x4*)(yg + ((size_t)chunk * 16 + t) * 512 + g * 16 + h0) = w; }
	v_mov_b32_e32 v126, v198
	v_mov_b32_e32 v127, v199
	v_fmac_f32_e32 v112, v120, v132
	v_mul_f32_e32 v120, 0x3d372713, v112
	v_mul_f32_e32 v120, v112, v120
	v_fma_f32 v120, v112, v120, v112
	v_mul_f32_e32 v120, 0x3fcc422a, v120
	v_mul_f32_e32 v120, 0xbfb8aa3b, v120
	v_exp_f32_e32 v120, v120
	v_fmac_f32_e32 v117, v125, v129
	v_fmac_f32_e32 v113, v121, v133
	v_fmac_f32_e32 v118, v126, v130
	v_add_f32_e32 v120, 1.0, v120
	v_rcp_f32_e32 v120, v120
	v_fmac_f32_e32 v114, v122, v134
	v_fmac_f32_e32 v119, v127, v131
	v_fmac_f32_e32 v116, v124, v128
	v_mul_f32_e32 v112, v112, v120
	v_mul_f32_e32 v120, 0x3d372713, v117
	v_mul_f32_e32 v120, v117, v120
	v_fma_f32 v120, v117, v120, v117
	v_mul_f32_e32 v120, 0x3fcc422a, v120
	v_mul_f32_e32 v120, 0xbfb8aa3b, v120
	v_exp_f32_e32 v120, v120
	v_mul_f32_e32 v124, 0x3d372713, v116
	v_fmac_f32_e32 v115, v123, v135
	v_mul_f32_e32 v124, v116, v124
	v_add_f32_e32 v120, 1.0, v120
	v_rcp_f32_e32 v120, v120
	v_fma_f32 v124, v116, v124, v116
	v_mul_f32_e32 v124, 0x3fcc422a, v124
	v_mul_f32_e32 v124, 0xbfb8aa3b, v124
	v_mul_f32_e32 v117, v117, v120
	v_mul_f32_e32 v120, 0x3d372713, v113
	v_mul_f32_e32 v120, v113, v120
	v_fma_f32 v120, v113, v120, v113
	v_mul_f32_e32 v120, 0x3fcc422a, v120
	v_mul_f32_e32 v120, 0xbfb8aa3b, v120
	v_exp_f32_e32 v120, v120
	v_exp_f32_e32 v124, v124
	v_add_f32_e32 v120, 1.0, v120
	v_rcp_f32_e32 v120, v120
	v_add_f32_e32 v124, 1.0, v124
	v_rcp_f32_e32 v124, v124
	v_mul_f32_e32 v113, v113, v120
	v_mul_f32_e32 v120, 0x3d372713, v118
	v_mul_f32_e32 v120, v118, v120
	v_fma_f32 v120, v118, v120, v118
	v_mul_f32_e32 v120, 0x3fcc422a, v120
	v_mul_f32_e32 v120, 0xbfb8aa3b, v120
	v_exp_f32_e32 v120, v120
	v_mul_f32_e32 v116, v116, v124
	v_add_f32_e32 v120, 1.0, v120
	v_rcp_f32_e32 v120, v120
	s_nop 0
	v_mul_f32_e32 v118, v118, v120
	v_mul_f32_e32 v120, 0x3d372713, v114
	v_mul_f32_e32 v120, v114, v120
	v_fma_f32 v120, v114, v120, v114
	v_mul_f32_e32 v120, 0x3fcc422a, v120
	v_mul_f32_e32 v120, 0xbfb8aa3b, v120
	v_exp_f32_e32 v120, v120
	s_nop 0
	v_add_f32_e32 v120, 1.0, v120
	v_rcp_f32_e32 v120, v120
	s_nop 0
	v_mul_f32_e32 v120, v114, v120
	v_mul_f32_e32 v114, 0x3d372713, v119
	v_mul_f32_e32 v114, v119, v114
	v_fma_f32 v114, v119, v114, v119
	v_mul_f32_e32 v114, 0x3fcc422a, v114
	v_mul_f32_e32 v114, 0xbfb8aa3b, v114
	v_exp_f32_e32 v114, v114
	s_nop 0
	v_add_f32_e32 v114, 1.0, v114
	v_rcp_f32_e32 v114, v114
	s_nop 0
	v_mul_f32_e32 v119, v119, v114
	v_mul_f32_e32 v114, 0x3d372713, v115
	v_mul_f32_e32 v114, v115, v114
	v_fma_f32 v114, v115, v114, v115
	v_mul_f32_e32 v114, 0x3fcc422a, v114
	v_mul_f32_e32 v114, 0xbfb8aa3b, v114
	v_exp_f32_e32 v114, v114
	s_nop 0
	v_add_f32_e32 v114, 1.0, v114
	v_rcp_f32_e32 v114, v114
	s_nop 0
	v_mul_f32_e32 v121, v115, v114
	v_cvt_pk_bf16_f32 v114, v116, v117
	v_cvt_pk_bf16_f32 v115, v118, v119
	v_cvt_pk_bf16_f32 v116, v112, v113
	v_or_b32_e32 v112, v159, v152
	v_lshlrev_b32_e32 v160, 10, v112
	v_lshl_add_u64 v[112:113], s[30:31], 0, v[160:161]
	v_lshl_add_u64 v[112:113], v[112:113], 0, vcc
	v_lshl_add_u64 v[112:113], v[112:113], 0, v[140:141]
	v_cvt_pk_bf16_f32 v117, v120, v121
	global_store_dwordx4 v[112:113], v[114:117], off
	v_or_b32_e32 v112, 16, v158
	v_lshlrev_b32_e32 v113, 4, v112
	v_mad_i64_i32 v[120:121], s[4:5], v112, s41, v[138:139]
	v_and_b32_e32 v122, 0x7df0, v113
	v_mov_b32_e32 v112, v218
	v_mov_b32_e32 v113, v219
	v_mov_b32_e32 v114, v220
	v_mov_b32_e32 v115, v221
	v_lshlrev_b32_e32 v123, 16, v112
	v_and_b32_e32 v124, 0xffff0000, v112
	v_lshlrev_b32_e32 v125, 16, v113
	v_and_b32_e32 v126, 0xffff0000, v113
	v_lshlrev_b32_e32 v127, 16, v114
	v_and_b32_e32 v128, 0xffff0000, v114
	v_lshlrev_b32_e32 v129, 16, v115
	v_and_b32_e32 v130, 0xffff0000, v115
	v_mov_b32_e32 v112, v192
	v_mov_b32_e32 v113, v193
	v_mov_b32_e32 v114, v194
	v_mov_b32_e32 v115, v195
	v_mov_b32_e32 v116, v196
	v_mov_b32_e32 v117, v197
	v_mov_b32_e32 v118, v198
	v_mov_b32_e32 v119, v199
	v_fmac_f32_e32 v104, v112, v127
	v_mul_f32_e32 v112, 0x3d372713, v104
	v_mul_f32_e32 v112, v104, v112
	v_fma_f32 v112, v104, v112, v104
	v_mul_f32_e32 v112, 0x3fcc422a, v112
	v_mul_f32_e32 v112, 0xbfb8aa3b, v112
	v_exp_f32_e32 v112, v112
	v_fmac_f32_e32 v109, v117, v124
	v_fmac_f32_e32 v105, v113, v128
	v_fmac_f32_e32 v110, v118, v125
	v_add_f32_e32 v112, 1.0, v112
	v_rcp_f32_e32 v112, v112
	v_fmac_f32_e32 v106, v114, v129
	v_fmac_f32_e32 v111, v119, v126
	v_fmac_f32_e32 v108, v116, v123
	v_mul_f32_e32 v104, v104, v112
	v_mul_f32_e32 v112, 0x3d372713, v109
	v_mul_f32_e32 v112, v109, v112
	v_fma_f32 v112, v109, v112, v109
	v_mul_f32_e32 v112, 0x3fcc422a, v112
	v_mul_f32_e32 v112, 0xbfb8aa3b, v112
	v_exp_f32_e32 v112, v112
	v_mul_f32_e32 v116, 0x3d372713, v108
	v_fmac_f32_e32 v107, v115, v130
	v_mul_f32_e32 v116, v108, v116
	v_add_f32_e32 v112, 1.0, v112
	v_rcp_f32_e32 v112, v112
	v_fma_f32 v116, v108, v116, v108
	v_mul_f32_e32 v116, 0x3fcc422a, v116
	v_mul_f32_e32 v116, 0xbfb8aa3b, v116
	v_mul_f32_e32 v109, v109, v112
	v_mul_f32_e32 v112, 0x3d372713, v105
	v_mul_f32_e32 v112, v105, v112
	v_fma_f32 v112, v105, v112, v105
	v_mul_f32_e32 v112, 0x3fcc422a, v112
	v_mul_f32_e32 v112, 0xbfb8aa3b, v112
	v_exp_f32_e32 v112, v112
	v_exp_f32_e32 v116, v116
	v_add_f32_e32 v112, 1.0, v112
	v_rcp_f32_e32 v112, v112
	v_add_f32_e32 v116, 1.0, v116
	v_rcp_f32_e32 v116, v116
	v_mul_f32_e32 v105, v105, v112
	v_mul_f32_e32 v112, 0x3d372713, v110
	v_mul_f32_e32 v112, v110, v112
	v_fma_f32 v112, v110, v112, v110
	v_mul_f32_e32 v112, 0x3fcc422a, v112
	v_mul_f32_e32 v112, 0xbfb8aa3b, v112
	v_exp_f32_e32 v112, v112
	v_mul_f32_e32 v108, v108, v116
	v_add_f32_e32 v112, 1.0, v112
	v_rcp_f32_e32 v112, v112
	s_nop 0
	v_mul_f32_e32 v110, v110, v112
; __device__ __forceinline__ unsigned cvt_pk_bf16(float lo, float hi) { unsigned r; asm volatile("v_cvt_pk_bf16_f32 %0, %1, %2" : "=v"(r) : "v"(lo), "v"(hi)); return r; }
; __device__ __forceinline__ float gelu_t(float x) { const float z = 1.5957691216f * (x + 0.044715f * x * x * x); return x * sigm(z); }
; __device__ __forceinline__ void UNPACK8(const u32x4 q, float (&f)[8]) { f[0] = bflo(q.x); f[1] = bfhi(q.x); f[2] = bflo(q.y); f[3] = bfhi(q.y); f[4] = bflo(q.z); f[5] = bfhi(q.z); f[6] = bflo(q.w); f[7] = bfhi(q.w); }
; #define EPI_FOR_ROWS() _Pragma("unroll") for (int ai = 0; ai < 2; ++ai) _Pragma("unroll") for (int m = 0; m < 4; ++m)
; __device__ __forceinline__ float sigm(float x) { return __builtin_amdgcn_rcpf(1.0f + __expf(-x)); }
;     __device__ __forceinline__ void operator()(const f32x4 (&acc)[2][2][4][2], const Unit& u, int wr, int wc, int fr, int fq) const {
;     ...
;         EPI_FOR_ROWS() {
;             const int gr = row0 + ai * 128 + m * 16, chunk = gr & 2047;
; #pragma unroll
;             for (int bj = 0; bj < 2; ++bj) { const int col = col0 + bj * 128, t = col >> 4, h0 = col & 15;
;                 const u32x4 uw = *(const u32x4*)(a2 + (size_t)gr * 384 + col); float uu[8]; UNPACK8(uw, uu);
;                 const f32x4 d0 = *(const f32x4*)(dsk + g * 16 + h0), d1 = *(const f32x4*)(dsk + g * 16 + h0 + 4); float o[8];
; #pragma unroll
;                 for (int e = 0; e < 4; ++e) { o[e] = gelu_t(acc[ai][bj][m][0][e] + d0[e] * uu[e]); o[4 + e] = gelu_t(acc[ai][bj][m][1][e] + d1[e] * uu[4 + e]); }
;                 u32x4 w; w.x = cvt_pk_bf16(o[0], o[1]); w.y = cvt_pk_bf16(o[2], o[3]); w.z = cvt_pk_bf16(o[4], o[5]); w.w = cvt_pk_bf16(o[6], o[7]);
;                 *(u32x4*)(yg + ((size_t)chunk * 16 + t) * 512 + g * 16 + h0) = w; }
	v_mul_f32_e32 v112, 0x3d372713, v106
	v_mul_f32_e32 v112, v106, v112
	v_fma_f32 v112, v106, v112, v106
	v_mul_f32_e32 v112, 0x3fcc422a, v112
	v_mul_f32_e32 v112, 0xbfb8aa3b, v112
	v_exp_f32_e32 v112, v112
	s_nop 0
	v_add_f32_e32 v112, 1.0, v112
	v_rcp_f32_e32 v112, v112
	s_nop 0
	v_mul_f32_e32 v112, v106, v112
	v_mul_f32_e32 v106, 0x3d372713, v111
	v_mul_f32_e32 v106, v111, v106
	v_fma_f32 v106, v111, v106, v111
	v_mul_f32_e32 v106, 0x3fcc422a, v106
	v_mul_f32_e32 v106, 0xbfb8aa3b, v106
	v_exp_f32_e32 v106, v106
	s_nop 0
	v_add_f32_e32 v106, 1.0, v106
	v_rcp_f32_e32 v106, v106
	s_nop 0
	v_mul_f32_e32 v111, v111, v106
	v_mul_f32_e32 v106, 0x3d372713, v107
	v_mul_f32_e32 v106, v107, v106
	v_fma_f32 v106, v107, v106, v107
	v_mul_f32_e32 v106, 0x3fcc422a, v106
	v_mul_f32_e32 v106, 0xbfb8aa3b, v106
	v_exp_f32_e32 v106, v106
	s_nop 0
	v_add_f32_e32 v106, 1.0, v106
	v_rcp_f32_e32 v106, v106
	s_nop 0
	v_mul_f32_e32 v113, v107, v106
	v_cvt_pk_bf16_f32 v106, v108, v109
	v_cvt_pk_bf16_f32 v107, v110, v111
	v_cvt_pk_bf16_f32 v108, v104, v105
	v_or_b32_e32 v104, v122, v151
	v_lshlrev_b32_e32 v160, 10, v104
	v_lshl_add_u64 v[104:105], s[30:31], 0, v[160:161]
	v_lshl_add_u64 v[104:105], v[104:105], 0, vcc
	v_lshl_add_u64 v[104:105], v[104:105], 0, v[140:141]
	v_cvt_pk_bf16_f32 v109, v112, v113
	global_store_dwordx4 v[104:105], v[106:109], off
	v_mov_b32_e32 v104, v222
	v_mov_b32_e32 v105, v223
	v_mov_b32_e32 v106, v224
	v_mov_b32_e32 v107, v225
	v_lshlrev_b32_e32 v112, 16, v104
	v_and_b32_e32 v113, 0xffff0000, v104
	v_lshlrev_b32_e32 v114, 16, v105
	v_and_b32_e32 v115, 0xffff0000, v105
	v_lshlrev_b32_e32 v116, 16, v106
	v_and_b32_e32 v117, 0xffff0000, v106
	v_lshlrev_b32_e32 v118, 16, v107
	v_and_b32_e32 v119, 0xffff0000, v107
	v_mov_b32_e32 v104, v192
	v_mov_b32_e32 v105, v193
	v_mov_b32_e32 v106, v194
	v_mov_b32_e32 v107, v195
	v_mov_b32_e32 v108, v196
	v_mov_b32_e32 v109, v197
	v_mov_b32_e32 v110, v198
	v_mov_b32_e32 v111, v199
	v_fmac_f32_e32 v96, v104, v116
	v_mul_f32_e32 v104, 0x3d372713, v96
	v_mul_f32_e32 v104, v96, v104
	v_fma_f32 v104, v96, v104, v96
	v_mul_f32_e32 v104, 0x3fcc422a, v104
	v_mul_f32_e32 v104, 0xbfb8aa3b, v104
	v_exp_f32_e32 v104, v104
	v_fmac_f32_e32 v101, v109, v113
	v_fmac_f32_e32 v97, v105, v117
	v_fmac_f32_e32 v102, v110, v114
	v_add_f32_e32 v104, 1.0, v104
	v_rcp_f32_e32 v104, v104
	v_fmac_f32_e32 v98, v106, v118
	v_fmac_f32_e32 v103, v111, v115
	v_fmac_f32_e32 v100, v108, v112
	v_mul_f32_e32 v96, v96, v104
	v_mul_f32_e32 v104, 0x3d372713, v101
	v_mul_f32_e32 v104, v101, v104
	v_fma_f32 v104, v101, v104, v101
	v_mul_f32_e32 v104, 0x3fcc422a, v104
	v_mul_f32_e32 v104, 0xbfb8aa3b, v104
	v_exp_f32_e32 v104, v104
	v_mul_f32_e32 v108, 0x3d372713, v100
	v_fmac_f32_e32 v99, v107, v119
	v_mul_f32_e32 v108, v100, v108
	v_add_f32_e32 v104, 1.0, v104
	v_rcp_f32_e32 v104, v104
	v_fma_f32 v108, v100, v108, v100
	v_mul_f32_e32 v108, 0x3fcc422a, v108
	v_mul_f32_e32 v108, 0xbfb8aa3b, v108
	v_mul_f32_e32 v101, v101, v104
	v_mul_f32_e32 v104, 0x3d372713, v97
	v_mul_f32_e32 v104, v97, v104
	v_fma_f32 v104, v97, v104, v97
	v_mul_f32_e32 v104, 0x3fcc422a, v104
	v_mul_f32_e32 v104, 0xbfb8aa3b, v104
	v_exp_f32_e32 v104, v104
	v_exp_f32_e32 v108, v108
	v_add_f32_e32 v104, 1.0, v104
	v_rcp_f32_e32 v104, v104
	v_add_f32_e32 v108, 1.0, v108
	v_rcp_f32_e32 v108, v108
	v_mul_f32_e32 v97, v97, v104
	v_mul_f32_e32 v104, 0x3d372713, v102
	v_mul_f32_e32 v104, v102, v104
	v_fma_f32 v104, v102, v104, v102
	v_mul_f32_e32 v104, 0x3fcc422a, v104
	v_mul_f32_e32 v104, 0xbfb8aa3b, v104
	v_exp_f32_e32 v104, v104
	v_mul_f32_e32 v100, v100, v108
	v_add_f32_e32 v104, 1.0, v104
	v_rcp_f32_e32 v104, v104
	s_nop 0
	v_mul_f32_e32 v102, v102, v104
	v_mul_f32_e32 v104, 0x3d372713, v98
	v_mul_f32_e32 v104, v98, v104
	v_fma_f32 v104, v98, v104, v98
	v_mul_f32_e32 v104, 0x3fcc422a, v104
	v_mul_f32_e32 v104, 0xbfb8aa3b, v104
	v_exp_f32_e32 v104, v104
	s_nop 0
	v_add_f32_e32 v104, 1.0, v104
	v_rcp_f32_e32 v104, v104
	s_nop 0
	v_mul_f32_e32 v104, v98, v104
	v_mul_f32_e32 v98, 0x3d372713, v103
	v_mul_f32_e32 v98, v103, v98
	v_fma_f32 v98, v103, v98, v103
	v_mul_f32_e32 v98, 0x3fcc422a, v98
	v_mul_f32_e32 v98, 0xbfb8aa3b, v98
	v_exp_f32_e32 v98, v98
	s_nop 0
	v_add_f32_e32 v98, 1.0, v98
	v_rcp_f32_e32 v98, v98
	s_nop 0
	v_mul_f32_e32 v103, v103, v98
	v_mul_f32_e32 v98, 0x3d372713, v99
	v_mul_f32_e32 v98, v99, v98
	v_fma_f32 v98, v99, v98, v99
	v_mul_f32_e32 v98, 0x3fcc422a, v98
	v_mul_f32_e32 v98, 0xbfb8aa3b, v98
	v_exp_f32_e32 v98, v98
	s_nop 0
	v_add_f32_e32 v98, 1.0, v98
	v_rcp_f32_e32 v98, v98
	s_nop 0
	v_mul_f32_e32 v105, v99, v98
	v_cvt_pk_bf16_f32 v98, v100, v101
	v_cvt_pk_bf16_f32 v99, v102, v103
	v_cvt_pk_bf16_f32 v100, v96, v97
	v_or_b32_e32 v96, v122, v152
	v_lshlrev_b32_e32 v160, 10, v96
	v_lshl_add_u64 v[96:97], s[30:31], 0, v[160:161]
	v_lshl_add_u64 v[96:97], v[96:97], 0, vcc
	v_lshl_add_u64 v[96:97], v[96:97], 0, v[140:141]
	v_cvt_pk_bf16_f32 v101, v104, v105
	global_store_dwordx4 v[96:97], v[98:101], off
	v_or_b32_e32 v96, 32, v158
	v_lshlrev_b32_e32 v97, 4, v96
	v_mad_i64_i32 v[104:105], s[4:5], v96, s41, v[138:139]
	v_and_b32_e32 v106, 0x7ef0, v97
	v_mov_b32_e32 v96, v226
	v_mov_b32_e32 v97, v227
	v_mov_b32_e32 v98, v228
	v_mov_b32_e32 v99, v229
	v_lshlrev_b32_e32 v108, 16, v96
	v_and_b32_e32 v109, 0xffff0000, v96
	v_lshlrev_b32_e32 v110, 16, v97
	v_and_b32_e32 v111, 0xffff0000, v97
	v_lshlrev_b32_e32 v112, 16, v98
	v_and_b32_e32 v113, 0xffff0000, v98
	v_lshlrev_b32_e32 v114, 16, v99
	v_and_b32_e32 v107, 0xffff0000, v99
	v_mov_b32_e32 v96, v192
	v_mov_b32_e32 v97, v193
	v_mov_b32_e32 v98, v194
	v_mov_b32_e32 v99, v195
	v_mov_b32_e32 v100, v196
; __device__ __forceinline__ unsigned cvt_pk_bf16(float lo, float hi) { unsigned r; asm volatile("v_cvt_pk_bf16_f32 %0, %1, %2" : "=v"(r) : "v"(lo), "v"(hi)); return r; }
; __device__ __forceinline__ float gelu_t(float x) { const float z = 1.5957691216f * (x + 0.044715f * x * x * x); return x * sigm(z); }
; __device__ __forceinline__ void UNPACK8(const u32x4 q, float (&f)[8]) { f[0] = bflo(q.x); f[1] = bfhi(q.x); f[2] = bflo(q.y); f[3] = bfhi(q.y); f[4] = bflo(q.z); f[5] = bfhi(q.z); f[6] = bflo(q.w); f[7] = bfhi(q.w); }
; #define EPI_FOR_ROWS() _Pragma("unroll") for (int ai = 0; ai < 2; ++ai) _Pragma("unroll") for (int m = 0; m < 4; ++m)
; __device__ __forceinline__ float sigm(float x) { return __builtin_amdgcn_rcpf(1.0f + __expf(-x)); }
;     __device__ __forceinline__ void operator()(const f32x4 (&acc)[2][2][4][2], const Unit& u, int wr, int wc, int fr, int fq) const {
;     ...
;         EPI_FOR_ROWS() {
;             const int gr = row0 + ai * 128 + m * 16, chunk = gr & 2047;
; #pragma unroll
;             for (int bj = 0; bj < 2; ++bj) { const int col = col0 + bj * 128, t = col >> 4, h0 = col & 15;
;                 const u32x4 uw = *(const u32x4*)(a2 + (size_t)gr * 384 + col); float uu[8]; UNPACK8(uw, uu);
;                 const f32x4 d0 = *(const f32x4*)(dsk + g * 16 + h0), d1 = *(const f32x4*)(dsk + g * 16 + h0 + 4); float o[8];
; #pragma unroll
;                 for (int e = 0; e < 4; ++e) { o[e] = gelu_t(acc[ai][bj][m][0][e] + d0[e] * uu[e]); o[4 + e] = gelu_t(acc[ai][bj][m][1][e] + d1[e] * uu[4 + e]); }
;                 u32x4 w; w.x = cvt_pk_bf16(o[0], o[1]); w.y = cvt_pk_bf16(o[2], o[3]); w.z = cvt_pk_bf16(o[4], o[5]); w.w = cvt_pk_bf16(o[6], o[7]);
;                 *(u32x4*)(yg + ((size_t)chunk * 16 + t) * 512 + g * 16 + h0) = w; }
	v_mov_b32_e32 v101, v197
	v_mov_b32_e32 v102, v198
	v_mov_b32_e32 v103, v199
	v_fmac_f32_e32 v88, v96, v112
	v_mul_f32_e32 v96, 0x3d372713, v88
	v_mul_f32_e32 v96, v88, v96
	v_fma_f32 v96, v88, v96, v88
	v_mul_f32_e32 v96, 0x3fcc422a, v96
	v_mul_f32_e32 v96, 0xbfb8aa3b, v96
	v_exp_f32_e32 v96, v96
	v_fmac_f32_e32 v93, v101, v109
	v_fmac_f32_e32 v89, v97, v113
	v_fmac_f32_e32 v94, v102, v110
	v_add_f32_e32 v96, 1.0, v96
	v_rcp_f32_e32 v96, v96
	v_fmac_f32_e32 v90, v98, v114
	v_fmac_f32_e32 v95, v103, v111
	v_fmac_f32_e32 v92, v100, v108
	v_mul_f32_e32 v96, v88, v96
	v_mul_f32_e32 v88, 0x3d372713, v93
	v_mul_f32_e32 v88, v93, v88
	v_fma_f32 v88, v93, v88, v93
	v_mul_f32_e32 v88, 0x3fcc422a, v88
	v_mul_f32_e32 v88, 0xbfb8aa3b, v88
	v_exp_f32_e32 v88, v88
	v_mul_f32_e32 v100, 0x3d372713, v92
	v_mul_f32_e32 v100, v92, v100
	v_fma_f32 v100, v92, v100, v92
	v_add_f32_e32 v88, 1.0, v88
	v_rcp_f32_e32 v88, v88
	v_mul_f32_e32 v100, 0x3fcc422a, v100
	v_mul_f32_e32 v100, 0xbfb8aa3b, v100
	v_fmac_f32_e32 v91, v99, v107
	v_mul_f32_e32 v88, v93, v88
	v_mul_f32_e32 v93, 0x3d372713, v89
	v_mul_f32_e32 v93, v89, v93
	v_fma_f32 v93, v89, v93, v89
	v_mul_f32_e32 v93, 0x3fcc422a, v93
	v_mul_f32_e32 v93, 0xbfb8aa3b, v93
	v_exp_f32_e32 v93, v93
	v_exp_f32_e32 v100, v100
	v_add_f32_e32 v93, 1.0, v93
	v_rcp_f32_e32 v93, v93
	v_add_f32_e32 v100, 1.0, v100
	v_rcp_f32_e32 v100, v100
	v_mul_f32_e32 v93, v89, v93
	v_mul_f32_e32 v89, 0x3d372713, v94
	v_mul_f32_e32 v89, v94, v89
	v_fma_f32 v89, v94, v89, v94
	v_mul_f32_e32 v89, 0x3fcc422a, v89
	v_mul_f32_e32 v89, 0xbfb8aa3b, v89
	v_exp_f32_e32 v89, v89
	v_mul_f32_e32 v92, v92, v100
	v_cvt_pk_bf16_f32 v88, v92, v88
	v_or_b32_e32 v92, v106, v151
	v_add_f32_e32 v89, 1.0, v89
	v_rcp_f32_e32 v89, v89
	v_lshlrev_b32_e32 v160, 10, v92
	v_mul_f32_e32 v89, v94, v89
	v_mul_f32_e32 v94, 0x3d372713, v90
	v_mul_f32_e32 v94, v90, v94
	v_fma_f32 v94, v90, v94, v90
	v_mul_f32_e32 v94, 0x3fcc422a, v94
	v_mul_f32_e32 v94, 0xbfb8aa3b, v94
	v_exp_f32_e32 v94, v94
	s_nop 0
	v_add_f32_e32 v94, 1.0, v94
	v_rcp_f32_e32 v94, v94
	s_nop 0
	v_mul_f32_e32 v94, v90, v94
	v_mul_f32_e32 v90, 0x3d372713, v95
	v_mul_f32_e32 v90, v95, v90
	v_fma_f32 v90, v95, v90, v95
	v_mul_f32_e32 v90, 0x3fcc422a, v90
	v_mul_f32_e32 v90, 0xbfb8aa3b, v90
	v_exp_f32_e32 v90, v90
	s_nop 0
	v_add_f32_e32 v90, 1.0, v90
	v_rcp_f32_e32 v90, v90
	s_nop 0
	v_mul_f32_e32 v90, v95, v90
	v_mul_f32_e32 v95, 0x3d372713, v91
	v_mul_f32_e32 v95, v91, v95
	v_fma_f32 v95, v91, v95, v91
	v_mul_f32_e32 v95, 0x3fcc422a, v95
	v_mul_f32_e32 v95, 0xbfb8aa3b, v95
	v_exp_f32_e32 v95, v95
	v_cvt_pk_bf16_f32 v89, v89, v90
	v_cvt_pk_bf16_f32 v90, v96, v93
	v_lshl_add_u64 v[92:93], s[30:31], 0, v[160:161]
	v_add_f32_e32 v95, 1.0, v95
	v_rcp_f32_e32 v95, v95
	v_lshl_add_u64 v[92:93], v[92:93], 0, vcc
	v_lshl_add_u64 v[92:93], v[92:93], 0, v[140:141]
	v_mul_f32_e32 v91, v91, v95
	v_cvt_pk_bf16_f32 v91, v94, v91
	global_store_dwordx4 v[92:93], v[88:91], off
	s_nop 1
	v_mov_b32_e32 v88, v230
	v_mov_b32_e32 v89, v231
	v_mov_b32_e32 v90, v232
	v_mov_b32_e32 v91, v233
	v_lshlrev_b32_e32 v97, 16, v88
	v_and_b32_e32 v98, 0xffff0000, v88
	v_lshlrev_b32_e32 v99, 16, v89
	v_and_b32_e32 v100, 0xffff0000, v89
	v_lshlrev_b32_e32 v101, 16, v90
	v_and_b32_e32 v102, 0xffff0000, v90
	v_lshlrev_b32_e32 v103, 16, v91
	v_and_b32_e32 v96, 0xffff0000, v91
	v_mov_b32_e32 v88, v192
	v_mov_b32_e32 v89, v193
	v_mov_b32_e32 v90, v194
	v_mov_b32_e32 v91, v195
	v_mov_b32_e32 v92, v196
	v_mov_b32_e32 v93, v197
	v_mov_b32_e32 v94, v198
	v_mov_b32_e32 v95, v199
	v_fmac_f32_e32 v80, v88, v101
	v_mul_f32_e32 v88, 0x3d372713, v80
	v_mul_f32_e32 v88, v80, v88
	v_fma_f32 v88, v80, v88, v80
	v_mul_f32_e32 v88, 0x3fcc422a, v88
	v_mul_f32_e32 v88, 0xbfb8aa3b, v88
	v_exp_f32_e32 v88, v88
	v_fmac_f32_e32 v85, v93, v98
	v_fmac_f32_e32 v81, v89, v102
	v_fmac_f32_e32 v86, v94, v99
	v_add_f32_e32 v88, 1.0, v88
	v_rcp_f32_e32 v88, v88
	v_fmac_f32_e32 v82, v90, v103
	v_fmac_f32_e32 v87, v95, v100
	v_fmac_f32_e32 v84, v92, v97
	v_mul_f32_e32 v88, v80, v88
	v_mul_f32_e32 v80, 0x3d372713, v85
	v_mul_f32_e32 v80, v85, v80
	v_fma_f32 v80, v85, v80, v85
	v_mul_f32_e32 v80, 0x3fcc422a, v80
	v_mul_f32_e32 v80, 0xbfb8aa3b, v80
	v_exp_f32_e32 v80, v80
	v_mul_f32_e32 v92, 0x3d372713, v84
	v_mul_f32_e32 v92, v84, v92
	v_fma_f32 v92, v84, v92, v84
	v_add_f32_e32 v80, 1.0, v80
	v_rcp_f32_e32 v80, v80
	v_mul_f32_e32 v92, 0x3fcc422a, v92
	v_mul_f32_e32 v92, 0xbfb8aa3b, v92
	v_fmac_f32_e32 v83, v91, v96
	v_mul_f32_e32 v80, v85, v80
	v_mul_f32_e32 v85, 0x3d372713, v81
	v_mul_f32_e32 v85, v81, v85
	v_fma_f32 v85, v81, v85, v81
	v_mul_f32_e32 v85, 0x3fcc422a, v85
	v_mul_f32_e32 v85, 0xbfb8aa3b, v85
	v_exp_f32_e32 v85, v85
	v_exp_f32_e32 v92, v92
	v_add_f32_e32 v85, 1.0, v85
	v_rcp_f32_e32 v85, v85
	v_add_f32_e32 v92, 1.0, v92
	v_rcp_f32_e32 v92, v92
	v_mul_f32_e32 v85, v81, v85
	v_mul_f32_e32 v81, 0x3d372713, v86
	v_mul_f32_e32 v81, v86, v81
	v_fma_f32 v81, v86, v81, v86
	v_mul_f32_e32 v81, 0x3fcc422a, v81
	v_mul_f32_e32 v81, 0xbfb8aa3b, v81
	v_exp_f32_e32 v81, v81
	v_mul_f32_e32 v84, v84, v92
	v_cvt_pk_bf16_f32 v80, v84, v80
	v_or_b32_e32 v84, v106, v152
	v_add_f32_e32 v81, 1.0, v81
	v_rcp_f32_e32 v81, v81
	v_lshlrev_b32_e32 v160, 10, v84
	v_mul_f32_e32 v81, v86, v81
	v_mul_f32_e32 v86, 0x3d372713, v82
	v_mul_f32_e32 v86, v82, v86
	v_fma_f32 v86, v82, v86, v82
	v_mul_f32_e32 v86, 0x3fcc422a, v86
	v_mul_f32_e32 v86, 0xbfb8aa3b, v86
	v_exp_f32_e32 v86, v86
	s_nop 0
	v_add_f32_e32 v86, 1.0, v86
	v_rcp_f32_e32 v86, v86
	s_nop 0
	v_mul_f32_e32 v86, v82, v86
	v_mul_f32_e32 v82, 0x3d372713, v87
	v_mul_f32_e32 v82, v87, v82
	v_fma_f32 v82, v87, v82, v87
; __device__ __forceinline__ unsigned cvt_pk_bf16(float lo, float hi) { unsigned r; asm volatile("v_cvt_pk_bf16_f32 %0, %1, %2" : "=v"(r) : "v"(lo), "v"(hi)); return r; }
; __device__ __forceinline__ float gelu_t(float x) { const float z = 1.5957691216f * (x + 0.044715f * x * x * x); return x * sigm(z); }
; __device__ __forceinline__ void UNPACK8(const u32x4 q, float (&f)[8]) { f[0] = bflo(q.x); f[1] = bfhi(q.x); f[2] = bflo(q.y); f[3] = bfhi(q.y); f[4] = bflo(q.z); f[5] = bfhi(q.z); f[6] = bflo(q.w); f[7] = bfhi(q.w); }
; #define EPI_FOR_ROWS() _Pragma("unroll") for (int ai = 0; ai < 2; ++ai) _Pragma("unroll") for (int m = 0; m < 4; ++m)
; __device__ __forceinline__ float sigm(float x) { return __builtin_amdgcn_rcpf(1.0f + __expf(-x)); }
;     __device__ __forceinline__ void operator()(const f32x4 (&acc)[2][2][4][2], const Unit& u, int wr, int wc, int fr, int fq) const {
;     ...
;         EPI_FOR_ROWS() {
;             const int gr = row0 + ai * 128 + m * 16, chunk = gr & 2047;
; #pragma unroll
;             for (int bj = 0; bj < 2; ++bj) { const int col = col0 + bj * 128, t = col >> 4, h0 = col & 15;
;                 const u32x4 uw = *(const u32x4*)(a2 + (size_t)gr * 384 + col); float uu[8]; UNPACK8(uw, uu);
;                 const f32x4 d0 = *(const f32x4*)(dsk + g * 16 + h0), d1 = *(const f32x4*)(dsk + g * 16 + h0 + 4); float o[8];
; #pragma unroll
;                 for (int e = 0; e < 4; ++e) { o[e] = gelu_t(acc[ai][bj][m][0][e] + d0[e] * uu[e]); o[4 + e] = gelu_t(acc[ai][bj][m][1][e] + d1[e] * uu[4 + e]); }
;                 u32x4 w; w.x = cvt_pk_bf16(o[0], o[1]); w.y = cvt_pk_bf16(o[2], o[3]); w.z = cvt_pk_bf16(o[4], o[5]); w.w = cvt_pk_bf16(o[6], o[7]);
;                 *(u32x4*)(yg + ((size_t)chunk * 16 + t) * 512 + g * 16 + h0) = w; }
	v_mul_f32_e32 v82, 0x3fcc422a, v82
	v_mul_f32_e32 v82, 0xbfb8aa3b, v82
	v_exp_f32_e32 v82, v82
	s_nop 0
	v_add_f32_e32 v82, 1.0, v82
	v_rcp_f32_e32 v82, v82
	s_nop 0
	v_mul_f32_e32 v82, v87, v82
	v_mul_f32_e32 v87, 0x3d372713, v83
	v_mul_f32_e32 v87, v83, v87
	v_fma_f32 v87, v83, v87, v83
	v_mul_f32_e32 v87, 0x3fcc422a, v87
	v_mul_f32_e32 v87, 0xbfb8aa3b, v87
	v_exp_f32_e32 v87, v87
	v_cvt_pk_bf16_f32 v81, v81, v82
	v_cvt_pk_bf16_f32 v82, v88, v85
	v_lshl_add_u64 v[84:85], s[30:31], 0, v[160:161]
	v_add_f32_e32 v87, 1.0, v87
	v_rcp_f32_e32 v87, v87
	v_lshl_add_u64 v[84:85], v[84:85], 0, vcc
	v_lshl_add_u64 v[84:85], v[84:85], 0, v[140:141]
	v_mul_f32_e32 v83, v83, v87
	v_cvt_pk_bf16_f32 v83, v86, v83
	global_store_dwordx4 v[84:85], v[80:83], off
	s_nop 1
	v_or_b32_e32 v80, 48, v158
	v_lshlrev_b32_e32 v81, 4, v80
	v_mad_i64_i32 v[88:89], s[4:5], v80, s41, v[138:139]
	v_and_b32_e32 v90, 0x7ff0, v81
	v_mov_b32_e32 v80, v234
	v_mov_b32_e32 v81, v235
	v_mov_b32_e32 v82, v236
	v_mov_b32_e32 v83, v237
	v_lshlrev_b32_e32 v93, 16, v80
	v_and_b32_e32 v94, 0xffff0000, v80
	v_lshlrev_b32_e32 v95, 16, v81
	v_and_b32_e32 v92, 0xffff0000, v81
	v_lshlrev_b32_e32 v96, 16, v82
	v_and_b32_e32 v97, 0xffff0000, v82
	v_lshlrev_b32_e32 v98, 16, v83
	v_and_b32_e32 v91, 0xffff0000, v83
	v_mov_b32_e32 v80, v192
	v_mov_b32_e32 v81, v193
	v_mov_b32_e32 v82, v194
	v_mov_b32_e32 v83, v195
	v_mov_b32_e32 v84, v196
	v_mov_b32_e32 v85, v197
	v_mov_b32_e32 v86, v198
	v_mov_b32_e32 v87, v199
	v_fmac_f32_e32 v72, v80, v96
	v_mul_f32_e32 v80, 0x3d372713, v72
	v_mul_f32_e32 v80, v72, v80
	v_fma_f32 v80, v72, v80, v72
	v_mul_f32_e32 v80, 0x3fcc422a, v80
	v_mul_f32_e32 v80, 0xbfb8aa3b, v80
	v_exp_f32_e32 v80, v80
	v_fmac_f32_e32 v77, v85, v94
	v_fmac_f32_e32 v73, v81, v97
	v_fmac_f32_e32 v78, v86, v95
	v_add_f32_e32 v80, 1.0, v80
	v_rcp_f32_e32 v80, v80
	v_fmac_f32_e32 v74, v82, v98
	v_fmac_f32_e32 v79, v87, v92
	v_fmac_f32_e32 v76, v84, v93
	v_mul_f32_e32 v80, v72, v80
	v_mul_f32_e32 v72, 0x3d372713, v77
	v_mul_f32_e32 v72, v77, v72
	v_fma_f32 v72, v77, v72, v77
	v_mul_f32_e32 v72, 0x3fcc422a, v72
	v_mul_f32_e32 v72, 0xbfb8aa3b, v72
	v_exp_f32_e32 v72, v72
	v_mul_f32_e32 v84, 0x3d372713, v76
	v_mul_f32_e32 v84, v76, v84
	v_fma_f32 v84, v76, v84, v76
	v_add_f32_e32 v72, 1.0, v72
	v_rcp_f32_e32 v72, v72
	v_mul_f32_e32 v84, 0x3fcc422a, v84
	v_mul_f32_e32 v84, 0xbfb8aa3b, v84
	v_fmac_f32_e32 v75, v83, v91
	v_mul_f32_e32 v72, v77, v72
	v_mul_f32_e32 v77, 0x3d372713, v73
	v_mul_f32_e32 v77, v73, v77
	v_fma_f32 v77, v73, v77, v73
	v_mul_f32_e32 v77, 0x3fcc422a, v77
	v_mul_f32_e32 v77, 0xbfb8aa3b, v77
	v_exp_f32_e32 v77, v77
	v_exp_f32_e32 v84, v84
	v_add_f32_e32 v77, 1.0, v77
	v_rcp_f32_e32 v77, v77
	v_add_f32_e32 v84, 1.0, v84
	v_rcp_f32_e32 v84, v84
	v_mul_f32_e32 v77, v73, v77
	v_mul_f32_e32 v73, 0x3d372713, v78
	v_mul_f32_e32 v73, v78, v73
	v_fma_f32 v73, v78, v73, v78
	v_mul_f32_e32 v73, 0x3fcc422a, v73
	v_mul_f32_e32 v73, 0xbfb8aa3b, v73
	v_exp_f32_e32 v73, v73
	v_mul_f32_e32 v76, v76, v84
	v_cvt_pk_bf16_f32 v72, v76, v72
	v_or_b32_e32 v76, v90, v151
	v_add_f32_e32 v73, 1.0, v73
	v_rcp_f32_e32 v73, v73
	v_lshlrev_b32_e32 v160, 10, v76
	v_mul_f32_e32 v73, v78, v73
	v_mul_f32_e32 v78, 0x3d372713, v74
	v_mul_f32_e32 v78, v74, v78
	v_fma_f32 v78, v74, v78, v74
	v_mul_f32_e32 v78, 0x3fcc422a, v78
	v_mul_f32_e32 v78, 0xbfb8aa3b, v78
	v_exp_f32_e32 v78, v78
	s_nop 0
	v_add_f32_e32 v78, 1.0, v78
	v_rcp_f32_e32 v78, v78
	s_nop 0
	v_mul_f32_e32 v78, v74, v78
	v_mul_f32_e32 v74, 0x3d372713, v79
	v_mul_f32_e32 v74, v79, v74
	v_fma_f32 v74, v79, v74, v79
	v_mul_f32_e32 v74, 0x3fcc422a, v74
	v_mul_f32_e32 v74, 0xbfb8aa3b, v74
	v_exp_f32_e32 v74, v74
	s_nop 0
	v_add_f32_e32 v74, 1.0, v74
	v_rcp_f32_e32 v74, v74
	s_nop 0
	v_mul_f32_e32 v74, v79, v74
	v_mul_f32_e32 v79, 0x3d372713, v75
	v_mul_f32_e32 v79, v75, v79
	v_fma_f32 v79, v75, v79, v75
	v_mul_f32_e32 v79, 0x3fcc422a, v79
	v_mul_f32_e32 v79, 0xbfb8aa3b, v79
	v_exp_f32_e32 v79, v79
	v_cvt_pk_bf16_f32 v73, v73, v74
	v_cvt_pk_bf16_f32 v74, v80, v77
	v_lshl_add_u64 v[76:77], s[30:31], 0, v[160:161]
	v_add_f32_e32 v79, 1.0, v79
	v_rcp_f32_e32 v79, v79
	v_lshl_add_u64 v[76:77], v[76:77], 0, vcc
	v_lshl_add_u64 v[76:77], v[76:77], 0, v[140:141]
	v_mul_f32_e32 v75, v75, v79
	v_cvt_pk_bf16_f32 v75, v78, v75
	global_store_dwordx4 v[76:77], v[72:75], off
	s_nop 1
	v_mov_b32_e32 v72, v238
	v_mov_b32_e32 v73, v239
	v_mov_b32_e32 v74, v240
	v_mov_b32_e32 v75, v241
	v_lshlrev_b32_e32 v82, 16, v72
	v_and_b32_e32 v83, 0xffff0000, v72
	v_lshlrev_b32_e32 v84, 16, v73
	v_and_b32_e32 v81, 0xffff0000, v73
	v_lshlrev_b32_e32 v85, 16, v74
	v_and_b32_e32 v86, 0xffff0000, v74
	v_lshlrev_b32_e32 v87, 16, v75
	v_and_b32_e32 v80, 0xffff0000, v75
	v_mov_b32_e32 v72, v192
	v_mov_b32_e32 v73, v193
	v_mov_b32_e32 v74, v194
	v_mov_b32_e32 v75, v195
	v_mov_b32_e32 v76, v196
	v_mov_b32_e32 v77, v197
	v_mov_b32_e32 v78, v198
	v_mov_b32_e32 v79, v199
	v_fmac_f32_e32 v64, v72, v85
	v_mul_f32_e32 v72, 0x3d372713, v64
	v_mul_f32_e32 v72, v64, v72
	v_fma_f32 v72, v64, v72, v64
	v_mul_f32_e32 v72, 0x3fcc422a, v72
	v_mul_f32_e32 v72, 0xbfb8aa3b, v72
	v_exp_f32_e32 v72, v72
	v_fmac_f32_e32 v69, v77, v83
	v_fmac_f32_e32 v65, v73, v86
	v_fmac_f32_e32 v70, v78, v84
	v_add_f32_e32 v72, 1.0, v72
	v_rcp_f32_e32 v72, v72
	v_fmac_f32_e32 v66, v74, v87
	v_fmac_f32_e32 v71, v79, v81
	v_fmac_f32_e32 v68, v76, v82
	v_mul_f32_e32 v72, v64, v72
	v_mul_f32_e32 v64, 0x3d372713, v69
	v_mul_f32_e32 v64, v69, v64
	v_fma_f32 v64, v69, v64, v69
	v_mul_f32_e32 v64, 0x3fcc422a, v64
	v_mul_f32_e32 v64, 0xbfb8aa3b, v64
	v_exp_f32_e32 v64, v64
	v_mul_f32_e32 v76, 0x3d372713, v68
	v_mul_f32_e32 v76, v68, v76
; __device__ __forceinline__ unsigned cvt_pk_bf16(float lo, float hi) { unsigned r; asm volatile("v_cvt_pk_bf16_f32 %0, %1, %2" : "=v"(r) : "v"(lo), "v"(hi)); return r; }
; __device__ __forceinline__ float gelu_t(float x) { const float z = 1.5957691216f * (x + 0.044715f * x * x * x); return x * sigm(z); }
; __device__ __forceinline__ void UNPACK8(const u32x4 q, float (&f)[8]) { f[0] = bflo(q.x); f[1] = bfhi(q.x); f[2] = bflo(q.y); f[3] = bfhi(q.y); f[4] = bflo(q.z); f[5] = bfhi(q.z); f[6] = bflo(q.w); f[7] = bfhi(q.w); }
; #define EPI_FOR_ROWS() _Pragma("unroll") for (int ai = 0; ai < 2; ++ai) _Pragma("unroll") for (int m = 0; m < 4; ++m)
; __device__ __forceinline__ float sigm(float x) { return __builtin_amdgcn_rcpf(1.0f + __expf(-x)); }
;     __device__ __forceinline__ void operator()(const f32x4 (&acc)[2][2][4][2], const Unit& u, int wr, int wc, int fr, int fq) const {
;     ...
;         EPI_FOR_ROWS() {
;             const int gr = row0 + ai * 128 + m * 16, chunk = gr & 2047;
; #pragma unroll
;             for (int bj = 0; bj < 2; ++bj) { const int col = col0 + bj * 128, t = col >> 4, h0 = col & 15;
;                 const u32x4 uw = *(const u32x4*)(a2 + (size_t)gr * 384 + col); float uu[8]; UNPACK8(uw, uu);
;                 const f32x4 d0 = *(const f32x4*)(dsk + g * 16 + h0), d1 = *(const f32x4*)(dsk + g * 16 + h0 + 4); float o[8];
; #pragma unroll
;                 for (int e = 0; e < 4; ++e) { o[e] = gelu_t(acc[ai][bj][m][0][e] + d0[e] * uu[e]); o[4 + e] = gelu_t(acc[ai][bj][m][1][e] + d1[e] * uu[4 + e]); }
;                 u32x4 w; w.x = cvt_pk_bf16(o[0], o[1]); w.y = cvt_pk_bf16(o[2], o[3]); w.z = cvt_pk_bf16(o[4], o[5]); w.w = cvt_pk_bf16(o[6], o[7]);
;                 *(u32x4*)(yg + ((size_t)chunk * 16 + t) * 512 + g * 16 + h0) = w; }
	v_fma_f32 v76, v68, v76, v68
	v_add_f32_e32 v64, 1.0, v64
	v_rcp_f32_e32 v64, v64
	v_mul_f32_e32 v76, 0x3fcc422a, v76
	v_mul_f32_e32 v76, 0xbfb8aa3b, v76
	v_fmac_f32_e32 v67, v75, v80
	v_mul_f32_e32 v64, v69, v64
	v_mul_f32_e32 v69, 0x3d372713, v65
	v_mul_f32_e32 v69, v65, v69
	v_fma_f32 v69, v65, v69, v65
	v_mul_f32_e32 v69, 0x3fcc422a, v69
	v_mul_f32_e32 v69, 0xbfb8aa3b, v69
	v_exp_f32_e32 v69, v69
	v_exp_f32_e32 v76, v76
	v_add_f32_e32 v69, 1.0, v69
	v_rcp_f32_e32 v69, v69
	v_add_f32_e32 v76, 1.0, v76
	v_rcp_f32_e32 v76, v76
	v_mul_f32_e32 v69, v65, v69
	v_mul_f32_e32 v65, 0x3d372713, v70
	v_mul_f32_e32 v65, v70, v65
	v_fma_f32 v65, v70, v65, v70
	v_mul_f32_e32 v65, 0x3fcc422a, v65
	v_mul_f32_e32 v65, 0xbfb8aa3b, v65
	v_exp_f32_e32 v65, v65
	v_mul_f32_e32 v68, v68, v76
	v_cvt_pk_bf16_f32 v64, v68, v64
	v_or_b32_e32 v68, v90, v152
	v_add_f32_e32 v65, 1.0, v65
	v_rcp_f32_e32 v65, v65
	v_lshlrev_b32_e32 v160, 10, v68
	v_mul_f32_e32 v65, v70, v65
	v_mul_f32_e32 v70, 0x3d372713, v66
	v_mul_f32_e32 v70, v66, v70
	v_fma_f32 v70, v66, v70, v66
	v_mul_f32_e32 v70, 0x3fcc422a, v70
	v_mul_f32_e32 v70, 0xbfb8aa3b, v70
	v_exp_f32_e32 v70, v70
	s_nop 0
	v_add_f32_e32 v70, 1.0, v70
	v_rcp_f32_e32 v70, v70
	s_nop 0
	v_mul_f32_e32 v70, v66, v70
	v_mul_f32_e32 v66, 0x3d372713, v71
	v_mul_f32_e32 v66, v71, v66
	v_fma_f32 v66, v71, v66, v71
	v_mul_f32_e32 v66, 0x3fcc422a, v66
	v_mul_f32_e32 v66, 0xbfb8aa3b, v66
	v_exp_f32_e32 v66, v66
	s_nop 0
	v_add_f32_e32 v66, 1.0, v66
	v_rcp_f32_e32 v66, v66
	s_nop 0
	v_mul_f32_e32 v66, v71, v66
	v_mul_f32_e32 v71, 0x3d372713, v67
	v_mul_f32_e32 v71, v67, v71
	v_fma_f32 v71, v67, v71, v67
	v_mul_f32_e32 v71, 0x3fcc422a, v71
	v_mul_f32_e32 v71, 0xbfb8aa3b, v71
	v_exp_f32_e32 v71, v71
	v_cvt_pk_bf16_f32 v65, v65, v66
	v_cvt_pk_bf16_f32 v66, v72, v69
	v_lshl_add_u64 v[68:69], s[30:31], 0, v[160:161]
	v_add_f32_e32 v71, 1.0, v71
	v_rcp_f32_e32 v71, v71
	v_lshl_add_u64 v[68:69], v[68:69], 0, vcc
	v_lshl_add_u64 v[68:69], v[68:69], 0, v[140:141]
	v_mul_f32_e32 v67, v67, v71
	v_cvt_pk_bf16_f32 v67, v70, v67
	global_store_dwordx4 v[68:69], v[64:67], off
	s_nop 1
	v_add_u32_e32 v64, 0x80, v158
	v_lshlrev_b32_e32 v65, 4, v64
	v_mad_i64_i32 v[72:73], s[4:5], v64, s41, v[138:139]
	v_and_b32_e32 v74, 0x7cf0, v65
	global_load_dwordx4 v[200:203], v[72:73], off
	global_load_dwordx4 v[214:217], v[72:73], off offset:256
	v_add_u32_e32 v180, 0x90, v158
	v_mad_i64_i32 v[182:183], s[4:5], v180, s41, v[138:139]
	global_load_dwordx4 v[218:221], v[182:183], off
	v_add_u32_e32 v180, 0x90, v158
	v_mad_i64_i32 v[182:183], s[4:5], v180, s41, v[138:139]
	global_load_dwordx4 v[222:225], v[182:183], off offset:256
	v_add_u32_e32 v180, 0xa0, v158
	v_mad_i64_i32 v[182:183], s[4:5], v180, s41, v[138:139]
	global_load_dwordx4 v[226:229], v[182:183], off
	v_add_u32_e32 v180, 0xa0, v158
	v_mad_i64_i32 v[182:183], s[4:5], v180, s41, v[138:139]
	global_load_dwordx4 v[230:233], v[182:183], off offset:256
	v_add_u32_e32 v180, 0xb0, v158
	v_mad_i64_i32 v[182:183], s[4:5], v180, s41, v[138:139]
	global_load_dwordx4 v[234:237], v[182:183], off
	v_add_u32_e32 v180, 0xb0, v158
	v_mad_i64_i32 v[182:183], s[4:5], v180, s41, v[138:139]
	global_load_dwordx4 v[238:241], v[182:183], off offset:256
	s_waitcnt vmcnt(0)
	v_mov_b32_e32 v64, v200
	v_mov_b32_e32 v65, v201
	v_mov_b32_e32 v66, v202
	v_mov_b32_e32 v67, v203
	v_lshlrev_b32_e32 v75, 16, v64
	v_and_b32_e32 v76, 0xffff0000, v64
	v_lshlrev_b32_e32 v77, 16, v65
	v_and_b32_e32 v78, 0xffff0000, v65
	v_lshlrev_b32_e32 v79, 16, v66
	v_and_b32_e32 v80, 0xffff0000, v66
	v_lshlrev_b32_e32 v81, 16, v67
	v_and_b32_e32 v82, 0xffff0000, v67
	v_mov_b32_e32 v64, v192
	v_mov_b32_e32 v65, v193
	v_mov_b32_e32 v66, v194
	v_mov_b32_e32 v67, v195
	v_mov_b32_e32 v68, v196
	v_mov_b32_e32 v69, v197
	v_mov_b32_e32 v70, v198
	v_mov_b32_e32 v71, v199
	v_fmac_f32_e32 v56, v64, v79
	v_mul_f32_e32 v64, 0x3d372713, v56
	v_mul_f32_e32 v64, v56, v64
	v_fma_f32 v64, v56, v64, v56
	v_mul_f32_e32 v64, 0x3fcc422a, v64
	v_mul_f32_e32 v64, 0xbfb8aa3b, v64
	v_exp_f32_e32 v64, v64
	v_fmac_f32_e32 v61, v69, v76
	v_fmac_f32_e32 v57, v65, v80
	v_fmac_f32_e32 v62, v70, v77
	v_add_f32_e32 v64, 1.0, v64
	v_rcp_f32_e32 v64, v64
	v_fmac_f32_e32 v58, v66, v81
	v_fmac_f32_e32 v63, v71, v78
	v_fmac_f32_e32 v60, v68, v75
	v_mul_f32_e32 v64, v56, v64
	v_mul_f32_e32 v56, 0x3d372713, v61
	v_mul_f32_e32 v56, v61, v56
	v_fma_f32 v56, v61, v56, v61
	v_mul_f32_e32 v56, 0x3fcc422a, v56
	v_mul_f32_e32 v56, 0xbfb8aa3b, v56
	v_exp_f32_e32 v56, v56
	v_mul_f32_e32 v68, 0x3d372713, v60
	v_mul_f32_e32 v68, v60, v68
	v_fma_f32 v68, v60, v68, v60
	v_add_f32_e32 v56, 1.0, v56
	v_rcp_f32_e32 v56, v56
	v_mul_f32_e32 v68, 0x3fcc422a, v68
	v_mul_f32_e32 v68, 0xbfb8aa3b, v68
	v_fmac_f32_e32 v59, v67, v82
	v_mul_f32_e32 v56, v61, v56
	v_mul_f32_e32 v61, 0x3d372713, v57
	v_mul_f32_e32 v61, v57, v61
	v_fma_f32 v61, v57, v61, v57
	v_mul_f32_e32 v61, 0x3fcc422a, v61
	v_mul_f32_e32 v61, 0xbfb8aa3b, v61
	v_exp_f32_e32 v61, v61
	v_exp_f32_e32 v68, v68
	v_add_f32_e32 v61, 1.0, v61
	v_rcp_f32_e32 v61, v61
	v_add_f32_e32 v68, 1.0, v68
	v_rcp_f32_e32 v68, v68
	v_mul_f32_e32 v61, v57, v61
	v_mul_f32_e32 v57, 0x3d372713, v62
	v_mul_f32_e32 v57, v62, v57
	v_fma_f32 v57, v62, v57, v62
	v_mul_f32_e32 v57, 0x3fcc422a, v57
	v_mul_f32_e32 v57, 0xbfb8aa3b, v57
	v_exp_f32_e32 v57, v57
	v_mul_f32_e32 v60, v60, v68
	v_cvt_pk_bf16_f32 v56, v60, v56
	v_or_b32_e32 v60, v74, v151
	v_add_f32_e32 v57, 1.0, v57
	v_rcp_f32_e32 v57, v57
	v_lshlrev_b32_e32 v160, 10, v60
	v_mul_f32_e32 v57, v62, v57
	v_mul_f32_e32 v62, 0x3d372713, v58
	v_mul_f32_e32 v62, v58, v62
	v_fma_f32 v62, v58, v62, v58
	v_mul_f32_e32 v62, 0x3fcc422a, v62
; __device__ __forceinline__ unsigned cvt_pk_bf16(float lo, float hi) { unsigned r; asm volatile("v_cvt_pk_bf16_f32 %0, %1, %2" : "=v"(r) : "v"(lo), "v"(hi)); return r; }
; __device__ __forceinline__ float gelu_t(float x) { const float z = 1.5957691216f * (x + 0.044715f * x * x * x); return x * sigm(z); }
; __device__ __forceinline__ void UNPACK8(const u32x4 q, float (&f)[8]) { f[0] = bflo(q.x); f[1] = bfhi(q.x); f[2] = bflo(q.y); f[3] = bfhi(q.y); f[4] = bflo(q.z); f[5] = bfhi(q.z); f[6] = bflo(q.w); f[7] = bfhi(q.w); }
; #define EPI_FOR_ROWS() _Pragma("unroll") for (int ai = 0; ai < 2; ++ai) _Pragma("unroll") for (int m = 0; m < 4; ++m)
; __device__ __forceinline__ float sigm(float x) { return __builtin_amdgcn_rcpf(1.0f + __expf(-x)); }
;     __device__ __forceinline__ void operator()(const f32x4 (&acc)[2][2][4][2], const Unit& u, int wr, int wc, int fr, int fq) const {
;     ...
;         EPI_FOR_ROWS() {
;             const int gr = row0 + ai * 128 + m * 16, chunk = gr & 2047;
; #pragma unroll
;             for (int bj = 0; bj < 2; ++bj) { const int col = col0 + bj * 128, t = col >> 4, h0 = col & 15;
;                 const u32x4 uw = *(const u32x4*)(a2 + (size_t)gr * 384 + col); float uu[8]; UNPACK8(uw, uu);
;                 const f32x4 d0 = *(const f32x4*)(dsk + g * 16 + h0), d1 = *(const f32x4*)(dsk + g * 16 + h0 + 4); float o[8];
; #pragma unroll
;                 for (int e = 0; e < 4; ++e) { o[e] = gelu_t(acc[ai][bj][m][0][e] + d0[e] * uu[e]); o[4 + e] = gelu_t(acc[ai][bj][m][1][e] + d1[e] * uu[4 + e]); }
;                 u32x4 w; w.x = cvt_pk_bf16(o[0], o[1]); w.y = cvt_pk_bf16(o[2], o[3]); w.z = cvt_pk_bf16(o[4], o[5]); w.w = cvt_pk_bf16(o[6], o[7]);
;                 *(u32x4*)(yg + ((size_t)chunk * 16 + t) * 512 + g * 16 + h0) = w; }
	v_mul_f32_e32 v62, 0xbfb8aa3b, v62
	v_exp_f32_e32 v62, v62
	s_nop 0
	v_add_f32_e32 v62, 1.0, v62
	v_rcp_f32_e32 v62, v62
	s_nop 0
	v_mul_f32_e32 v62, v58, v62
	v_mul_f32_e32 v58, 0x3d372713, v63
	v_mul_f32_e32 v58, v63, v58
	v_fma_f32 v58, v63, v58, v63
	v_mul_f32_e32 v58, 0x3fcc422a, v58
	v_mul_f32_e32 v58, 0xbfb8aa3b, v58
	v_exp_f32_e32 v58, v58
	s_nop 0
	v_add_f32_e32 v58, 1.0, v58
	v_rcp_f32_e32 v58, v58
	s_nop 0
	v_mul_f32_e32 v58, v63, v58
	v_mul_f32_e32 v63, 0x3d372713, v59
	v_mul_f32_e32 v63, v59, v63
	v_fma_f32 v63, v59, v63, v59
	v_mul_f32_e32 v63, 0x3fcc422a, v63
	v_mul_f32_e32 v63, 0xbfb8aa3b, v63
	v_exp_f32_e32 v63, v63
	v_cvt_pk_bf16_f32 v57, v57, v58
	v_cvt_pk_bf16_f32 v58, v64, v61
	v_lshl_add_u64 v[60:61], s[30:31], 0, v[160:161]
	v_add_f32_e32 v63, 1.0, v63
	v_rcp_f32_e32 v63, v63
	v_lshl_add_u64 v[60:61], v[60:61], 0, vcc
	v_lshl_add_u64 v[60:61], v[60:61], 0, v[140:141]
	v_mul_f32_e32 v59, v59, v63
	v_cvt_pk_bf16_f32 v59, v62, v59
	global_store_dwordx4 v[60:61], v[56:59], off
	s_nop 1
	v_mov_b32_e32 v56, v214
	v_mov_b32_e32 v57, v215
	v_mov_b32_e32 v58, v216
	v_mov_b32_e32 v59, v217
	v_lshlrev_b32_e32 v64, 16, v56
	v_and_b32_e32 v65, 0xffff0000, v56
	v_lshlrev_b32_e32 v66, 16, v57
	v_and_b32_e32 v67, 0xffff0000, v57
	v_lshlrev_b32_e32 v68, 16, v58
	v_and_b32_e32 v69, 0xffff0000, v58
	v_lshlrev_b32_e32 v70, 16, v59
	v_and_b32_e32 v71, 0xffff0000, v59
	v_mov_b32_e32 v56, v192
	v_mov_b32_e32 v57, v193
	v_mov_b32_e32 v58, v194
	v_mov_b32_e32 v59, v195
	v_mov_b32_e32 v60, v196
	v_mov_b32_e32 v61, v197
	v_mov_b32_e32 v62, v198
	v_mov_b32_e32 v63, v199
	v_fmac_f32_e32 v48, v56, v68
	v_mul_f32_e32 v56, 0x3d372713, v48
	v_mul_f32_e32 v56, v48, v56
	v_fma_f32 v56, v48, v56, v48
	v_mul_f32_e32 v56, 0x3fcc422a, v56
	v_mul_f32_e32 v56, 0xbfb8aa3b, v56
	v_exp_f32_e32 v56, v56
	v_fmac_f32_e32 v53, v61, v65
	v_fmac_f32_e32 v49, v57, v69
	v_fmac_f32_e32 v54, v62, v66
	v_add_f32_e32 v56, 1.0, v56
	v_rcp_f32_e32 v56, v56
	v_fmac_f32_e32 v50, v58, v70
	v_fmac_f32_e32 v55, v63, v67
	v_fmac_f32_e32 v52, v60, v64
	v_mul_f32_e32 v56, v48, v56
	v_mul_f32_e32 v48, 0x3d372713, v53
	v_mul_f32_e32 v48, v53, v48
	v_fma_f32 v48, v53, v48, v53
	v_mul_f32_e32 v48, 0x3fcc422a, v48
	v_mul_f32_e32 v48, 0xbfb8aa3b, v48
	v_exp_f32_e32 v48, v48
	v_mul_f32_e32 v60, 0x3d372713, v52
	v_mul_f32_e32 v60, v52, v60
	v_fma_f32 v60, v52, v60, v52
	v_add_f32_e32 v48, 1.0, v48
	v_rcp_f32_e32 v48, v48
	v_mul_f32_e32 v60, 0x3fcc422a, v60
	v_mul_f32_e32 v60, 0xbfb8aa3b, v60
	v_fmac_f32_e32 v51, v59, v71
	v_mul_f32_e32 v48, v53, v48
	v_mul_f32_e32 v53, 0x3d372713, v49
	v_mul_f32_e32 v53, v49, v53
	v_fma_f32 v53, v49, v53, v49
	v_mul_f32_e32 v53, 0x3fcc422a, v53
	v_mul_f32_e32 v53, 0xbfb8aa3b, v53
	v_exp_f32_e32 v53, v53
	v_exp_f32_e32 v60, v60
	v_add_f32_e32 v53, 1.0, v53
	v_rcp_f32_e32 v53, v53
	v_add_f32_e32 v60, 1.0, v60
	v_rcp_f32_e32 v60, v60
	v_mul_f32_e32 v53, v49, v53
	v_mul_f32_e32 v49, 0x3d372713, v54
	v_mul_f32_e32 v49, v54, v49
	v_fma_f32 v49, v54, v49, v54
	v_mul_f32_e32 v49, 0x3fcc422a, v49
	v_mul_f32_e32 v49, 0xbfb8aa3b, v49
	v_exp_f32_e32 v49, v49
	v_mul_f32_e32 v52, v52, v60
	v_cvt_pk_bf16_f32 v48, v52, v48
	v_or_b32_e32 v52, v74, v152
	v_add_f32_e32 v49, 1.0, v49
	v_rcp_f32_e32 v49, v49
	v_lshlrev_b32_e32 v160, 10, v52
	v_mul_f32_e32 v49, v54, v49
	v_mul_f32_e32 v54, 0x3d372713, v50
	v_mul_f32_e32 v54, v50, v54
	v_fma_f32 v54, v50, v54, v50
	v_mul_f32_e32 v54, 0x3fcc422a, v54
	v_mul_f32_e32 v54, 0xbfb8aa3b, v54
	v_exp_f32_e32 v54, v54
	s_nop 0
	v_add_f32_e32 v54, 1.0, v54
	v_rcp_f32_e32 v54, v54
	s_nop 0
	v_mul_f32_e32 v54, v50, v54
	v_mul_f32_e32 v50, 0x3d372713, v55
	v_mul_f32_e32 v50, v55, v50
	v_fma_f32 v50, v55, v50, v55
	v_mul_f32_e32 v50, 0x3fcc422a, v50
	v_mul_f32_e32 v50, 0xbfb8aa3b, v50
	v_exp_f32_e32 v50, v50
	s_nop 0
	v_add_f32_e32 v50, 1.0, v50
	v_rcp_f32_e32 v50, v50
	s_nop 0
	v_mul_f32_e32 v50, v55, v50
	v_mul_f32_e32 v55, 0x3d372713, v51
	v_mul_f32_e32 v55, v51, v55
	v_fma_f32 v55, v51, v55, v51
	v_mul_f32_e32 v55, 0x3fcc422a, v55
	v_mul_f32_e32 v55, 0xbfb8aa3b, v55
	v_exp_f32_e32 v55, v55
	v_cvt_pk_bf16_f32 v49, v49, v50
	v_cvt_pk_bf16_f32 v50, v56, v53
	v_lshl_add_u64 v[52:53], s[30:31], 0, v[160:161]
	v_add_f32_e32 v55, 1.0, v55
	v_rcp_f32_e32 v55, v55
	v_lshl_add_u64 v[52:53], v[52:53], 0, vcc
	v_lshl_add_u64 v[52:53], v[52:53], 0, v[140:141]
	v_mul_f32_e32 v51, v51, v55
	v_cvt_pk_bf16_f32 v51, v54, v51
	global_store_dwordx4 v[52:53], v[48:51], off
	s_nop 1
	v_add_u32_e32 v48, 0x90, v158
	v_lshlrev_b32_e32 v49, 4, v48
	v_mad_i64_i32 v[56:57], s[4:5], v48, s41, v[138:139]
	v_and_b32_e32 v58, 0x7df0, v49
	v_mov_b32_e32 v48, v218
	v_mov_b32_e32 v49, v219
	v_mov_b32_e32 v50, v220
	v_mov_b32_e32 v51, v221
	v_lshlrev_b32_e32 v59, 16, v48
	v_and_b32_e32 v60, 0xffff0000, v48
	v_lshlrev_b32_e32 v61, 16, v49
	v_and_b32_e32 v62, 0xffff0000, v49
	v_lshlrev_b32_e32 v63, 16, v50
	v_and_b32_e32 v64, 0xffff0000, v50
	v_lshlrev_b32_e32 v65, 16, v51
	v_and_b32_e32 v66, 0xffff0000, v51
	v_mov_b32_e32 v48, v192
	v_mov_b32_e32 v49, v193
	v_mov_b32_e32 v50, v194
	v_mov_b32_e32 v51, v195
	v_mov_b32_e32 v52, v196
	v_mov_b32_e32 v53, v197
	v_mov_b32_e32 v54, v198
	v_mov_b32_e32 v55, v199
	v_fmac_f32_e32 v40, v48, v63
	v_mul_f32_e32 v48, 0x3d372713, v40
	v_mul_f32_e32 v48, v40, v48
	v_fma_f32 v48, v40, v48, v40
	v_mul_f32_e32 v48, 0x3fcc422a, v48
	v_mul_f32_e32 v48, 0xbfb8aa3b, v48
	v_exp_f32_e32 v48, v48
	v_fmac_f32_e32 v45, v53, v60
	v_fmac_f32_e32 v41, v49, v64
	v_fmac_f32_e32 v46, v54, v61
	v_add_f32_e32 v48, 1.0, v48
	v_rcp_f32_e32 v48, v48
	v_fmac_f32_e32 v42, v50, v65
	v_fmac_f32_e32 v47, v55, v62
	v_fmac_f32_e32 v44, v52, v59
	v_mul_f32_e32 v48, v40, v48
; __device__ __forceinline__ unsigned cvt_pk_bf16(float lo, float hi) { unsigned r; asm volatile("v_cvt_pk_bf16_f32 %0, %1, %2" : "=v"(r) : "v"(lo), "v"(hi)); return r; }
; __device__ __forceinline__ float gelu_t(float x) { const float z = 1.5957691216f * (x + 0.044715f * x * x * x); return x * sigm(z); }
; __device__ __forceinline__ void UNPACK8(const u32x4 q, float (&f)[8]) { f[0] = bflo(q.x); f[1] = bfhi(q.x); f[2] = bflo(q.y); f[3] = bfhi(q.y); f[4] = bflo(q.z); f[5] = bfhi(q.z); f[6] = bflo(q.w); f[7] = bfhi(q.w); }
; #define EPI_FOR_ROWS() _Pragma("unroll") for (int ai = 0; ai < 2; ++ai) _Pragma("unroll") for (int m = 0; m < 4; ++m)
; __device__ __forceinline__ float sigm(float x) { return __builtin_amdgcn_rcpf(1.0f + __expf(-x)); }
;     __device__ __forceinline__ void operator()(const f32x4 (&acc)[2][2][4][2], const Unit& u, int wr, int wc, int fr, int fq) const {
;     ...
;         EPI_FOR_ROWS() {
;             const int gr = row0 + ai * 128 + m * 16, chunk = gr & 2047;
; #pragma unroll
;             for (int bj = 0; bj < 2; ++bj) { const int col = col0 + bj * 128, t = col >> 4, h0 = col & 15;
;                 const u32x4 uw = *(const u32x4*)(a2 + (size_t)gr * 384 + col); float uu[8]; UNPACK8(uw, uu);
;                 const f32x4 d0 = *(const f32x4*)(dsk + g * 16 + h0), d1 = *(const f32x4*)(dsk + g * 16 + h0 + 4); float o[8];
; #pragma unroll
;                 for (int e = 0; e < 4; ++e) { o[e] = gelu_t(acc[ai][bj][m][0][e] + d0[e] * uu[e]); o[4 + e] = gelu_t(acc[ai][bj][m][1][e] + d1[e] * uu[4 + e]); }
;                 u32x4 w; w.x = cvt_pk_bf16(o[0], o[1]); w.y = cvt_pk_bf16(o[2], o[3]); w.z = cvt_pk_bf16(o[4], o[5]); w.w = cvt_pk_bf16(o[6], o[7]);
;                 *(u32x4*)(yg + ((size_t)chunk * 16 + t) * 512 + g * 16 + h0) = w; }
	v_mul_f32_e32 v40, 0x3d372713, v45
	v_mul_f32_e32 v40, v45, v40
	v_fma_f32 v40, v45, v40, v45
	v_mul_f32_e32 v40, 0x3fcc422a, v40
	v_mul_f32_e32 v40, 0xbfb8aa3b, v40
	v_exp_f32_e32 v40, v40
	v_mul_f32_e32 v52, 0x3d372713, v44
	v_mul_f32_e32 v52, v44, v52
	v_fma_f32 v52, v44, v52, v44
	v_add_f32_e32 v40, 1.0, v40
	v_rcp_f32_e32 v40, v40
	v_mul_f32_e32 v52, 0x3fcc422a, v52
	v_mul_f32_e32 v52, 0xbfb8aa3b, v52
	v_fmac_f32_e32 v43, v51, v66
	v_mul_f32_e32 v40, v45, v40
	v_mul_f32_e32 v45, 0x3d372713, v41
	v_mul_f32_e32 v45, v41, v45
	v_fma_f32 v45, v41, v45, v41
	v_mul_f32_e32 v45, 0x3fcc422a, v45
	v_mul_f32_e32 v45, 0xbfb8aa3b, v45
	v_exp_f32_e32 v45, v45
	v_exp_f32_e32 v52, v52
	v_add_f32_e32 v45, 1.0, v45
	v_rcp_f32_e32 v45, v45
	v_add_f32_e32 v52, 1.0, v52
	v_rcp_f32_e32 v52, v52
	v_mul_f32_e32 v45, v41, v45
	v_mul_f32_e32 v41, 0x3d372713, v46
	v_mul_f32_e32 v41, v46, v41
	v_fma_f32 v41, v46, v41, v46
	v_mul_f32_e32 v41, 0x3fcc422a, v41
	v_mul_f32_e32 v41, 0xbfb8aa3b, v41
	v_exp_f32_e32 v41, v41
	v_mul_f32_e32 v44, v44, v52
	v_cvt_pk_bf16_f32 v40, v44, v40
	v_or_b32_e32 v44, v58, v151
	v_add_f32_e32 v41, 1.0, v41
	v_rcp_f32_e32 v41, v41
	v_lshlrev_b32_e32 v160, 10, v44
	v_mul_f32_e32 v41, v46, v41
	v_mul_f32_e32 v46, 0x3d372713, v42
	v_mul_f32_e32 v46, v42, v46
	v_fma_f32 v46, v42, v46, v42
	v_mul_f32_e32 v46, 0x3fcc422a, v46
	v_mul_f32_e32 v46, 0xbfb8aa3b, v46
	v_exp_f32_e32 v46, v46
	s_nop 0
	v_add_f32_e32 v46, 1.0, v46
	v_rcp_f32_e32 v46, v46
	s_nop 0
	v_mul_f32_e32 v46, v42, v46
	v_mul_f32_e32 v42, 0x3d372713, v47
	v_mul_f32_e32 v42, v47, v42
	v_fma_f32 v42, v47, v42, v47
	v_mul_f32_e32 v42, 0x3fcc422a, v42
	v_mul_f32_e32 v42, 0xbfb8aa3b, v42
	v_exp_f32_e32 v42, v42
	s_nop 0
	v_add_f32_e32 v42, 1.0, v42
	v_rcp_f32_e32 v42, v42
	s_nop 0
	v_mul_f32_e32 v42, v47, v42
	v_mul_f32_e32 v47, 0x3d372713, v43
	v_mul_f32_e32 v47, v43, v47
	v_fma_f32 v47, v43, v47, v43
	v_mul_f32_e32 v47, 0x3fcc422a, v47
	v_mul_f32_e32 v47, 0xbfb8aa3b, v47
	v_exp_f32_e32 v47, v47
	v_cvt_pk_bf16_f32 v41, v41, v42
	v_cvt_pk_bf16_f32 v42, v48, v45
	v_lshl_add_u64 v[44:45], s[30:31], 0, v[160:161]
	v_add_f32_e32 v47, 1.0, v47
	v_rcp_f32_e32 v47, v47
	v_lshl_add_u64 v[44:45], v[44:45], 0, vcc
	v_lshl_add_u64 v[44:45], v[44:45], 0, v[140:141]
	v_mul_f32_e32 v43, v43, v47
	v_cvt_pk_bf16_f32 v43, v46, v43
	global_store_dwordx4 v[44:45], v[40:43], off
	s_nop 1
	v_mov_b32_e32 v40, v222
	v_mov_b32_e32 v41, v223
	v_mov_b32_e32 v42, v224
	v_mov_b32_e32 v43, v225
	v_lshlrev_b32_e32 v48, 16, v40
	v_and_b32_e32 v49, 0xffff0000, v40
	v_lshlrev_b32_e32 v50, 16, v41
	v_and_b32_e32 v51, 0xffff0000, v41
	v_lshlrev_b32_e32 v52, 16, v42
	v_and_b32_e32 v53, 0xffff0000, v42
	v_lshlrev_b32_e32 v54, 16, v43
	v_and_b32_e32 v55, 0xffff0000, v43
	v_mov_b32_e32 v40, v192
	v_mov_b32_e32 v41, v193
	v_mov_b32_e32 v42, v194
	v_mov_b32_e32 v43, v195
	v_mov_b32_e32 v44, v196
	v_mov_b32_e32 v45, v197
	v_mov_b32_e32 v46, v198
	v_mov_b32_e32 v47, v199
	v_fmac_f32_e32 v32, v40, v52
	v_mul_f32_e32 v40, 0x3d372713, v32
	v_mul_f32_e32 v40, v32, v40
	v_fma_f32 v40, v32, v40, v32
	v_mul_f32_e32 v40, 0x3fcc422a, v40
	v_mul_f32_e32 v40, 0xbfb8aa3b, v40
	v_exp_f32_e32 v40, v40
	v_fmac_f32_e32 v37, v45, v49
	v_fmac_f32_e32 v33, v41, v53
	v_fmac_f32_e32 v38, v46, v50
	v_add_f32_e32 v40, 1.0, v40
	v_rcp_f32_e32 v40, v40
	v_fmac_f32_e32 v34, v42, v54
	v_fmac_f32_e32 v39, v47, v51
	v_fmac_f32_e32 v36, v44, v48
	v_mul_f32_e32 v40, v32, v40
	v_mul_f32_e32 v32, 0x3d372713, v37
	v_mul_f32_e32 v32, v37, v32
	v_fma_f32 v32, v37, v32, v37
	v_mul_f32_e32 v32, 0x3fcc422a, v32
	v_mul_f32_e32 v32, 0xbfb8aa3b, v32
	v_exp_f32_e32 v32, v32
	v_mul_f32_e32 v44, 0x3d372713, v36
	v_mul_f32_e32 v44, v36, v44
	v_fma_f32 v44, v36, v44, v36
	v_add_f32_e32 v32, 1.0, v32
	v_rcp_f32_e32 v32, v32
	v_mul_f32_e32 v44, 0x3fcc422a, v44
	v_mul_f32_e32 v44, 0xbfb8aa3b, v44
	v_fmac_f32_e32 v35, v43, v55
	v_mul_f32_e32 v32, v37, v32
	v_mul_f32_e32 v37, 0x3d372713, v33
	v_mul_f32_e32 v37, v33, v37
	v_fma_f32 v37, v33, v37, v33
	v_mul_f32_e32 v37, 0x3fcc422a, v37
	v_mul_f32_e32 v37, 0xbfb8aa3b, v37
	v_exp_f32_e32 v37, v37
	v_exp_f32_e32 v44, v44
	v_add_f32_e32 v37, 1.0, v37
	v_rcp_f32_e32 v37, v37
	v_add_f32_e32 v44, 1.0, v44
	v_rcp_f32_e32 v44, v44
	v_mul_f32_e32 v37, v33, v37
	v_mul_f32_e32 v33, 0x3d372713, v38
	v_mul_f32_e32 v33, v38, v33
	v_fma_f32 v33, v38, v33, v38
	v_mul_f32_e32 v33, 0x3fcc422a, v33
	v_mul_f32_e32 v33, 0xbfb8aa3b, v33
	v_exp_f32_e32 v33, v33
	v_mul_f32_e32 v36, v36, v44
	v_cvt_pk_bf16_f32 v32, v36, v32
	v_or_b32_e32 v36, v58, v152
	v_add_f32_e32 v33, 1.0, v33
	v_rcp_f32_e32 v33, v33
	v_lshlrev_b32_e32 v160, 10, v36
	v_mul_f32_e32 v33, v38, v33
	v_mul_f32_e32 v38, 0x3d372713, v34
	v_mul_f32_e32 v38, v34, v38
	v_fma_f32 v38, v34, v38, v34
	v_mul_f32_e32 v38, 0x3fcc422a, v38
	v_mul_f32_e32 v38, 0xbfb8aa3b, v38
	v_exp_f32_e32 v38, v38
	s_nop 0
	v_add_f32_e32 v38, 1.0, v38
	v_rcp_f32_e32 v38, v38
	s_nop 0
	v_mul_f32_e32 v38, v34, v38
	v_mul_f32_e32 v34, 0x3d372713, v39
	v_mul_f32_e32 v34, v39, v34
	v_fma_f32 v34, v39, v34, v39
	v_mul_f32_e32 v34, 0x3fcc422a, v34
	v_mul_f32_e32 v34, 0xbfb8aa3b, v34
	v_exp_f32_e32 v34, v34
	s_nop 0
	v_add_f32_e32 v34, 1.0, v34
	v_rcp_f32_e32 v34, v34
	s_nop 0
	v_mul_f32_e32 v34, v39, v34
	v_mul_f32_e32 v39, 0x3d372713, v35
	v_mul_f32_e32 v39, v35, v39
	v_fma_f32 v39, v35, v39, v35
	v_mul_f32_e32 v39, 0x3fcc422a, v39
	v_mul_f32_e32 v39, 0xbfb8aa3b, v39
	v_exp_f32_e32 v39, v39
	v_cvt_pk_bf16_f32 v33, v33, v34
	v_cvt_pk_bf16_f32 v34, v40, v37
	v_lshl_add_u64 v[36:37], s[30:31], 0, v[160:161]
	v_add_f32_e32 v39, 1.0, v39
	v_rcp_f32_e32 v39, v39
	v_lshl_add_u64 v[36:37], v[36:37], 0, vcc
; __device__ __forceinline__ unsigned cvt_pk_bf16(float lo, float hi) { unsigned r; asm volatile("v_cvt_pk_bf16_f32 %0, %1, %2" : "=v"(r) : "v"(lo), "v"(hi)); return r; }
; __device__ __forceinline__ float gelu_t(float x) { const float z = 1.5957691216f * (x + 0.044715f * x * x * x); return x * sigm(z); }
; __device__ __forceinline__ void UNPACK8(const u32x4 q, float (&f)[8]) { f[0] = bflo(q.x); f[1] = bfhi(q.x); f[2] = bflo(q.y); f[3] = bfhi(q.y); f[4] = bflo(q.z); f[5] = bfhi(q.z); f[6] = bflo(q.w); f[7] = bfhi(q.w); }
; #define EPI_FOR_ROWS() _Pragma("unroll") for (int ai = 0; ai < 2; ++ai) _Pragma("unroll") for (int m = 0; m < 4; ++m)
; __device__ __forceinline__ float sigm(float x) { return __builtin_amdgcn_rcpf(1.0f + __expf(-x)); }
;     __device__ __forceinline__ void operator()(const f32x4 (&acc)[2][2][4][2], const Unit& u, int wr, int wc, int fr, int fq) const {
;     ...
;         EPI_FOR_ROWS() {
;             const int gr = row0 + ai * 128 + m * 16, chunk = gr & 2047;
; #pragma unroll
;             for (int bj = 0; bj < 2; ++bj) { const int col = col0 + bj * 128, t = col >> 4, h0 = col & 15;
;                 const u32x4 uw = *(const u32x4*)(a2 + (size_t)gr * 384 + col); float uu[8]; UNPACK8(uw, uu);
;                 const f32x4 d0 = *(const f32x4*)(dsk + g * 16 + h0), d1 = *(const f32x4*)(dsk + g * 16 + h0 + 4); float o[8];
; #pragma unroll
;                 for (int e = 0; e < 4; ++e) { o[e] = gelu_t(acc[ai][bj][m][0][e] + d0[e] * uu[e]); o[4 + e] = gelu_t(acc[ai][bj][m][1][e] + d1[e] * uu[4 + e]); }
;                 u32x4 w; w.x = cvt_pk_bf16(o[0], o[1]); w.y = cvt_pk_bf16(o[2], o[3]); w.z = cvt_pk_bf16(o[4], o[5]); w.w = cvt_pk_bf16(o[6], o[7]);
;                 *(u32x4*)(yg + ((size_t)chunk * 16 + t) * 512 + g * 16 + h0) = w; }
	v_lshl_add_u64 v[36:37], v[36:37], 0, v[140:141]
	v_mul_f32_e32 v35, v35, v39
	v_cvt_pk_bf16_f32 v35, v38, v35
	global_store_dwordx4 v[36:37], v[32:35], off
	s_nop 1
	v_add_u32_e32 v32, 0xa0, v158
	v_lshlrev_b32_e32 v33, 4, v32
	v_mad_i64_i32 v[40:41], s[4:5], v32, s41, v[138:139]
	v_and_b32_e32 v42, 0x7ef0, v33
	v_mov_b32_e32 v32, v226
	v_mov_b32_e32 v33, v227
	v_mov_b32_e32 v34, v228
	v_mov_b32_e32 v35, v229
	v_lshlrev_b32_e32 v43, 16, v32
	v_and_b32_e32 v44, 0xffff0000, v32
	v_lshlrev_b32_e32 v45, 16, v33
	v_and_b32_e32 v46, 0xffff0000, v33
	v_lshlrev_b32_e32 v47, 16, v34
	v_and_b32_e32 v48, 0xffff0000, v34
	v_lshlrev_b32_e32 v49, 16, v35
	v_and_b32_e32 v50, 0xffff0000, v35
	v_mov_b32_e32 v32, v192
	v_mov_b32_e32 v33, v193
	v_mov_b32_e32 v34, v194
	v_mov_b32_e32 v35, v195
	v_mov_b32_e32 v36, v196
	v_mov_b32_e32 v37, v197
	v_mov_b32_e32 v38, v198
	v_mov_b32_e32 v39, v199
	v_fmac_f32_e32 v24, v32, v47
	v_mul_f32_e32 v32, 0x3d372713, v24
	v_mul_f32_e32 v32, v24, v32
	v_fma_f32 v32, v24, v32, v24
	v_mul_f32_e32 v32, 0x3fcc422a, v32
	v_mul_f32_e32 v32, 0xbfb8aa3b, v32
	v_exp_f32_e32 v32, v32
	v_fmac_f32_e32 v29, v37, v44
	v_fmac_f32_e32 v25, v33, v48
	v_fmac_f32_e32 v30, v38, v45
	v_add_f32_e32 v32, 1.0, v32
	v_rcp_f32_e32 v32, v32
	v_fmac_f32_e32 v26, v34, v49
	v_fmac_f32_e32 v31, v39, v46
	v_fmac_f32_e32 v28, v36, v43
	v_mul_f32_e32 v32, v24, v32
	v_mul_f32_e32 v24, 0x3d372713, v29
	v_mul_f32_e32 v24, v29, v24
	v_fma_f32 v24, v29, v24, v29
	v_mul_f32_e32 v24, 0x3fcc422a, v24
	v_mul_f32_e32 v24, 0xbfb8aa3b, v24
	v_exp_f32_e32 v24, v24
	v_mul_f32_e32 v36, 0x3d372713, v28
	v_mul_f32_e32 v36, v28, v36
	v_fma_f32 v36, v28, v36, v28
	v_add_f32_e32 v24, 1.0, v24
	v_rcp_f32_e32 v24, v24
	v_mul_f32_e32 v36, 0x3fcc422a, v36
	v_mul_f32_e32 v36, 0xbfb8aa3b, v36
	v_fmac_f32_e32 v27, v35, v50
	v_mul_f32_e32 v24, v29, v24
	v_mul_f32_e32 v29, 0x3d372713, v25
	v_mul_f32_e32 v29, v25, v29
	v_fma_f32 v29, v25, v29, v25
	v_mul_f32_e32 v29, 0x3fcc422a, v29
	v_mul_f32_e32 v29, 0xbfb8aa3b, v29
	v_exp_f32_e32 v29, v29
	v_exp_f32_e32 v36, v36
	v_add_f32_e32 v29, 1.0, v29
	v_rcp_f32_e32 v29, v29
	v_add_f32_e32 v36, 1.0, v36
	v_rcp_f32_e32 v36, v36
	v_mul_f32_e32 v29, v25, v29
	v_mul_f32_e32 v25, 0x3d372713, v30
	v_mul_f32_e32 v25, v30, v25
	v_fma_f32 v25, v30, v25, v30
	v_mul_f32_e32 v25, 0x3fcc422a, v25
	v_mul_f32_e32 v25, 0xbfb8aa3b, v25
	v_exp_f32_e32 v25, v25
	v_mul_f32_e32 v28, v28, v36
	v_cvt_pk_bf16_f32 v24, v28, v24
	v_or_b32_e32 v28, v42, v151
	v_add_f32_e32 v25, 1.0, v25
	v_rcp_f32_e32 v25, v25
	v_lshlrev_b32_e32 v160, 10, v28
	v_mul_f32_e32 v25, v30, v25
	v_mul_f32_e32 v30, 0x3d372713, v26
	v_mul_f32_e32 v30, v26, v30
	v_fma_f32 v30, v26, v30, v26
	v_mul_f32_e32 v30, 0x3fcc422a, v30
	v_mul_f32_e32 v30, 0xbfb8aa3b, v30
	v_exp_f32_e32 v30, v30
	s_nop 0
	v_add_f32_e32 v30, 1.0, v30
	v_rcp_f32_e32 v30, v30
	s_nop 0
	v_mul_f32_e32 v30, v26, v30
	v_mul_f32_e32 v26, 0x3d372713, v31
	v_mul_f32_e32 v26, v31, v26
	v_fma_f32 v26, v31, v26, v31
	v_mul_f32_e32 v26, 0x3fcc422a, v26
	v_mul_f32_e32 v26, 0xbfb8aa3b, v26
	v_exp_f32_e32 v26, v26
	s_nop 0
	v_add_f32_e32 v26, 1.0, v26
	v_rcp_f32_e32 v26, v26
	s_nop 0
	v_mul_f32_e32 v26, v31, v26
	v_mul_f32_e32 v31, 0x3d372713, v27
	v_mul_f32_e32 v31, v27, v31
	v_fma_f32 v31, v27, v31, v27
	v_mul_f32_e32 v31, 0x3fcc422a, v31
	v_mul_f32_e32 v31, 0xbfb8aa3b, v31
	v_exp_f32_e32 v31, v31
	v_cvt_pk_bf16_f32 v25, v25, v26
	v_cvt_pk_bf16_f32 v26, v32, v29
	v_lshl_add_u64 v[28:29], s[30:31], 0, v[160:161]
	v_add_f32_e32 v31, 1.0, v31
	v_rcp_f32_e32 v31, v31
	v_lshl_add_u64 v[28:29], v[28:29], 0, vcc
	v_lshl_add_u64 v[28:29], v[28:29], 0, v[140:141]
	v_mul_f32_e32 v27, v27, v31
	v_cvt_pk_bf16_f32 v27, v30, v27
	global_store_dwordx4 v[28:29], v[24:27], off
	s_nop 1
	v_mov_b32_e32 v24, v230
	v_mov_b32_e32 v25, v231
	v_mov_b32_e32 v26, v232
	v_mov_b32_e32 v27, v233
	v_lshlrev_b32_e32 v32, 16, v24
	v_and_b32_e32 v33, 0xffff0000, v24
	v_lshlrev_b32_e32 v34, 16, v25
	v_and_b32_e32 v35, 0xffff0000, v25
	v_lshlrev_b32_e32 v36, 16, v26
	v_and_b32_e32 v37, 0xffff0000, v26
	v_lshlrev_b32_e32 v38, 16, v27
	v_and_b32_e32 v39, 0xffff0000, v27
	v_mov_b32_e32 v24, v192
	v_mov_b32_e32 v25, v193
	v_mov_b32_e32 v26, v194
	v_mov_b32_e32 v27, v195
	v_mov_b32_e32 v28, v196
	v_mov_b32_e32 v29, v197
	v_mov_b32_e32 v30, v198
	v_mov_b32_e32 v31, v199
	v_fmac_f32_e32 v16, v24, v36
	v_mul_f32_e32 v24, 0x3d372713, v16
	v_mul_f32_e32 v24, v16, v24
	v_fma_f32 v24, v16, v24, v16
	v_mul_f32_e32 v24, 0x3fcc422a, v24
	v_mul_f32_e32 v24, 0xbfb8aa3b, v24
	v_exp_f32_e32 v24, v24
	v_fmac_f32_e32 v21, v29, v33
	v_fmac_f32_e32 v17, v25, v37
	v_fmac_f32_e32 v22, v30, v34
	v_add_f32_e32 v24, 1.0, v24
	v_rcp_f32_e32 v24, v24
	v_fmac_f32_e32 v18, v26, v38
	v_fmac_f32_e32 v23, v31, v35
	v_fmac_f32_e32 v20, v28, v32
	v_mul_f32_e32 v24, v16, v24
	v_mul_f32_e32 v16, 0x3d372713, v21
	v_mul_f32_e32 v16, v21, v16
	v_fma_f32 v16, v21, v16, v21
	v_mul_f32_e32 v16, 0x3fcc422a, v16
	v_mul_f32_e32 v16, 0xbfb8aa3b, v16
	v_exp_f32_e32 v16, v16
	v_mul_f32_e32 v28, 0x3d372713, v20
	v_mul_f32_e32 v28, v20, v28
	v_fma_f32 v28, v20, v28, v20
	v_add_f32_e32 v16, 1.0, v16
	v_rcp_f32_e32 v16, v16
	v_mul_f32_e32 v28, 0x3fcc422a, v28
	v_mul_f32_e32 v28, 0xbfb8aa3b, v28
	v_fmac_f32_e32 v19, v27, v39
	v_mul_f32_e32 v16, v21, v16
	v_mul_f32_e32 v21, 0x3d372713, v17
	v_mul_f32_e32 v21, v17, v21
	v_fma_f32 v21, v17, v21, v17
	v_mul_f32_e32 v21, 0x3fcc422a, v21
	v_mul_f32_e32 v21, 0xbfb8aa3b, v21
	v_exp_f32_e32 v21, v21
	v_exp_f32_e32 v28, v28
	v_add_f32_e32 v21, 1.0, v21
	v_rcp_f32_e32 v21, v21
	v_add_f32_e32 v28, 1.0, v28
	v_rcp_f32_e32 v28, v28
	v_mul_f32_e32 v21, v17, v21
	v_mul_f32_e32 v17, 0x3d372713, v22
; __device__ __forceinline__ unsigned cvt_pk_bf16(float lo, float hi) { unsigned r; asm volatile("v_cvt_pk_bf16_f32 %0, %1, %2" : "=v"(r) : "v"(lo), "v"(hi)); return r; }
; __device__ __forceinline__ float gelu_t(float x) { const float z = 1.5957691216f * (x + 0.044715f * x * x * x); return x * sigm(z); }
; __device__ __forceinline__ void UNPACK8(const u32x4 q, float (&f)[8]) { f[0] = bflo(q.x); f[1] = bfhi(q.x); f[2] = bflo(q.y); f[3] = bfhi(q.y); f[4] = bflo(q.z); f[5] = bfhi(q.z); f[6] = bflo(q.w); f[7] = bfhi(q.w); }
; #define EPI_FOR_ROWS() _Pragma("unroll") for (int ai = 0; ai < 2; ++ai) _Pragma("unroll") for (int m = 0; m < 4; ++m)
;     __device__ __forceinline__ void operator()(const f32x4 (&acc)[2][2][4][2], const Unit& u, int wr, int wc, int fr, int fq) const {
;         const int row0 = u.pm * 256 + wr * 64 + fr, col0 = wc * 32 + 8 * fq; const int g = u.pn;
;         EPI_FOR_ROWS() {
;             const int gr = row0 + ai * 128 + m * 16, chunk = gr & 2047;
; #pragma unroll
;             for (int bj = 0; bj < 2; ++bj) { const int col = col0 + bj * 128, t = col >> 4, h0 = col & 15;
;                 const u32x4 uw = *(const u32x4*)(a2 + (size_t)gr * 384 + col); float uu[8]; UNPACK8(uw, uu);
;                 const f32x4 d0 = *(const f32x4*)(dsk + g * 16 + h0), d1 = *(const f32x4*)(dsk + g * 16 + h0 + 4); float o[8];
; #pragma unroll
;                 for (int e = 0; e < 4; ++e) { o[e] = gelu_t(acc[ai][bj][m][0][e] + d0[e] * uu[e]); o[4 + e] = gelu_t(acc[ai][bj][m][1][e] + d1[e] * uu[4 + e]); }
;                 u32x4 w; w.x = cvt_pk_bf16(o[0], o[1]); w.y = cvt_pk_bf16(o[2], o[3]); w.z = cvt_pk_bf16(o[4], o[5]); w.w = cvt_pk_bf16(o[6], o[7]);
;                 *(u32x4*)(yg + ((size_t)chunk * 16 + t) * 512 + g * 16 + h0) = w; }
;         }
;     }
	v_mul_f32_e32 v17, v22, v17
	v_fma_f32 v17, v22, v17, v22
	v_mul_f32_e32 v17, 0x3fcc422a, v17
	v_mul_f32_e32 v17, 0xbfb8aa3b, v17
	v_exp_f32_e32 v17, v17
	v_mul_f32_e32 v20, v20, v28
	v_cvt_pk_bf16_f32 v16, v20, v16
	v_or_b32_e32 v20, v42, v152
	v_add_f32_e32 v17, 1.0, v17
	v_rcp_f32_e32 v17, v17
	v_lshlrev_b32_e32 v160, 10, v20
	v_mul_f32_e32 v17, v22, v17
	v_mul_f32_e32 v22, 0x3d372713, v18
	v_mul_f32_e32 v22, v18, v22
	v_fma_f32 v22, v18, v22, v18
	v_mul_f32_e32 v22, 0x3fcc422a, v22
	v_mul_f32_e32 v22, 0xbfb8aa3b, v22
	v_exp_f32_e32 v22, v22
	s_nop 0
	v_add_f32_e32 v22, 1.0, v22
	v_rcp_f32_e32 v22, v22
	s_nop 0
	v_mul_f32_e32 v22, v18, v22
	v_mul_f32_e32 v18, 0x3d372713, v23
	v_mul_f32_e32 v18, v23, v18
	v_fma_f32 v18, v23, v18, v23
	v_mul_f32_e32 v18, 0x3fcc422a, v18
	v_mul_f32_e32 v18, 0xbfb8aa3b, v18
	v_exp_f32_e32 v18, v18
	s_nop 0
	v_add_f32_e32 v18, 1.0, v18
	v_rcp_f32_e32 v18, v18
	s_nop 0
	v_mul_f32_e32 v18, v23, v18
	v_mul_f32_e32 v23, 0x3d372713, v19
	v_mul_f32_e32 v23, v19, v23
	v_fma_f32 v23, v19, v23, v19
	v_mul_f32_e32 v23, 0x3fcc422a, v23
	v_mul_f32_e32 v23, 0xbfb8aa3b, v23
	v_exp_f32_e32 v23, v23
	v_cvt_pk_bf16_f32 v17, v17, v18
	v_cvt_pk_bf16_f32 v18, v24, v21
	v_lshl_add_u64 v[20:21], s[30:31], 0, v[160:161]
	v_add_f32_e32 v23, 1.0, v23
	v_rcp_f32_e32 v23, v23
	v_lshl_add_u64 v[20:21], v[20:21], 0, vcc
	v_lshl_add_u64 v[20:21], v[20:21], 0, v[140:141]
	v_mul_f32_e32 v19, v19, v23
	v_cvt_pk_bf16_f32 v19, v22, v19
	global_store_dwordx4 v[20:21], v[16:19], off
	s_nop 1
	v_add_u32_e32 v16, 0xb0, v158
	v_lshlrev_b32_e32 v17, 4, v16
	v_mad_i64_i32 v[20:21], s[4:5], v16, s41, v[138:139]
	v_and_b32_e32 v22, 0x7ff0, v17
	v_mov_b32_e32 v16, v234
	v_mov_b32_e32 v17, v235
	v_mov_b32_e32 v18, v236
	v_mov_b32_e32 v19, v237
	s_mov_b64 s[4:5], -1
	v_lshlrev_b32_e32 v23, 16, v16
	v_and_b32_e32 v28, 0xffff0000, v16
	v_lshlrev_b32_e32 v29, 16, v17
	v_and_b32_e32 v30, 0xffff0000, v17
	v_lshlrev_b32_e32 v31, 16, v18
	v_and_b32_e32 v32, 0xffff0000, v18
	v_lshlrev_b32_e32 v33, 16, v19
	v_and_b32_e32 v34, 0xffff0000, v19
	v_mov_b32_e32 v16, v192
	v_mov_b32_e32 v17, v193
	v_mov_b32_e32 v18, v194
	v_mov_b32_e32 v19, v195
	v_mov_b32_e32 v24, v196
	v_mov_b32_e32 v25, v197
	v_mov_b32_e32 v26, v198
	v_mov_b32_e32 v27, v199
	v_fmac_f32_e32 v8, v16, v31
	v_mul_f32_e32 v16, 0x3d372713, v8
	v_mul_f32_e32 v16, v8, v16
	v_fma_f32 v16, v8, v16, v8
	v_mul_f32_e32 v16, 0x3fcc422a, v16
	v_mul_f32_e32 v16, 0xbfb8aa3b, v16
	v_exp_f32_e32 v16, v16
	v_fmac_f32_e32 v13, v25, v28
	v_fmac_f32_e32 v9, v17, v32
	v_fmac_f32_e32 v14, v26, v29
	v_add_f32_e32 v16, 1.0, v16
	v_rcp_f32_e32 v16, v16
	v_fmac_f32_e32 v10, v18, v33
	v_fmac_f32_e32 v15, v27, v30
	v_fmac_f32_e32 v12, v24, v23
	v_mul_f32_e32 v16, v8, v16
	v_mul_f32_e32 v8, 0x3d372713, v13
	v_mul_f32_e32 v8, v13, v8
	v_fma_f32 v8, v13, v8, v13
	v_mul_f32_e32 v8, 0x3fcc422a, v8
	v_mul_f32_e32 v8, 0xbfb8aa3b, v8
	v_exp_f32_e32 v8, v8
	v_mul_f32_e32 v23, 0x3d372713, v12
	v_mul_f32_e32 v23, v12, v23
	v_fma_f32 v23, v12, v23, v12
	v_add_f32_e32 v8, 1.0, v8
	v_rcp_f32_e32 v8, v8
	v_mul_f32_e32 v23, 0x3fcc422a, v23
	v_mul_f32_e32 v23, 0xbfb8aa3b, v23
	v_fmac_f32_e32 v11, v19, v34
	v_mul_f32_e32 v8, v13, v8
	v_mul_f32_e32 v13, 0x3d372713, v9
	v_mul_f32_e32 v13, v9, v13
	v_fma_f32 v13, v9, v13, v9
	v_mul_f32_e32 v13, 0x3fcc422a, v13
	v_mul_f32_e32 v13, 0xbfb8aa3b, v13
	v_exp_f32_e32 v13, v13
	v_exp_f32_e32 v23, v23
	v_add_f32_e32 v13, 1.0, v13
	v_rcp_f32_e32 v13, v13
	v_add_f32_e32 v23, 1.0, v23
	v_rcp_f32_e32 v23, v23
	v_mul_f32_e32 v13, v9, v13
	v_mul_f32_e32 v9, 0x3d372713, v14
	v_mul_f32_e32 v9, v14, v9
	v_fma_f32 v9, v14, v9, v14
	v_mul_f32_e32 v9, 0x3fcc422a, v9
	v_mul_f32_e32 v9, 0xbfb8aa3b, v9
	v_exp_f32_e32 v9, v9
	v_mul_f32_e32 v12, v12, v23
	v_cvt_pk_bf16_f32 v8, v12, v8
	v_or_b32_e32 v12, v22, v151
	v_add_f32_e32 v9, 1.0, v9
	v_rcp_f32_e32 v9, v9
	v_lshlrev_b32_e32 v160, 10, v12
	v_mul_f32_e32 v9, v14, v9
	v_mul_f32_e32 v14, 0x3d372713, v10
	v_mul_f32_e32 v14, v10, v14
	v_fma_f32 v14, v10, v14, v10
	v_mul_f32_e32 v14, 0x3fcc422a, v14
	v_mul_f32_e32 v14, 0xbfb8aa3b, v14
	v_exp_f32_e32 v14, v14
	s_nop 0
	v_add_f32_e32 v14, 1.0, v14
	v_rcp_f32_e32 v14, v14
	s_nop 0
	v_mul_f32_e32 v14, v10, v14
	v_mul_f32_e32 v10, 0x3d372713, v15
; __device__ __forceinline__ unsigned cvt_pk_bf16(float lo, float hi) { unsigned r; asm volatile("v_cvt_pk_bf16_f32 %0, %1, %2" : "=v"(r) : "v"(lo), "v"(hi)); return r; }
; __device__ __forceinline__ float gelu_t(float x) { const float z = 1.5957691216f * (x + 0.044715f * x * x * x); return x * sigm(z); }
; __device__ __forceinline__ void UNPACK8(const u32x4 q, float (&f)[8]) { f[0] = bflo(q.x); f[1] = bfhi(q.x); f[2] = bflo(q.y); f[3] = bfhi(q.y); f[4] = bflo(q.z); f[5] = bfhi(q.z); f[6] = bflo(q.w); f[7] = bfhi(q.w); }
; #define EPI_FOR_ROWS() _Pragma("unroll") for (int ai = 0; ai < 2; ++ai) _Pragma("unroll") for (int m = 0; m < 4; ++m)
;     __device__ __forceinline__ void operator()(const f32x4 (&acc)[2][2][4][2], const Unit& u, int wr, int wc, int fr, int fq) const {
;         const int row0 = u.pm * 256 + wr * 64 + fr, col0 = wc * 32 + 8 * fq; const int g = u.pn;
;         EPI_FOR_ROWS() {
;             const int gr = row0 + ai * 128 + m * 16, chunk = gr & 2047;
; #pragma unroll
;             for (int bj = 0; bj < 2; ++bj) { const int col = col0 + bj * 128, t = col >> 4, h0 = col & 15;
;                 const u32x4 uw = *(const u32x4*)(a2 + (size_t)gr * 384 + col); float uu[8]; UNPACK8(uw, uu);
;                 const f32x4 d0 = *(const f32x4*)(dsk + g * 16 + h0), d1 = *(const f32x4*)(dsk + g * 16 + h0 + 4); float o[8];
; #pragma unroll
;                 for (int e = 0; e < 4; ++e) { o[e] = gelu_t(acc[ai][bj][m][0][e] + d0[e] * uu[e]); o[4 + e] = gelu_t(acc[ai][bj][m][1][e] + d1[e] * uu[4 + e]); }
;                 u32x4 w; w.x = cvt_pk_bf16(o[0], o[1]); w.y = cvt_pk_bf16(o[2], o[3]); w.z = cvt_pk_bf16(o[4], o[5]); w.w = cvt_pk_bf16(o[6], o[7]);
;                 *(u32x4*)(yg + ((size_t)chunk * 16 + t) * 512 + g * 16 + h0) = w; }
;         }
;     }
	v_mul_f32_e32 v10, v15, v10
	v_fma_f32 v10, v15, v10, v15
	v_mul_f32_e32 v10, 0x3fcc422a, v10
	v_mul_f32_e32 v10, 0xbfb8aa3b, v10
	v_exp_f32_e32 v10, v10
	s_nop 0
	v_add_f32_e32 v10, 1.0, v10
	v_rcp_f32_e32 v10, v10
	s_nop 0
	v_mul_f32_e32 v10, v15, v10
	v_mul_f32_e32 v15, 0x3d372713, v11
	v_mul_f32_e32 v15, v11, v15
	v_fma_f32 v15, v11, v15, v11
	v_mul_f32_e32 v15, 0x3fcc422a, v15
	v_mul_f32_e32 v15, 0xbfb8aa3b, v15
	v_exp_f32_e32 v15, v15
	v_cvt_pk_bf16_f32 v9, v9, v10
	v_cvt_pk_bf16_f32 v10, v16, v13
	v_lshl_add_u64 v[12:13], s[30:31], 0, v[160:161]
	v_add_f32_e32 v15, 1.0, v15
	v_rcp_f32_e32 v15, v15
	v_lshl_add_u64 v[12:13], v[12:13], 0, vcc
	v_lshl_add_u64 v[12:13], v[12:13], 0, v[140:141]
	v_mul_f32_e32 v11, v11, v15
	v_cvt_pk_bf16_f32 v11, v14, v11
	global_store_dwordx4 v[12:13], v[8:11], off
	s_nop 1
	v_mov_b32_e32 v8, v238
	v_mov_b32_e32 v9, v239
	v_mov_b32_e32 v10, v240
	v_mov_b32_e32 v11, v241
	v_lshlrev_b32_e32 v16, 16, v8
	v_and_b32_e32 v17, 0xffff0000, v8
	v_lshlrev_b32_e32 v18, 16, v9
	v_and_b32_e32 v19, 0xffff0000, v9
	v_lshlrev_b32_e32 v20, 16, v10
	v_and_b32_e32 v21, 0xffff0000, v10
	v_lshlrev_b32_e32 v23, 16, v11
	v_and_b32_e32 v24, 0xffff0000, v11
	v_mov_b32_e32 v8, v192
	v_mov_b32_e32 v9, v193
	v_mov_b32_e32 v10, v194
	v_mov_b32_e32 v11, v195
	v_mov_b32_e32 v12, v196
	v_mov_b32_e32 v13, v197
	v_mov_b32_e32 v14, v198
	v_mov_b32_e32 v15, v199
	v_fmac_f32_e32 v0, v8, v20
	v_mul_f32_e32 v8, 0x3d372713, v0
	v_mul_f32_e32 v8, v0, v8
	v_fma_f32 v8, v0, v8, v0
	v_mul_f32_e32 v8, 0x3fcc422a, v8
	v_mul_f32_e32 v8, 0xbfb8aa3b, v8
	v_exp_f32_e32 v8, v8
	v_fmac_f32_e32 v5, v13, v17
	v_fmac_f32_e32 v1, v9, v21
	v_fmac_f32_e32 v6, v14, v18
	v_add_f32_e32 v8, 1.0, v8
	v_rcp_f32_e32 v8, v8
	v_fmac_f32_e32 v2, v10, v23
	v_fmac_f32_e32 v7, v15, v19
	v_fmac_f32_e32 v4, v12, v16
	v_mul_f32_e32 v8, v0, v8
	v_mul_f32_e32 v0, 0x3d372713, v5
	v_mul_f32_e32 v0, v5, v0
	v_fma_f32 v0, v5, v0, v5
	v_mul_f32_e32 v0, 0x3fcc422a, v0
	v_mul_f32_e32 v0, 0xbfb8aa3b, v0
	v_exp_f32_e32 v0, v0
	v_mul_f32_e32 v12, 0x3d372713, v4
	v_mul_f32_e32 v12, v4, v12
	v_fma_f32 v12, v4, v12, v4
	v_add_f32_e32 v0, 1.0, v0
	v_rcp_f32_e32 v0, v0
	v_mul_f32_e32 v12, 0x3fcc422a, v12
	v_mul_f32_e32 v12, 0xbfb8aa3b, v12
	v_fmac_f32_e32 v3, v11, v24
	v_mul_f32_e32 v0, v5, v0
	v_mul_f32_e32 v5, 0x3d372713, v1
	v_mul_f32_e32 v5, v1, v5
	v_fma_f32 v5, v1, v5, v1
	v_mul_f32_e32 v5, 0x3fcc422a, v5
	v_mul_f32_e32 v5, 0xbfb8aa3b, v5
	v_exp_f32_e32 v5, v5
	v_exp_f32_e32 v12, v12
	v_add_f32_e32 v5, 1.0, v5
	v_rcp_f32_e32 v5, v5
	v_add_f32_e32 v12, 1.0, v12
	v_rcp_f32_e32 v12, v12
	v_mul_f32_e32 v5, v1, v5
	v_mul_f32_e32 v1, 0x3d372713, v6
	v_mul_f32_e32 v1, v6, v1
	v_fma_f32 v1, v6, v1, v6
	v_mul_f32_e32 v1, 0x3fcc422a, v1
	v_mul_f32_e32 v1, 0xbfb8aa3b, v1
	v_exp_f32_e32 v1, v1
	v_mul_f32_e32 v4, v4, v12
	v_cvt_pk_bf16_f32 v0, v4, v0
	v_or_b32_e32 v4, v22, v152
	v_add_f32_e32 v1, 1.0, v1
	v_rcp_f32_e32 v1, v1
	v_lshlrev_b32_e32 v160, 10, v4
	v_mul_f32_e32 v1, v6, v1
	v_mul_f32_e32 v6, 0x3d372713, v2
	v_mul_f32_e32 v6, v2, v6
	v_fma_f32 v6, v2, v6, v2
	v_mul_f32_e32 v6, 0x3fcc422a, v6
	v_mul_f32_e32 v6, 0xbfb8aa3b, v6
	v_exp_f32_e32 v6, v6
	s_nop 0
	v_add_f32_e32 v6, 1.0, v6
	v_rcp_f32_e32 v6, v6
	s_nop 0
	v_mul_f32_e32 v6, v2, v6
	v_mul_f32_e32 v2, 0x3d372713, v7
	v_mul_f32_e32 v2, v7, v2
	v_fma_f32 v2, v7, v2, v7
	v_mul_f32_e32 v2, 0x3fcc422a, v2
	v_mul_f32_e32 v2, 0xbfb8aa3b, v2
	v_exp_f32_e32 v2, v2
	s_nop 0
	v_add_f32_e32 v2, 1.0, v2
	v_rcp_f32_e32 v2, v2
	s_nop 0
	v_mul_f32_e32 v2, v7, v2
	v_mul_f32_e32 v7, 0x3d372713, v3
	v_mul_f32_e32 v7, v3, v7
	v_fma_f32 v7, v3, v7, v3
	v_mul_f32_e32 v7, 0x3fcc422a, v7
	v_mul_f32_e32 v7, 0xbfb8aa3b, v7
	v_exp_f32_e32 v7, v7
	v_cvt_pk_bf16_f32 v1, v1, v2
	v_cvt_pk_bf16_f32 v2, v8, v5
	v_lshl_add_u64 v[4:5], s[30:31], 0, v[160:161]
	v_add_f32_e32 v7, 1.0, v7
	v_rcp_f32_e32 v7, v7
	v_lshl_add_u64 v[4:5], v[4:5], 0, vcc
	v_lshl_add_u64 v[4:5], v[4:5], 0, v[140:141]
	s_and_b64 vcc, exec, s[8:9]
	v_mul_f32_e32 v3, v3, v7
	v_cvt_pk_bf16_f32 v3, v6, v3
	global_store_dwordx4 v[4:5], v[0:3], off
	s_cbranch_vccnz .LBB0_790
	v_readlane_b32 s4, v255, 4
	v_readlane_b32 s5, v255, 5
	s_andn2_b64 vcc, exec, s[4:5]
	s_cbranch_vccnz .LBB0_789
	s_barrier
	s_branch .LBB0_789

; __device__ __forceinline__ unsigned cvt_pk_bf16(float lo, float hi) { unsigned r; asm volatile("v_cvt_pk_bf16_f32 %0, %1, %2" : "=v"(r) : "v"(lo), "v"(hi)); return r; }
; __device__ __forceinline__ float sigm(float x) { return __builtin_amdgcn_rcpf(1.0f + __expf(-x)); }
; __device__ __forceinline__ void UNPACK8(const u32x4 q, float (&f)[8]) { f[0] = bflo(q.x); f[1] = bfhi(q.x); f[2] = bflo(q.y); f[3] = bfhi(q.y); f[4] = bflo(q.z); f[5] = bfhi(q.z); f[6] = bflo(q.w); f[7] = bfhi(q.w); }
; #define EPI_FOR_ROWS() _Pragma("unroll") for (int ai = 0; ai < 2; ++ai) _Pragma("unroll") for (int m = 0; m < 4; ++m)
;     __device__ __forceinline__ void operator()(const f32x4 (&acc)[2][2][4][2], const Unit& u, int wr, int wc, int fr, int fq) const {
;         EPI_ROWCOL();
;         EPI_FOR_ROWS() {
;             const int row = row0 + ai * 128 + m * 16;
; #pragma unroll
;             for (int bj = 0; bj < 2; ++bj) { const int col = col0 + bj * 128;
;                 const f32x4 b0 = *(const f32x4*)(gb + col), b1 = *(const f32x4*)(gb + col + 4);
;                 const u32x4 yw = *(const u32x4*)(yg + (size_t)row * 512 + col); float y[8]; UNPACK8(yw, y);
;                 const f32x4 a0 = acc[ai][bj][m][0] + b0, a1 = acc[ai][bj][m][1] + b1; float o[8];
; #pragma unroll
;                 for (int e = 0; e < 4; ++e) { o[e] = y[e] * sigm(a0[e]); o[4 + e] = y[4 + e] * sigm(a1[e]); }
;                 u32x4 w; w.x = cvt_pk_bf16(o[0], o[1]); w.y = cvt_pk_bf16(o[2], o[3]); w.z = cvt_pk_bf16(o[4], o[5]); w.w = cvt_pk_bf16(o[6], o[7]);
;                 *(u32x4*)(mix + (size_t)row * 1024 + 512 + col) = w; }
;         }
;     }
.LBB0_873:
	v_lshl_or_b32 v130, s64, 8, v139
	v_ashrrev_i32_e32 v131, 31, v130
	v_lshl_add_u64 v[128:129], v[130:131], 2, s[2:3]
	v_lshl_add_u32 v132, s63, 8, v138
	v_ashrrev_i32_e32 v133, 31, v132
	v_lshlrev_b64 v[154:155], 10, v[132:133]
	v_lshlrev_b64 v[130:131], 1, v[130:131]
	v_lshl_add_u64 v[154:155], s[30:31], 0, v[154:155]
	v_lshl_add_u64 v[158:159], v[154:155], 0, v[130:131]
	s_andn2_b64 vcc, exec, s[6:7]
	s_mov_b64 s[6:7], -1
	global_load_dwordx4 v[166:169], v[128:129], off
	global_load_dwordx4 v[190:193], v[128:129], off offset:16
	global_load_dwordx4 v[202:205], v[158:159], off
	global_load_dwordx4 v[214:217], v[158:159], off offset:256
	global_load_dwordx4 v[194:197], v[128:129], off offset:512
	global_load_dwordx4 v[198:201], v[128:129], off offset:528
	v_or_b32_e32 v178, 16, v132
	v_ashrrev_i32_e32 v179, 31, v178
	v_lshlrev_b64 v[180:181], 10, v[178:179]
	v_lshl_add_u64 v[180:181], s[30:31], 0, v[180:181]
	v_lshl_add_u64 v[180:181], v[180:181], 0, v[130:131]
	global_load_dwordx4 v[218:221], v[180:181], off
	v_or_b32_e32 v178, 16, v132
	v_ashrrev_i32_e32 v179, 31, v178
	v_lshlrev_b64 v[180:181], 10, v[178:179]
	v_lshl_add_u64 v[180:181], s[30:31], 0, v[180:181]
	v_lshl_add_u64 v[180:181], v[180:181], 0, v[130:131]
	global_load_dwordx4 v[222:225], v[180:181], off offset:256
	v_or_b32_e32 v178, 32, v132
	v_ashrrev_i32_e32 v179, 31, v178
	v_lshlrev_b64 v[180:181], 10, v[178:179]
	v_lshl_add_u64 v[180:181], s[30:31], 0, v[180:181]
	v_lshl_add_u64 v[180:181], v[180:181], 0, v[130:131]
	global_load_dwordx4 v[226:229], v[180:181], off
	v_or_b32_e32 v178, 32, v132
	v_ashrrev_i32_e32 v179, 31, v178
	v_lshlrev_b64 v[180:181], 10, v[178:179]
	v_lshl_add_u64 v[180:181], s[30:31], 0, v[180:181]
	v_lshl_add_u64 v[180:181], v[180:181], 0, v[130:131]
	global_load_dwordx4 v[230:233], v[180:181], off offset:256
	v_or_b32_e32 v178, 48, v132
	v_ashrrev_i32_e32 v179, 31, v178
	v_lshlrev_b64 v[180:181], 10, v[178:179]
	v_lshl_add_u64 v[180:181], s[30:31], 0, v[180:181]
	v_lshl_add_u64 v[180:181], v[180:181], 0, v[130:131]
	global_load_dwordx4 v[234:237], v[180:181], off
	v_or_b32_e32 v178, 48, v132
	v_ashrrev_i32_e32 v179, 31, v178
	v_lshlrev_b64 v[180:181], 10, v[178:179]
	v_lshl_add_u64 v[180:181], s[30:31], 0, v[180:181]
	v_lshl_add_u64 v[180:181], v[180:181], 0, v[130:131]
	global_load_dwordx4 v[238:241], v[180:181], off offset:256
	s_waitcnt vmcnt(0)
	v_mov_b32_e32 v146, v166
	v_mov_b32_e32 v147, v167
	v_mov_b32_e32 v148, v168
	v_mov_b32_e32 v149, v169
	v_mov_b32_e32 v150, v190
	v_mov_b32_e32 v151, v191
	v_mov_b32_e32 v152, v192
	v_mov_b32_e32 v153, v193
	v_mov_b32_e32 v154, v202
	v_mov_b32_e32 v155, v203
	v_mov_b32_e32 v156, v204
	v_mov_b32_e32 v157, v205
	v_add_f32_e32 v124, v124, v146
	v_add_f32_e32 v120, v120, v150
	v_add_f32_e32 v125, v125, v147
	v_add_f32_e32 v121, v121, v151
	v_add_f32_e32 v126, v126, v148
	v_mul_f32_e32 v124, 0xbfb8aa3b, v124
	v_mul_f32_e32 v120, 0xbfb8aa3b, v120
	v_mul_f32_e32 v125, 0xbfb8aa3b, v125
	v_mul_f32_e32 v121, 0xbfb8aa3b, v121
	v_mul_f32_e32 v126, 0xbfb8aa3b, v126
	v_add_f32_e32 v122, v122, v152
	v_add_f32_e32 v127, v127, v149
	v_add_f32_e32 v123, v123, v153
	v_exp_f32_e32 v124, v124
	v_exp_f32_e32 v120, v120
	v_exp_f32_e32 v125, v125
	v_exp_f32_e32 v121, v121
	v_exp_f32_e32 v126, v126
	v_mul_f32_e32 v122, 0xbfb8aa3b, v122
	v_mul_f32_e32 v127, 0xbfb8aa3b, v127
	v_mul_f32_e32 v123, 0xbfb8aa3b, v123
	v_exp_f32_e32 v122, v122
	v_exp_f32_e32 v127, v127
	v_exp_f32_e32 v123, v123
	v_add_f32_e32 v124, 1.0, v124
	v_add_f32_e32 v120, 1.0, v120
	v_add_f32_e32 v125, 1.0, v125
	v_add_f32_e32 v121, 1.0, v121
	v_add_f32_e32 v126, 1.0, v126
	v_rcp_f32_e32 v124, v124
	v_rcp_f32_e32 v120, v120
	v_rcp_f32_e32 v125, v125
	v_rcp_f32_e32 v121, v121
	v_rcp_f32_e32 v126, v126
	v_add_f32_e32 v122, 1.0, v122
	v_add_f32_e32 v127, 1.0, v127
	v_add_f32_e32 v123, 1.0, v123
	v_rcp_f32_e32 v122, v122
	v_rcp_f32_e32 v127, v127
	v_rcp_f32_e32 v123, v123
	v_lshlrev_b32_e32 v145, 16, v154
	v_and_b32_e32 v146, 0xffff0000, v154
	v_lshlrev_b32_e32 v147, 16, v155
	v_lshlrev_b32_e32 v149, 16, v156
	v_and_b32_e32 v150, 0xffff0000, v156
	v_mul_f32_e32 v124, v124, v145
	v_mul_f32_e32 v145, v120, v149
	v_mul_f32_e32 v120, v125, v146
	v_mul_f32_e32 v125, v121, v150
	v_mul_f32_e32 v121, v126, v147
	v_lshlrev_b64 v[146:147], 11, v[132:133]
	v_and_b32_e32 v148, 0xffff0000, v155
	v_lshlrev_b32_e32 v151, 16, v157
	v_and_b32_e32 v152, 0xffff0000, v157
	v_lshl_add_u64 v[146:147], s[26:27], 0, v[146:147]
	v_mul_f32_e32 v126, v122, v151
	v_mul_f32_e32 v122, v127, v148
	v_mul_f32_e32 v123, v123, v152
	v_lshl_add_u64 v[150:151], v[146:147], 0, v[130:131]
	v_cvt_pk_bf16_f32 v120, v124, v120
	v_cvt_pk_bf16_f32 v121, v121, v122
	v_cvt_pk_bf16_f32 v122, v145, v125
	v_cvt_pk_bf16_f32 v123, v126, v123
	global_store_dwordx4 v[150:151], v[120:123], off offset:1024
	v_mov_b32_e32 v124, v214
	v_mov_b32_e32 v125, v215
	v_mov_b32_e32 v126, v216
	v_mov_b32_e32 v127, v217
	s_nop 0
	v_mov_b32_e32 v120, v194
	v_mov_b32_e32 v121, v195
	v_mov_b32_e32 v122, v196
	v_mov_b32_e32 v123, v197
	v_mov_b32_e32 v146, v198
	v_mov_b32_e32 v147, v199
	v_mov_b32_e32 v148, v200
	v_mov_b32_e32 v149, v201
	v_or_b32_e32 v152, 16, v132
	v_ashrrev_i32_e32 v153, 31, v152
	v_lshlrev_b64 v[154:155], 10, v[152:153]
	v_lshl_add_u64 v[154:155], s[30:31], 0, v[154:155]
	v_lshl_add_u64 v[154:155], v[154:155], 0, v[130:131]
	v_lshlrev_b32_e32 v133, 16, v124
	v_add_f32_e32 v112, v112, v146
	v_add_f32_e32 v117, v117, v121
	v_add_f32_e32 v113, v113, v147
	v_add_f32_e32 v118, v118, v122
	v_add_f32_e32 v114, v114, v148
	v_add_f32_e32 v119, v119, v123
	v_add_f32_e32 v115, v115, v149
	v_add_f32_e32 v116, v116, v120
; __device__ __forceinline__ unsigned cvt_pk_bf16(float lo, float hi) { unsigned r; asm volatile("v_cvt_pk_bf16_f32 %0, %1, %2" : "=v"(r) : "v"(lo), "v"(hi)); return r; }
; __device__ __forceinline__ float sigm(float x) { return __builtin_amdgcn_rcpf(1.0f + __expf(-x)); }
; __device__ __forceinline__ void UNPACK8(const u32x4 q, float (&f)[8]) { f[0] = bflo(q.x); f[1] = bfhi(q.x); f[2] = bflo(q.y); f[3] = bfhi(q.y); f[4] = bflo(q.z); f[5] = bfhi(q.z); f[6] = bflo(q.w); f[7] = bfhi(q.w); }
; #define EPI_FOR_ROWS() _Pragma("unroll") for (int ai = 0; ai < 2; ++ai) _Pragma("unroll") for (int m = 0; m < 4; ++m)
;     __device__ __forceinline__ void operator()(const f32x4 (&acc)[2][2][4][2], const Unit& u, int wr, int wc, int fr, int fq) const {
;         EPI_ROWCOL();
;         EPI_FOR_ROWS() {
;             const int row = row0 + ai * 128 + m * 16;
; #pragma unroll
;             for (int bj = 0; bj < 2; ++bj) { const int col = col0 + bj * 128;
;                 const f32x4 b0 = *(const f32x4*)(gb + col), b1 = *(const f32x4*)(gb + col + 4);
;                 const u32x4 yw = *(const u32x4*)(yg + (size_t)row * 512 + col); float y[8]; UNPACK8(yw, y);
;                 const f32x4 a0 = acc[ai][bj][m][0] + b0, a1 = acc[ai][bj][m][1] + b1; float o[8];
; #pragma unroll
;                 for (int e = 0; e < 4; ++e) { o[e] = y[e] * sigm(a0[e]); o[4 + e] = y[4 + e] * sigm(a1[e]); }
;                 u32x4 w; w.x = cvt_pk_bf16(o[0], o[1]); w.y = cvt_pk_bf16(o[2], o[3]); w.z = cvt_pk_bf16(o[4], o[5]); w.w = cvt_pk_bf16(o[6], o[7]);
;                 *(u32x4*)(mix + (size_t)row * 1024 + 512 + col) = w; }
;         }
;     }
	v_mul_f32_e32 v112, 0xbfb8aa3b, v112
	v_mul_f32_e32 v117, 0xbfb8aa3b, v117
	v_mul_f32_e32 v113, 0xbfb8aa3b, v113
	v_mul_f32_e32 v118, 0xbfb8aa3b, v118
	v_mul_f32_e32 v114, 0xbfb8aa3b, v114
	v_mul_f32_e32 v119, 0xbfb8aa3b, v119
	v_mul_f32_e32 v115, 0xbfb8aa3b, v115
	v_mul_f32_e32 v116, 0xbfb8aa3b, v116
	v_exp_f32_e32 v112, v112
	v_exp_f32_e32 v117, v117
	v_exp_f32_e32 v113, v113
	v_exp_f32_e32 v118, v118
	v_exp_f32_e32 v114, v114
	v_exp_f32_e32 v119, v119
	v_exp_f32_e32 v115, v115
	v_exp_f32_e32 v116, v116
	v_add_f32_e32 v112, 1.0, v112
	v_add_f32_e32 v117, 1.0, v117
	v_add_f32_e32 v113, 1.0, v113
	v_add_f32_e32 v118, 1.0, v118
	v_add_f32_e32 v114, 1.0, v114
	v_add_f32_e32 v119, 1.0, v119
	v_add_f32_e32 v115, 1.0, v115
	v_add_f32_e32 v116, 1.0, v116
	v_rcp_f32_e32 v112, v112
	v_rcp_f32_e32 v117, v117
	v_rcp_f32_e32 v113, v113
	v_rcp_f32_e32 v118, v118
	v_rcp_f32_e32 v114, v114
	v_rcp_f32_e32 v119, v119
	v_rcp_f32_e32 v115, v115
	v_rcp_f32_e32 v116, v116
	v_and_b32_e32 v124, 0xffff0000, v124
	v_lshlrev_b32_e32 v145, 16, v125
	v_and_b32_e32 v125, 0xffff0000, v125
	v_lshlrev_b32_e32 v156, 16, v126
	v_and_b32_e32 v126, 0xffff0000, v126
	v_lshlrev_b32_e32 v157, 16, v127
	v_and_b32_e32 v127, 0xffff0000, v127
	v_mul_f32_e32 v120, v112, v156
	v_mul_f32_e32 v112, v117, v124
	v_mul_f32_e32 v117, v113, v126
	v_mul_f32_e32 v113, v118, v145
	v_mul_f32_e32 v118, v114, v157
	v_mul_f32_e32 v114, v119, v125
	v_mul_f32_e32 v115, v115, v127
	v_mul_f32_e32 v116, v116, v133
	v_cvt_pk_bf16_f32 v112, v116, v112
	v_cvt_pk_bf16_f32 v113, v113, v114
	v_cvt_pk_bf16_f32 v114, v120, v117
	v_cvt_pk_bf16_f32 v115, v118, v115
	global_store_dwordx4 v[150:151], v[112:115], off offset:1280
	v_mov_b32_e32 v116, v218
	v_mov_b32_e32 v117, v219
	v_mov_b32_e32 v118, v220
	v_mov_b32_e32 v119, v221
	s_nop 0
	v_mov_b32_e32 v112, v166
	v_mov_b32_e32 v113, v167
	v_mov_b32_e32 v114, v168
	v_mov_b32_e32 v115, v169
	v_mov_b32_e32 v120, v190
	v_mov_b32_e32 v121, v191
	v_mov_b32_e32 v122, v192
	v_mov_b32_e32 v123, v193
	v_add_f32_e32 v109, v109, v113
	v_add_f32_e32 v104, v104, v120
	v_add_f32_e32 v105, v105, v121
	v_add_f32_e32 v110, v110, v114
	v_add_f32_e32 v106, v106, v122
	v_add_f32_e32 v111, v111, v115
	v_add_f32_e32 v108, v108, v112
	v_mul_f32_e32 v104, 0xbfb8aa3b, v104
	v_mul_f32_e32 v109, 0xbfb8aa3b, v109
	v_mul_f32_e32 v105, 0xbfb8aa3b, v105
	v_mul_f32_e32 v110, 0xbfb8aa3b, v110
	v_mul_f32_e32 v106, 0xbfb8aa3b, v106
	v_mul_f32_e32 v111, 0xbfb8aa3b, v111
	v_mul_f32_e32 v108, 0xbfb8aa3b, v108
	v_exp_f32_e32 v104, v104
	v_exp_f32_e32 v109, v109
	v_exp_f32_e32 v105, v105
	v_exp_f32_e32 v110, v110
	v_exp_f32_e32 v106, v106
	v_exp_f32_e32 v111, v111
	v_add_f32_e32 v107, v107, v123
	v_exp_f32_e32 v108, v108
	v_mul_f32_e32 v107, 0xbfb8aa3b, v107
	v_exp_f32_e32 v107, v107
	v_add_f32_e32 v104, 1.0, v104
	v_add_f32_e32 v109, 1.0, v109
	v_add_f32_e32 v105, 1.0, v105
	v_add_f32_e32 v110, 1.0, v110
	v_add_f32_e32 v106, 1.0, v106
	v_add_f32_e32 v111, 1.0, v111
	v_add_f32_e32 v108, 1.0, v108
	v_rcp_f32_e32 v104, v104
	v_rcp_f32_e32 v109, v109
	v_rcp_f32_e32 v105, v105
	v_rcp_f32_e32 v110, v110
	v_rcp_f32_e32 v106, v106
	v_rcp_f32_e32 v111, v111
	v_rcp_f32_e32 v108, v108
	v_add_f32_e32 v107, 1.0, v107
	v_lshlrev_b32_e32 v124, 16, v116
	v_and_b32_e32 v116, 0xffff0000, v116
	v_lshlrev_b32_e32 v125, 16, v117
	v_and_b32_e32 v117, 0xffff0000, v117
	v_lshlrev_b32_e32 v126, 16, v118
	v_and_b32_e32 v118, 0xffff0000, v118
	v_lshlrev_b32_e32 v127, 16, v119
	v_rcp_f32_e32 v107, v107
	v_mul_f32_e32 v112, v104, v126
	v_mul_f32_e32 v104, v109, v116
	v_mul_f32_e32 v109, v105, v118
	v_mul_f32_e32 v105, v110, v125
	v_mul_f32_e32 v110, v106, v127
	v_mul_f32_e32 v106, v111, v117
	v_mul_f32_e32 v108, v108, v124
	v_cvt_pk_bf16_f32 v104, v108, v104
	v_cvt_pk_bf16_f32 v105, v105, v106
	v_cvt_pk_bf16_f32 v106, v112, v109
	v_lshlrev_b64 v[112:113], 11, v[152:153]
	v_and_b32_e32 v119, 0xffff0000, v119
	v_lshl_add_u64 v[112:113], s[26:27], 0, v[112:113]
	v_mul_f32_e32 v107, v107, v119
	v_lshl_add_u64 v[116:117], v[112:113], 0, v[130:131]
	v_cvt_pk_bf16_f32 v107, v110, v107
	global_store_dwordx4 v[116:117], v[104:107], off offset:1024
	v_mov_b32_e32 v108, v222
	v_mov_b32_e32 v109, v223
	v_mov_b32_e32 v110, v224
	v_mov_b32_e32 v111, v225
	s_nop 0
	v_mov_b32_e32 v104, v194
	v_mov_b32_e32 v105, v195
	v_mov_b32_e32 v106, v196
	v_mov_b32_e32 v107, v197
	v_mov_b32_e32 v112, v198
	v_mov_b32_e32 v113, v199
	v_mov_b32_e32 v114, v200
	v_mov_b32_e32 v115, v201
	v_or_b32_e32 v118, 32, v132
	v_ashrrev_i32_e32 v119, 31, v118
	v_lshlrev_b64 v[120:121], 10, v[118:119]
	v_lshl_add_u64 v[120:121], s[30:31], 0, v[120:121]
	v_lshl_add_u64 v[120:121], v[120:121], 0, v[130:131]
	v_add_f32_e32 v101, v101, v105
	v_add_f32_e32 v96, v96, v112
	v_add_f32_e32 v97, v97, v113
	v_add_f32_e32 v102, v102, v106
	v_add_f32_e32 v98, v98, v114
	v_add_f32_e32 v103, v103, v107
	v_add_f32_e32 v99, v99, v115
	v_add_f32_e32 v100, v100, v104
	v_mul_f32_e32 v96, 0xbfb8aa3b, v96
	v_mul_f32_e32 v101, 0xbfb8aa3b, v101
	v_mul_f32_e32 v97, 0xbfb8aa3b, v97
	v_mul_f32_e32 v102, 0xbfb8aa3b, v102
	v_mul_f32_e32 v98, 0xbfb8aa3b, v98
	v_mul_f32_e32 v103, 0xbfb8aa3b, v103
	v_mul_f32_e32 v99, 0xbfb8aa3b, v99
	v_mul_f32_e32 v100, 0xbfb8aa3b, v100
	v_exp_f32_e32 v96, v96
	v_exp_f32_e32 v101, v101
	v_exp_f32_e32 v97, v97
	v_exp_f32_e32 v102, v102
	v_exp_f32_e32 v98, v98
	v_exp_f32_e32 v103, v103
	v_exp_f32_e32 v99, v99
	v_exp_f32_e32 v100, v100
	v_add_f32_e32 v96, 1.0, v96
	v_add_f32_e32 v101, 1.0, v101
	v_add_f32_e32 v97, 1.0, v97
	v_add_f32_e32 v102, 1.0, v102
	v_add_f32_e32 v98, 1.0, v98
	v_add_f32_e32 v103, 1.0, v103
	v_add_f32_e32 v99, 1.0, v99
	v_add_f32_e32 v100, 1.0, v100
; __device__ __forceinline__ unsigned cvt_pk_bf16(float lo, float hi) { unsigned r; asm volatile("v_cvt_pk_bf16_f32 %0, %1, %2" : "=v"(r) : "v"(lo), "v"(hi)); return r; }
; __device__ __forceinline__ float sigm(float x) { return __builtin_amdgcn_rcpf(1.0f + __expf(-x)); }
; __device__ __forceinline__ void UNPACK8(const u32x4 q, float (&f)[8]) { f[0] = bflo(q.x); f[1] = bfhi(q.x); f[2] = bflo(q.y); f[3] = bfhi(q.y); f[4] = bflo(q.z); f[5] = bfhi(q.z); f[6] = bflo(q.w); f[7] = bfhi(q.w); }
; #define EPI_FOR_ROWS() _Pragma("unroll") for (int ai = 0; ai < 2; ++ai) _Pragma("unroll") for (int m = 0; m < 4; ++m)
;     __device__ __forceinline__ void operator()(const f32x4 (&acc)[2][2][4][2], const Unit& u, int wr, int wc, int fr, int fq) const {
;         EPI_ROWCOL();
;         EPI_FOR_ROWS() {
;             const int row = row0 + ai * 128 + m * 16;
; #pragma unroll
;             for (int bj = 0; bj < 2; ++bj) { const int col = col0 + bj * 128;
;                 const f32x4 b0 = *(const f32x4*)(gb + col), b1 = *(const f32x4*)(gb + col + 4);
;                 const u32x4 yw = *(const u32x4*)(yg + (size_t)row * 512 + col); float y[8]; UNPACK8(yw, y);
;                 const f32x4 a0 = acc[ai][bj][m][0] + b0, a1 = acc[ai][bj][m][1] + b1; float o[8];
; #pragma unroll
;                 for (int e = 0; e < 4; ++e) { o[e] = y[e] * sigm(a0[e]); o[4 + e] = y[4 + e] * sigm(a1[e]); }
;                 u32x4 w; w.x = cvt_pk_bf16(o[0], o[1]); w.y = cvt_pk_bf16(o[2], o[3]); w.z = cvt_pk_bf16(o[4], o[5]); w.w = cvt_pk_bf16(o[6], o[7]);
;                 *(u32x4*)(mix + (size_t)row * 1024 + 512 + col) = w; }
;         }
;     }
	v_rcp_f32_e32 v96, v96
	v_rcp_f32_e32 v101, v101
	v_rcp_f32_e32 v97, v97
	v_rcp_f32_e32 v102, v102
	v_rcp_f32_e32 v98, v98
	v_rcp_f32_e32 v103, v103
	v_rcp_f32_e32 v99, v99
	v_rcp_f32_e32 v100, v100
	v_lshlrev_b32_e32 v122, 16, v108
	v_and_b32_e32 v108, 0xffff0000, v108
	v_lshlrev_b32_e32 v123, 16, v109
	v_and_b32_e32 v109, 0xffff0000, v109
	v_lshlrev_b32_e32 v124, 16, v110
	v_and_b32_e32 v110, 0xffff0000, v110
	v_lshlrev_b32_e32 v125, 16, v111
	v_and_b32_e32 v111, 0xffff0000, v111
	v_mul_f32_e32 v104, v96, v124
	v_mul_f32_e32 v96, v101, v108
	v_mul_f32_e32 v101, v97, v110
	v_mul_f32_e32 v97, v102, v123
	v_mul_f32_e32 v102, v98, v125
	v_mul_f32_e32 v98, v103, v109
	v_mul_f32_e32 v99, v99, v111
	v_mul_f32_e32 v100, v100, v122
	v_cvt_pk_bf16_f32 v96, v100, v96
	v_cvt_pk_bf16_f32 v97, v97, v98
	v_cvt_pk_bf16_f32 v98, v104, v101
	v_cvt_pk_bf16_f32 v99, v102, v99
	global_store_dwordx4 v[116:117], v[96:99], off offset:1280
	v_mov_b32_e32 v100, v226
	v_mov_b32_e32 v101, v227
	v_mov_b32_e32 v102, v228
	v_mov_b32_e32 v103, v229
	s_nop 0
	v_mov_b32_e32 v96, v166
	v_mov_b32_e32 v97, v167
	v_mov_b32_e32 v98, v168
	v_mov_b32_e32 v99, v169
	v_mov_b32_e32 v104, v190
	v_mov_b32_e32 v105, v191
	v_mov_b32_e32 v106, v192
	v_mov_b32_e32 v107, v193
	v_add_f32_e32 v93, v93, v97
	v_add_f32_e32 v88, v88, v104
	v_add_f32_e32 v89, v89, v105
	v_add_f32_e32 v94, v94, v98
	v_add_f32_e32 v90, v90, v106
	v_add_f32_e32 v95, v95, v99
	v_add_f32_e32 v92, v92, v96
	v_mul_f32_e32 v88, 0xbfb8aa3b, v88
	v_mul_f32_e32 v93, 0xbfb8aa3b, v93
	v_mul_f32_e32 v89, 0xbfb8aa3b, v89
	v_mul_f32_e32 v94, 0xbfb8aa3b, v94
	v_mul_f32_e32 v90, 0xbfb8aa3b, v90
	v_mul_f32_e32 v95, 0xbfb8aa3b, v95
	v_mul_f32_e32 v92, 0xbfb8aa3b, v92
	v_exp_f32_e32 v88, v88
	v_exp_f32_e32 v93, v93
	v_exp_f32_e32 v89, v89
	v_exp_f32_e32 v94, v94
	v_exp_f32_e32 v90, v90
	v_exp_f32_e32 v95, v95
	v_add_f32_e32 v91, v91, v107
	v_exp_f32_e32 v92, v92
	v_mul_f32_e32 v91, 0xbfb8aa3b, v91
	v_exp_f32_e32 v91, v91
	v_add_f32_e32 v88, 1.0, v88
	v_add_f32_e32 v93, 1.0, v93
	v_add_f32_e32 v89, 1.0, v89
	v_add_f32_e32 v94, 1.0, v94
	v_add_f32_e32 v90, 1.0, v90
	v_add_f32_e32 v95, 1.0, v95
	v_add_f32_e32 v92, 1.0, v92
	v_rcp_f32_e32 v88, v88
	v_rcp_f32_e32 v93, v93
	v_rcp_f32_e32 v89, v89
	v_rcp_f32_e32 v94, v94
	v_rcp_f32_e32 v90, v90
	v_rcp_f32_e32 v95, v95
	v_rcp_f32_e32 v92, v92
	v_add_f32_e32 v91, 1.0, v91
	v_lshlrev_b32_e32 v108, 16, v100
	v_and_b32_e32 v100, 0xffff0000, v100
	v_lshlrev_b32_e32 v109, 16, v101
	v_and_b32_e32 v101, 0xffff0000, v101
	v_lshlrev_b32_e32 v110, 16, v102
	v_and_b32_e32 v102, 0xffff0000, v102
	v_lshlrev_b32_e32 v111, 16, v103
	v_rcp_f32_e32 v91, v91
	v_mul_f32_e32 v96, v88, v110
	v_mul_f32_e32 v88, v93, v100
	v_mul_f32_e32 v93, v89, v102
	v_mul_f32_e32 v89, v94, v109
	v_mul_f32_e32 v94, v90, v111
	v_mul_f32_e32 v90, v95, v101
	v_mul_f32_e32 v92, v92, v108
	v_cvt_pk_bf16_f32 v88, v92, v88
	v_cvt_pk_bf16_f32 v89, v89, v90
	v_cvt_pk_bf16_f32 v90, v96, v93
	v_lshlrev_b64 v[96:97], 11, v[118:119]
	v_and_b32_e32 v103, 0xffff0000, v103
	v_lshl_add_u64 v[96:97], s[26:27], 0, v[96:97]
	v_mul_f32_e32 v91, v91, v103
	v_lshl_add_u64 v[100:101], v[96:97], 0, v[130:131]
	v_cvt_pk_bf16_f32 v91, v94, v91
	global_store_dwordx4 v[100:101], v[88:91], off offset:1024
	v_mov_b32_e32 v92, v230
	v_mov_b32_e32 v93, v231
	v_mov_b32_e32 v94, v232
	v_mov_b32_e32 v95, v233
	s_nop 0
	v_mov_b32_e32 v88, v194
	v_mov_b32_e32 v89, v195
	v_mov_b32_e32 v90, v196
	v_mov_b32_e32 v91, v197
	v_mov_b32_e32 v96, v198
	v_mov_b32_e32 v97, v199
	v_mov_b32_e32 v98, v200
	v_mov_b32_e32 v99, v201
	v_or_b32_e32 v102, 48, v132
	v_ashrrev_i32_e32 v103, 31, v102
	v_lshlrev_b64 v[104:105], 10, v[102:103]
	v_lshl_add_u64 v[104:105], s[30:31], 0, v[104:105]
	v_lshl_add_u64 v[104:105], v[104:105], 0, v[130:131]
	v_add_f32_e32 v85, v85, v89
	v_add_f32_e32 v80, v80, v96
	v_add_f32_e32 v81, v81, v97
	v_add_f32_e32 v86, v86, v90
	v_add_f32_e32 v82, v82, v98
	v_add_f32_e32 v87, v87, v91
	v_add_f32_e32 v83, v83, v99
	v_add_f32_e32 v84, v84, v88
	v_mul_f32_e32 v80, 0xbfb8aa3b, v80
	v_mul_f32_e32 v85, 0xbfb8aa3b, v85
	v_mul_f32_e32 v81, 0xbfb8aa3b, v81
	v_mul_f32_e32 v86, 0xbfb8aa3b, v86
	v_mul_f32_e32 v82, 0xbfb8aa3b, v82
	v_mul_f32_e32 v87, 0xbfb8aa3b, v87
	v_mul_f32_e32 v83, 0xbfb8aa3b, v83
	v_mul_f32_e32 v84, 0xbfb8aa3b, v84
	v_exp_f32_e32 v80, v80
	v_exp_f32_e32 v85, v85
	v_exp_f32_e32 v81, v81
	v_exp_f32_e32 v86, v86
	v_exp_f32_e32 v82, v82
	v_exp_f32_e32 v87, v87
	v_exp_f32_e32 v83, v83
	v_exp_f32_e32 v84, v84
	v_add_f32_e32 v80, 1.0, v80
	v_add_f32_e32 v85, 1.0, v85
	v_add_f32_e32 v81, 1.0, v81
	v_add_f32_e32 v86, 1.0, v86
	v_add_f32_e32 v82, 1.0, v82
	v_add_f32_e32 v87, 1.0, v87
	v_add_f32_e32 v83, 1.0, v83
	v_add_f32_e32 v84, 1.0, v84
	v_rcp_f32_e32 v80, v80
	v_rcp_f32_e32 v85, v85
	v_rcp_f32_e32 v81, v81
	v_rcp_f32_e32 v86, v86
	v_rcp_f32_e32 v82, v82
	v_rcp_f32_e32 v87, v87
	v_rcp_f32_e32 v83, v83
	v_rcp_f32_e32 v84, v84
	v_lshlrev_b32_e32 v106, 16, v92
	v_and_b32_e32 v92, 0xffff0000, v92
	v_lshlrev_b32_e32 v107, 16, v93
	v_and_b32_e32 v93, 0xffff0000, v93
	v_lshlrev_b32_e32 v108, 16, v94
	v_and_b32_e32 v94, 0xffff0000, v94
	v_lshlrev_b32_e32 v109, 16, v95
	v_and_b32_e32 v95, 0xffff0000, v95
	v_mul_f32_e32 v88, v80, v108
	v_mul_f32_e32 v80, v85, v92
	v_mul_f32_e32 v85, v81, v94
	v_mul_f32_e32 v81, v86, v107
	v_mul_f32_e32 v86, v82, v109
	v_mul_f32_e32 v82, v87, v93
	v_mul_f32_e32 v83, v83, v95
	v_mul_f32_e32 v84, v84, v106
	v_cvt_pk_bf16_f32 v80, v84, v80
	v_cvt_pk_bf16_f32 v81, v81, v82
	v_cvt_pk_bf16_f32 v82, v88, v85
	v_cvt_pk_bf16_f32 v83, v86, v83
	global_store_dwordx4 v[100:101], v[80:83], off offset:1280
	v_mov_b32_e32 v84, v234
; __device__ __forceinline__ unsigned cvt_pk_bf16(float lo, float hi) { unsigned r; asm volatile("v_cvt_pk_bf16_f32 %0, %1, %2" : "=v"(r) : "v"(lo), "v"(hi)); return r; }
; __device__ __forceinline__ float sigm(float x) { return __builtin_amdgcn_rcpf(1.0f + __expf(-x)); }
; __device__ __forceinline__ void UNPACK8(const u32x4 q, float (&f)[8]) { f[0] = bflo(q.x); f[1] = bfhi(q.x); f[2] = bflo(q.y); f[3] = bfhi(q.y); f[4] = bflo(q.z); f[5] = bfhi(q.z); f[6] = bflo(q.w); f[7] = bfhi(q.w); }
; #define EPI_FOR_ROWS() _Pragma("unroll") for (int ai = 0; ai < 2; ++ai) _Pragma("unroll") for (int m = 0; m < 4; ++m)
;     __device__ __forceinline__ void operator()(const f32x4 (&acc)[2][2][4][2], const Unit& u, int wr, int wc, int fr, int fq) const {
;         EPI_ROWCOL();
;         EPI_FOR_ROWS() {
;             const int row = row0 + ai * 128 + m * 16;
; #pragma unroll
;             for (int bj = 0; bj < 2; ++bj) { const int col = col0 + bj * 128;
;                 const f32x4 b0 = *(const f32x4*)(gb + col), b1 = *(const f32x4*)(gb + col + 4);
;                 const u32x4 yw = *(const u32x4*)(yg + (size_t)row * 512 + col); float y[8]; UNPACK8(yw, y);
;                 const f32x4 a0 = acc[ai][bj][m][0] + b0, a1 = acc[ai][bj][m][1] + b1; float o[8];
; #pragma unroll
;                 for (int e = 0; e < 4; ++e) { o[e] = y[e] * sigm(a0[e]); o[4 + e] = y[4 + e] * sigm(a1[e]); }
;                 u32x4 w; w.x = cvt_pk_bf16(o[0], o[1]); w.y = cvt_pk_bf16(o[2], o[3]); w.z = cvt_pk_bf16(o[4], o[5]); w.w = cvt_pk_bf16(o[6], o[7]);
;                 *(u32x4*)(mix + (size_t)row * 1024 + 512 + col) = w; }
;         }
;     }
	v_mov_b32_e32 v85, v235
	v_mov_b32_e32 v86, v236
	v_mov_b32_e32 v87, v237
	s_nop 0
	v_mov_b32_e32 v80, v166
	v_mov_b32_e32 v81, v167
	v_mov_b32_e32 v82, v168
	v_mov_b32_e32 v83, v169
	v_mov_b32_e32 v88, v190
	v_mov_b32_e32 v89, v191
	v_mov_b32_e32 v90, v192
	v_mov_b32_e32 v91, v193
	v_add_f32_e32 v77, v77, v81
	v_add_f32_e32 v72, v72, v88
	v_add_f32_e32 v73, v73, v89
	v_add_f32_e32 v78, v78, v82
	v_add_f32_e32 v74, v74, v90
	v_add_f32_e32 v79, v79, v83
	v_add_f32_e32 v76, v76, v80
	v_mul_f32_e32 v72, 0xbfb8aa3b, v72
	v_mul_f32_e32 v77, 0xbfb8aa3b, v77
	v_mul_f32_e32 v73, 0xbfb8aa3b, v73
	v_mul_f32_e32 v78, 0xbfb8aa3b, v78
	v_mul_f32_e32 v74, 0xbfb8aa3b, v74
	v_mul_f32_e32 v79, 0xbfb8aa3b, v79
	v_mul_f32_e32 v76, 0xbfb8aa3b, v76
	v_exp_f32_e32 v72, v72
	v_exp_f32_e32 v77, v77
	v_exp_f32_e32 v73, v73
	v_exp_f32_e32 v78, v78
	v_exp_f32_e32 v74, v74
	v_exp_f32_e32 v79, v79
	v_add_f32_e32 v75, v75, v91
	v_exp_f32_e32 v76, v76
	v_mul_f32_e32 v75, 0xbfb8aa3b, v75
	v_exp_f32_e32 v75, v75
	v_add_f32_e32 v72, 1.0, v72
	v_add_f32_e32 v77, 1.0, v77
	v_add_f32_e32 v73, 1.0, v73
	v_add_f32_e32 v78, 1.0, v78
	v_add_f32_e32 v74, 1.0, v74
	v_add_f32_e32 v79, 1.0, v79
	v_add_f32_e32 v76, 1.0, v76
	v_rcp_f32_e32 v72, v72
	v_rcp_f32_e32 v77, v77
	v_rcp_f32_e32 v73, v73
	v_rcp_f32_e32 v78, v78
	v_rcp_f32_e32 v74, v74
	v_rcp_f32_e32 v79, v79
	v_rcp_f32_e32 v76, v76
	v_add_f32_e32 v75, 1.0, v75
	v_lshlrev_b32_e32 v92, 16, v84
	v_and_b32_e32 v84, 0xffff0000, v84
	v_lshlrev_b32_e32 v93, 16, v85
	v_and_b32_e32 v85, 0xffff0000, v85
	v_lshlrev_b32_e32 v94, 16, v86
	v_and_b32_e32 v86, 0xffff0000, v86
	v_lshlrev_b32_e32 v95, 16, v87
	v_rcp_f32_e32 v75, v75
	v_mul_f32_e32 v80, v72, v94
	v_mul_f32_e32 v72, v77, v84
	v_mul_f32_e32 v77, v73, v86
	v_mul_f32_e32 v73, v78, v93
	v_mul_f32_e32 v78, v74, v95
	v_mul_f32_e32 v74, v79, v85
	v_mul_f32_e32 v76, v76, v92
	v_cvt_pk_bf16_f32 v72, v76, v72
	v_cvt_pk_bf16_f32 v73, v73, v74
	v_cvt_pk_bf16_f32 v74, v80, v77
	v_lshlrev_b64 v[80:81], 11, v[102:103]
	v_and_b32_e32 v87, 0xffff0000, v87
	v_lshl_add_u64 v[80:81], s[26:27], 0, v[80:81]
	v_mul_f32_e32 v75, v75, v87
	v_lshl_add_u64 v[84:85], v[80:81], 0, v[130:131]
	v_cvt_pk_bf16_f32 v75, v78, v75
	global_store_dwordx4 v[84:85], v[72:75], off offset:1024
	v_mov_b32_e32 v76, v238
	v_mov_b32_e32 v77, v239
	v_mov_b32_e32 v78, v240
	v_mov_b32_e32 v79, v241
	s_nop 0
	v_mov_b32_e32 v72, v194
	v_mov_b32_e32 v73, v195
	v_mov_b32_e32 v74, v196
	v_mov_b32_e32 v75, v197
	v_mov_b32_e32 v80, v198
	v_mov_b32_e32 v81, v199
	v_mov_b32_e32 v82, v200
	v_mov_b32_e32 v83, v201
	v_add_u32_e32 v86, 0x80, v132
	v_ashrrev_i32_e32 v87, 31, v86
	v_lshlrev_b64 v[88:89], 10, v[86:87]
	v_lshl_add_u64 v[88:89], s[30:31], 0, v[88:89]
	v_lshl_add_u64 v[88:89], v[88:89], 0, v[130:131]
	v_add_f32_e32 v69, v69, v73
	v_add_f32_e32 v64, v64, v80
	v_add_f32_e32 v65, v65, v81
	v_add_f32_e32 v70, v70, v74
	v_add_f32_e32 v66, v66, v82
	v_add_f32_e32 v71, v71, v75
	v_add_f32_e32 v67, v67, v83
	v_add_f32_e32 v68, v68, v72
	v_mul_f32_e32 v64, 0xbfb8aa3b, v64
	v_mul_f32_e32 v69, 0xbfb8aa3b, v69
	v_mul_f32_e32 v65, 0xbfb8aa3b, v65
	v_mul_f32_e32 v70, 0xbfb8aa3b, v70
	v_mul_f32_e32 v66, 0xbfb8aa3b, v66
	v_mul_f32_e32 v71, 0xbfb8aa3b, v71
	v_mul_f32_e32 v67, 0xbfb8aa3b, v67
	v_mul_f32_e32 v68, 0xbfb8aa3b, v68
	v_exp_f32_e32 v64, v64
	v_exp_f32_e32 v69, v69
	v_exp_f32_e32 v65, v65
	v_exp_f32_e32 v70, v70
	v_exp_f32_e32 v66, v66
	v_exp_f32_e32 v71, v71
	v_exp_f32_e32 v67, v67
	v_exp_f32_e32 v68, v68
	v_add_f32_e32 v64, 1.0, v64
	v_add_f32_e32 v69, 1.0, v69
	v_add_f32_e32 v65, 1.0, v65
	v_add_f32_e32 v70, 1.0, v70
	v_add_f32_e32 v66, 1.0, v66
	v_add_f32_e32 v71, 1.0, v71
	v_add_f32_e32 v67, 1.0, v67
	v_add_f32_e32 v68, 1.0, v68
	v_rcp_f32_e32 v64, v64
	v_rcp_f32_e32 v69, v69
	v_rcp_f32_e32 v65, v65
	v_rcp_f32_e32 v70, v70
	v_rcp_f32_e32 v66, v66
	v_rcp_f32_e32 v71, v71
	v_rcp_f32_e32 v67, v67
	v_rcp_f32_e32 v68, v68
	v_lshlrev_b32_e32 v90, 16, v76
	v_and_b32_e32 v76, 0xffff0000, v76
	v_lshlrev_b32_e32 v91, 16, v77
	v_and_b32_e32 v77, 0xffff0000, v77
	v_lshlrev_b32_e32 v92, 16, v78
	v_and_b32_e32 v78, 0xffff0000, v78
	v_lshlrev_b32_e32 v93, 16, v79
	v_and_b32_e32 v79, 0xffff0000, v79
	v_mul_f32_e32 v72, v64, v92
	v_mul_f32_e32 v64, v69, v76
	v_mul_f32_e32 v69, v65, v78
	v_mul_f32_e32 v65, v70, v91
	v_mul_f32_e32 v70, v66, v93
	v_mul_f32_e32 v66, v71, v77
	v_mul_f32_e32 v67, v67, v79
	v_mul_f32_e32 v68, v68, v90
	v_cvt_pk_bf16_f32 v64, v68, v64
	v_cvt_pk_bf16_f32 v65, v65, v66
	v_cvt_pk_bf16_f32 v66, v72, v69
	v_cvt_pk_bf16_f32 v67, v70, v67
	global_store_dwordx4 v[84:85], v[64:67], off offset:1280
	s_nop 0
	s_nop 0
	v_mov_b32_e32 v64, v166
	v_mov_b32_e32 v65, v167
	v_mov_b32_e32 v66, v168
	v_mov_b32_e32 v67, v169
	v_mov_b32_e32 v72, v190
	v_mov_b32_e32 v73, v191
	v_mov_b32_e32 v74, v192
	v_mov_b32_e32 v75, v193
	global_load_dwordx4 v[202:205], v[88:89], off
	global_load_dwordx4 v[214:217], v[88:89], off offset:256
	v_add_u32_e32 v178, 0x90, v132
	v_ashrrev_i32_e32 v179, 31, v178
	v_lshlrev_b64 v[180:181], 10, v[178:179]
	v_lshl_add_u64 v[180:181], s[30:31], 0, v[180:181]
	v_lshl_add_u64 v[180:181], v[180:181], 0, v[130:131]
	global_load_dwordx4 v[218:221], v[180:181], off
	v_add_u32_e32 v178, 0x90, v132
	v_ashrrev_i32_e32 v179, 31, v178
	v_lshlrev_b64 v[180:181], 10, v[178:179]
	v_lshl_add_u64 v[180:181], s[30:31], 0, v[180:181]
	v_lshl_add_u64 v[180:181], v[180:181], 0, v[130:131]
	global_load_dwordx4 v[222:225], v[180:181], off offset:256
	v_add_u32_e32 v178, 0xa0, v132
	v_ashrrev_i32_e32 v179, 31, v178
	v_lshlrev_b64 v[180:181], 10, v[178:179]
	v_lshl_add_u64 v[180:181], s[30:31], 0, v[180:181]
	v_lshl_add_u64 v[180:181], v[180:181], 0, v[130:131]
	global_load_dwordx4 v[226:229], v[180:181], off
	v_add_u32_e32 v178, 0xa0, v132
	v_ashrrev_i32_e32 v179, 31, v178
	v_lshlrev_b64 v[180:181], 10, v[178:179]
	v_lshl_add_u64 v[180:181], s[30:31], 0, v[180:181]
	v_lshl_add_u64 v[180:181], v[180:181], 0, v[130:131]
	global_load_dwordx4 v[230:233], v[180:181], off offset:256
	v_add_u32_e32 v178, 0xb0, v132
	v_ashrrev_i32_e32 v179, 31, v178
	v_lshlrev_b64 v[180:181], 10, v[178:179]
	v_lshl_add_u64 v[180:181], s[30:31], 0, v[180:181]
	v_lshl_add_u64 v[180:181], v[180:181], 0, v[130:131]
	global_load_dwordx4 v[234:237], v[180:181], off
	v_add_u32_e32 v178, 0xb0, v132
	v_ashrrev_i32_e32 v179, 31, v178
	v_lshlrev_b64 v[180:181], 10, v[178:179]
	v_lshl_add_u64 v[180:181], s[30:31], 0, v[180:181]
	v_lshl_add_u64 v[180:181], v[180:181], 0, v[130:131]
	global_load_dwordx4 v[238:241], v[180:181], off offset:256
	s_waitcnt vmcnt(0)
; __device__ __forceinline__ unsigned cvt_pk_bf16(float lo, float hi) { unsigned r; asm volatile("v_cvt_pk_bf16_f32 %0, %1, %2" : "=v"(r) : "v"(lo), "v"(hi)); return r; }
; __device__ __forceinline__ float sigm(float x) { return __builtin_amdgcn_rcpf(1.0f + __expf(-x)); }
; __device__ __forceinline__ void UNPACK8(const u32x4 q, float (&f)[8]) { f[0] = bflo(q.x); f[1] = bfhi(q.x); f[2] = bflo(q.y); f[3] = bfhi(q.y); f[4] = bflo(q.z); f[5] = bfhi(q.z); f[6] = bflo(q.w); f[7] = bfhi(q.w); }
; #define EPI_FOR_ROWS() _Pragma("unroll") for (int ai = 0; ai < 2; ++ai) _Pragma("unroll") for (int m = 0; m < 4; ++m)
;     __device__ __forceinline__ void operator()(const f32x4 (&acc)[2][2][4][2], const Unit& u, int wr, int wc, int fr, int fq) const {
;         EPI_ROWCOL();
;         EPI_FOR_ROWS() {
;             const int row = row0 + ai * 128 + m * 16;
; #pragma unroll
;             for (int bj = 0; bj < 2; ++bj) { const int col = col0 + bj * 128;
;                 const f32x4 b0 = *(const f32x4*)(gb + col), b1 = *(const f32x4*)(gb + col + 4);
;                 const u32x4 yw = *(const u32x4*)(yg + (size_t)row * 512 + col); float y[8]; UNPACK8(yw, y);
;                 const f32x4 a0 = acc[ai][bj][m][0] + b0, a1 = acc[ai][bj][m][1] + b1; float o[8];
; #pragma unroll
;                 for (int e = 0; e < 4; ++e) { o[e] = y[e] * sigm(a0[e]); o[4 + e] = y[4 + e] * sigm(a1[e]); }
;                 u32x4 w; w.x = cvt_pk_bf16(o[0], o[1]); w.y = cvt_pk_bf16(o[2], o[3]); w.z = cvt_pk_bf16(o[4], o[5]); w.w = cvt_pk_bf16(o[6], o[7]);
;                 *(u32x4*)(mix + (size_t)row * 1024 + 512 + col) = w; }
;         }
;     }
	v_mov_b32_e32 v68, v202
	v_mov_b32_e32 v69, v203
	v_mov_b32_e32 v70, v204
	v_mov_b32_e32 v71, v205
	v_add_f32_e32 v61, v61, v65
	v_add_f32_e32 v56, v56, v72
	v_add_f32_e32 v57, v57, v73
	v_add_f32_e32 v62, v62, v66
	v_add_f32_e32 v58, v58, v74
	v_add_f32_e32 v63, v63, v67
	v_add_f32_e32 v60, v60, v64
	v_mul_f32_e32 v56, 0xbfb8aa3b, v56
	v_mul_f32_e32 v61, 0xbfb8aa3b, v61
	v_mul_f32_e32 v57, 0xbfb8aa3b, v57
	v_mul_f32_e32 v62, 0xbfb8aa3b, v62
	v_mul_f32_e32 v58, 0xbfb8aa3b, v58
	v_mul_f32_e32 v63, 0xbfb8aa3b, v63
	v_mul_f32_e32 v60, 0xbfb8aa3b, v60
	v_exp_f32_e32 v56, v56
	v_exp_f32_e32 v61, v61
	v_exp_f32_e32 v57, v57
	v_exp_f32_e32 v62, v62
	v_exp_f32_e32 v58, v58
	v_exp_f32_e32 v63, v63
	v_add_f32_e32 v59, v59, v75
	v_exp_f32_e32 v60, v60
	v_mul_f32_e32 v59, 0xbfb8aa3b, v59
	v_exp_f32_e32 v59, v59
	v_add_f32_e32 v56, 1.0, v56
	v_add_f32_e32 v61, 1.0, v61
	v_add_f32_e32 v57, 1.0, v57
	v_add_f32_e32 v62, 1.0, v62
	v_add_f32_e32 v58, 1.0, v58
	v_add_f32_e32 v63, 1.0, v63
	v_add_f32_e32 v60, 1.0, v60
	v_rcp_f32_e32 v56, v56
	v_rcp_f32_e32 v61, v61
	v_rcp_f32_e32 v57, v57
	v_rcp_f32_e32 v62, v62
	v_rcp_f32_e32 v58, v58
	v_rcp_f32_e32 v63, v63
	v_rcp_f32_e32 v60, v60
	v_add_f32_e32 v59, 1.0, v59
	v_lshlrev_b32_e32 v76, 16, v68
	v_and_b32_e32 v68, 0xffff0000, v68
	v_lshlrev_b32_e32 v77, 16, v69
	v_and_b32_e32 v69, 0xffff0000, v69
	v_lshlrev_b32_e32 v78, 16, v70
	v_and_b32_e32 v70, 0xffff0000, v70
	v_lshlrev_b32_e32 v79, 16, v71
	v_rcp_f32_e32 v59, v59
	v_mul_f32_e32 v64, v56, v78
	v_mul_f32_e32 v56, v61, v68
	v_mul_f32_e32 v61, v57, v70
	v_mul_f32_e32 v57, v62, v77
	v_mul_f32_e32 v62, v58, v79
	v_mul_f32_e32 v58, v63, v69
	v_mul_f32_e32 v60, v60, v76
	v_cvt_pk_bf16_f32 v56, v60, v56
	v_cvt_pk_bf16_f32 v57, v57, v58
	v_cvt_pk_bf16_f32 v58, v64, v61
	v_lshlrev_b64 v[64:65], 11, v[86:87]
	v_and_b32_e32 v71, 0xffff0000, v71
	v_lshl_add_u64 v[64:65], s[26:27], 0, v[64:65]
	v_mul_f32_e32 v59, v59, v71
	v_lshl_add_u64 v[68:69], v[64:65], 0, v[130:131]
	v_cvt_pk_bf16_f32 v59, v62, v59
	global_store_dwordx4 v[68:69], v[56:59], off offset:1024
	v_mov_b32_e32 v60, v214
	v_mov_b32_e32 v61, v215
	v_mov_b32_e32 v62, v216
	v_mov_b32_e32 v63, v217
	s_nop 0
	v_mov_b32_e32 v56, v194
	v_mov_b32_e32 v57, v195
	v_mov_b32_e32 v58, v196
	v_mov_b32_e32 v59, v197
	v_mov_b32_e32 v64, v198
	v_mov_b32_e32 v65, v199
	v_mov_b32_e32 v66, v200
	v_mov_b32_e32 v67, v201
	v_add_u32_e32 v70, 0x90, v132
	v_ashrrev_i32_e32 v71, 31, v70
	v_lshlrev_b64 v[72:73], 10, v[70:71]
	v_lshl_add_u64 v[72:73], s[30:31], 0, v[72:73]
	v_lshl_add_u64 v[72:73], v[72:73], 0, v[130:131]
	v_add_f32_e32 v53, v53, v57
	v_add_f32_e32 v48, v48, v64
	v_add_f32_e32 v49, v49, v65
	v_add_f32_e32 v54, v54, v58
	v_add_f32_e32 v50, v50, v66
	v_add_f32_e32 v55, v55, v59
	v_add_f32_e32 v51, v51, v67
	v_add_f32_e32 v52, v52, v56
	v_mul_f32_e32 v48, 0xbfb8aa3b, v48
	v_mul_f32_e32 v53, 0xbfb8aa3b, v53
	v_mul_f32_e32 v49, 0xbfb8aa3b, v49
	v_mul_f32_e32 v54, 0xbfb8aa3b, v54
	v_mul_f32_e32 v50, 0xbfb8aa3b, v50
	v_mul_f32_e32 v55, 0xbfb8aa3b, v55
	v_mul_f32_e32 v51, 0xbfb8aa3b, v51
	v_mul_f32_e32 v52, 0xbfb8aa3b, v52
	v_exp_f32_e32 v48, v48
	v_exp_f32_e32 v53, v53
	v_exp_f32_e32 v49, v49
	v_exp_f32_e32 v54, v54
	v_exp_f32_e32 v50, v50
	v_exp_f32_e32 v55, v55
	v_exp_f32_e32 v51, v51
	v_exp_f32_e32 v52, v52
	v_add_f32_e32 v48, 1.0, v48
	v_add_f32_e32 v53, 1.0, v53
	v_add_f32_e32 v49, 1.0, v49
	v_add_f32_e32 v54, 1.0, v54
	v_add_f32_e32 v50, 1.0, v50
	v_add_f32_e32 v55, 1.0, v55
	v_add_f32_e32 v51, 1.0, v51
	v_add_f32_e32 v52, 1.0, v52
	v_rcp_f32_e32 v48, v48
	v_rcp_f32_e32 v53, v53
	v_rcp_f32_e32 v49, v49
	v_rcp_f32_e32 v54, v54
	v_rcp_f32_e32 v50, v50
	v_rcp_f32_e32 v55, v55
	v_rcp_f32_e32 v51, v51
	v_rcp_f32_e32 v52, v52
	v_lshlrev_b32_e32 v74, 16, v60
	v_and_b32_e32 v60, 0xffff0000, v60
	v_lshlrev_b32_e32 v75, 16, v61
	v_and_b32_e32 v61, 0xffff0000, v61
	v_lshlrev_b32_e32 v76, 16, v62
	v_and_b32_e32 v62, 0xffff0000, v62
	v_lshlrev_b32_e32 v77, 16, v63
	v_and_b32_e32 v63, 0xffff0000, v63
	v_mul_f32_e32 v56, v48, v76
	v_mul_f32_e32 v48, v53, v60
	v_mul_f32_e32 v53, v49, v62
	v_mul_f32_e32 v49, v54, v75
	v_mul_f32_e32 v54, v50, v77
	v_mul_f32_e32 v50, v55, v61
	v_mul_f32_e32 v51, v51, v63
	v_mul_f32_e32 v52, v52, v74
	v_cvt_pk_bf16_f32 v48, v52, v48
	v_cvt_pk_bf16_f32 v49, v49, v50
	v_cvt_pk_bf16_f32 v50, v56, v53
	v_cvt_pk_bf16_f32 v51, v54, v51
	global_store_dwordx4 v[68:69], v[48:51], off offset:1280
	v_mov_b32_e32 v52, v218
	v_mov_b32_e32 v53, v219
	v_mov_b32_e32 v54, v220
	v_mov_b32_e32 v55, v221
	s_nop 0
	v_mov_b32_e32 v48, v166
	v_mov_b32_e32 v49, v167
	v_mov_b32_e32 v50, v168
	v_mov_b32_e32 v51, v169
	v_mov_b32_e32 v56, v190
	v_mov_b32_e32 v57, v191
	v_mov_b32_e32 v58, v192
	v_mov_b32_e32 v59, v193
	v_add_f32_e32 v45, v45, v49
	v_add_f32_e32 v40, v40, v56
	v_add_f32_e32 v41, v41, v57
	v_add_f32_e32 v46, v46, v50
	v_add_f32_e32 v42, v42, v58
	v_add_f32_e32 v47, v47, v51
	v_add_f32_e32 v44, v44, v48
	v_mul_f32_e32 v40, 0xbfb8aa3b, v40
	v_mul_f32_e32 v45, 0xbfb8aa3b, v45
	v_mul_f32_e32 v41, 0xbfb8aa3b, v41
	v_mul_f32_e32 v46, 0xbfb8aa3b, v46
	v_mul_f32_e32 v42, 0xbfb8aa3b, v42
	v_mul_f32_e32 v47, 0xbfb8aa3b, v47
	v_mul_f32_e32 v44, 0xbfb8aa3b, v44
	v_exp_f32_e32 v40, v40
	v_exp_f32_e32 v45, v45
	v_exp_f32_e32 v41, v41
	v_exp_f32_e32 v46, v46
	v_exp_f32_e32 v42, v42
	v_exp_f32_e32 v47, v47
	v_add_f32_e32 v43, v43, v59
	v_exp_f32_e32 v44, v44
	v_mul_f32_e32 v43, 0xbfb8aa3b, v43
	v_exp_f32_e32 v43, v43
	v_add_f32_e32 v40, 1.0, v40
	v_add_f32_e32 v45, 1.0, v45
	v_add_f32_e32 v41, 1.0, v41
	v_add_f32_e32 v46, 1.0, v46
	v_add_f32_e32 v42, 1.0, v42
	v_add_f32_e32 v47, 1.0, v47
	v_add_f32_e32 v44, 1.0, v44
; __device__ __forceinline__ unsigned cvt_pk_bf16(float lo, float hi) { unsigned r; asm volatile("v_cvt_pk_bf16_f32 %0, %1, %2" : "=v"(r) : "v"(lo), "v"(hi)); return r; }
; __device__ __forceinline__ float sigm(float x) { return __builtin_amdgcn_rcpf(1.0f + __expf(-x)); }
; __device__ __forceinline__ void UNPACK8(const u32x4 q, float (&f)[8]) { f[0] = bflo(q.x); f[1] = bfhi(q.x); f[2] = bflo(q.y); f[3] = bfhi(q.y); f[4] = bflo(q.z); f[5] = bfhi(q.z); f[6] = bflo(q.w); f[7] = bfhi(q.w); }
; #define EPI_FOR_ROWS() _Pragma("unroll") for (int ai = 0; ai < 2; ++ai) _Pragma("unroll") for (int m = 0; m < 4; ++m)
;     __device__ __forceinline__ void operator()(const f32x4 (&acc)[2][2][4][2], const Unit& u, int wr, int wc, int fr, int fq) const {
;         EPI_ROWCOL();
;         EPI_FOR_ROWS() {
;             const int row = row0 + ai * 128 + m * 16;
; #pragma unroll
;             for (int bj = 0; bj < 2; ++bj) { const int col = col0 + bj * 128;
;                 const f32x4 b0 = *(const f32x4*)(gb + col), b1 = *(const f32x4*)(gb + col + 4);
;                 const u32x4 yw = *(const u32x4*)(yg + (size_t)row * 512 + col); float y[8]; UNPACK8(yw, y);
;                 const f32x4 a0 = acc[ai][bj][m][0] + b0, a1 = acc[ai][bj][m][1] + b1; float o[8];
; #pragma unroll
;                 for (int e = 0; e < 4; ++e) { o[e] = y[e] * sigm(a0[e]); o[4 + e] = y[4 + e] * sigm(a1[e]); }
;                 u32x4 w; w.x = cvt_pk_bf16(o[0], o[1]); w.y = cvt_pk_bf16(o[2], o[3]); w.z = cvt_pk_bf16(o[4], o[5]); w.w = cvt_pk_bf16(o[6], o[7]);
;                 *(u32x4*)(mix + (size_t)row * 1024 + 512 + col) = w; }
;         }
;     }
	v_rcp_f32_e32 v40, v40
	v_rcp_f32_e32 v45, v45
	v_rcp_f32_e32 v41, v41
	v_rcp_f32_e32 v46, v46
	v_rcp_f32_e32 v42, v42
	v_rcp_f32_e32 v47, v47
	v_rcp_f32_e32 v44, v44
	v_add_f32_e32 v43, 1.0, v43
	v_lshlrev_b32_e32 v60, 16, v52
	v_and_b32_e32 v52, 0xffff0000, v52
	v_lshlrev_b32_e32 v61, 16, v53
	v_and_b32_e32 v53, 0xffff0000, v53
	v_lshlrev_b32_e32 v62, 16, v54
	v_and_b32_e32 v54, 0xffff0000, v54
	v_lshlrev_b32_e32 v63, 16, v55
	v_rcp_f32_e32 v43, v43
	v_mul_f32_e32 v48, v40, v62
	v_mul_f32_e32 v40, v45, v52
	v_mul_f32_e32 v45, v41, v54
	v_mul_f32_e32 v41, v46, v61
	v_mul_f32_e32 v46, v42, v63
	v_mul_f32_e32 v42, v47, v53
	v_mul_f32_e32 v44, v44, v60
	v_cvt_pk_bf16_f32 v40, v44, v40
	v_cvt_pk_bf16_f32 v41, v41, v42
	v_cvt_pk_bf16_f32 v42, v48, v45
	v_lshlrev_b64 v[48:49], 11, v[70:71]
	v_and_b32_e32 v55, 0xffff0000, v55
	v_lshl_add_u64 v[48:49], s[26:27], 0, v[48:49]
	v_mul_f32_e32 v43, v43, v55
	v_lshl_add_u64 v[52:53], v[48:49], 0, v[130:131]
	v_cvt_pk_bf16_f32 v43, v46, v43
	global_store_dwordx4 v[52:53], v[40:43], off offset:1024
	v_mov_b32_e32 v44, v222
	v_mov_b32_e32 v45, v223
	v_mov_b32_e32 v46, v224
	v_mov_b32_e32 v47, v225
	s_nop 0
	v_mov_b32_e32 v40, v194
	v_mov_b32_e32 v41, v195
	v_mov_b32_e32 v42, v196
	v_mov_b32_e32 v43, v197
	v_mov_b32_e32 v48, v198
	v_mov_b32_e32 v49, v199
	v_mov_b32_e32 v50, v200
	v_mov_b32_e32 v51, v201
	v_add_u32_e32 v54, 0xa0, v132
	v_ashrrev_i32_e32 v55, 31, v54
	v_lshlrev_b64 v[56:57], 10, v[54:55]
	v_lshl_add_u64 v[56:57], s[30:31], 0, v[56:57]
	v_lshl_add_u64 v[56:57], v[56:57], 0, v[130:131]
	v_add_f32_e32 v37, v37, v41
	v_add_f32_e32 v32, v32, v48
	v_add_f32_e32 v33, v33, v49
	v_add_f32_e32 v38, v38, v42
	v_add_f32_e32 v34, v34, v50
	v_add_f32_e32 v39, v39, v43
	v_add_f32_e32 v35, v35, v51
	v_add_f32_e32 v36, v36, v40
	v_mul_f32_e32 v32, 0xbfb8aa3b, v32
	v_mul_f32_e32 v37, 0xbfb8aa3b, v37
	v_mul_f32_e32 v33, 0xbfb8aa3b, v33
	v_mul_f32_e32 v38, 0xbfb8aa3b, v38
	v_mul_f32_e32 v34, 0xbfb8aa3b, v34
	v_mul_f32_e32 v39, 0xbfb8aa3b, v39
	v_mul_f32_e32 v35, 0xbfb8aa3b, v35
	v_mul_f32_e32 v36, 0xbfb8aa3b, v36
	v_exp_f32_e32 v32, v32
	v_exp_f32_e32 v37, v37
	v_exp_f32_e32 v33, v33
	v_exp_f32_e32 v38, v38
	v_exp_f32_e32 v34, v34
	v_exp_f32_e32 v39, v39
	v_exp_f32_e32 v35, v35
	v_exp_f32_e32 v36, v36
	v_add_f32_e32 v32, 1.0, v32
	v_add_f32_e32 v37, 1.0, v37
	v_add_f32_e32 v33, 1.0, v33
	v_add_f32_e32 v38, 1.0, v38
	v_add_f32_e32 v34, 1.0, v34
	v_add_f32_e32 v39, 1.0, v39
	v_add_f32_e32 v35, 1.0, v35
	v_add_f32_e32 v36, 1.0, v36
	v_rcp_f32_e32 v32, v32
	v_rcp_f32_e32 v37, v37
	v_rcp_f32_e32 v33, v33
	v_rcp_f32_e32 v38, v38
	v_rcp_f32_e32 v34, v34
	v_rcp_f32_e32 v39, v39
	v_rcp_f32_e32 v35, v35
	v_rcp_f32_e32 v36, v36
	v_lshlrev_b32_e32 v58, 16, v44
	v_and_b32_e32 v44, 0xffff0000, v44
	v_lshlrev_b32_e32 v59, 16, v45
	v_and_b32_e32 v45, 0xffff0000, v45
	v_lshlrev_b32_e32 v60, 16, v46
	v_and_b32_e32 v46, 0xffff0000, v46
	v_lshlrev_b32_e32 v61, 16, v47
	v_and_b32_e32 v47, 0xffff0000, v47
	v_mul_f32_e32 v40, v32, v60
	v_mul_f32_e32 v32, v37, v44
	v_mul_f32_e32 v37, v33, v46
	v_mul_f32_e32 v33, v38, v59
	v_mul_f32_e32 v38, v34, v61
	v_mul_f32_e32 v34, v39, v45
	v_mul_f32_e32 v35, v35, v47
	v_mul_f32_e32 v36, v36, v58
	v_cvt_pk_bf16_f32 v32, v36, v32
	v_cvt_pk_bf16_f32 v33, v33, v34
	v_cvt_pk_bf16_f32 v34, v40, v37
	v_cvt_pk_bf16_f32 v35, v38, v35
	global_store_dwordx4 v[52:53], v[32:35], off offset:1280
	v_mov_b32_e32 v36, v226
	v_mov_b32_e32 v37, v227
	v_mov_b32_e32 v38, v228
	v_mov_b32_e32 v39, v229
	s_nop 0
	v_mov_b32_e32 v32, v166
	v_mov_b32_e32 v33, v167
	v_mov_b32_e32 v34, v168
	v_mov_b32_e32 v35, v169
	v_mov_b32_e32 v40, v190
	v_mov_b32_e32 v41, v191
	v_mov_b32_e32 v42, v192
	v_mov_b32_e32 v43, v193
	v_add_f32_e32 v29, v29, v33
	v_add_f32_e32 v24, v24, v40
	v_add_f32_e32 v25, v25, v41
	v_add_f32_e32 v30, v30, v34
	v_add_f32_e32 v26, v26, v42
	v_add_f32_e32 v31, v31, v35
	v_add_f32_e32 v28, v28, v32
	v_mul_f32_e32 v24, 0xbfb8aa3b, v24
	v_mul_f32_e32 v29, 0xbfb8aa3b, v29
	v_mul_f32_e32 v25, 0xbfb8aa3b, v25
	v_mul_f32_e32 v30, 0xbfb8aa3b, v30
	v_mul_f32_e32 v26, 0xbfb8aa3b, v26
	v_mul_f32_e32 v31, 0xbfb8aa3b, v31
	v_mul_f32_e32 v28, 0xbfb8aa3b, v28
	v_exp_f32_e32 v24, v24
	v_exp_f32_e32 v29, v29
	v_exp_f32_e32 v25, v25
	v_exp_f32_e32 v30, v30
	v_exp_f32_e32 v26, v26
	v_exp_f32_e32 v31, v31
	v_add_f32_e32 v27, v27, v43
	v_exp_f32_e32 v28, v28
	v_mul_f32_e32 v27, 0xbfb8aa3b, v27
	v_exp_f32_e32 v27, v27
	v_add_f32_e32 v24, 1.0, v24
	v_add_f32_e32 v29, 1.0, v29
	v_add_f32_e32 v25, 1.0, v25
	v_add_f32_e32 v30, 1.0, v30
	v_add_f32_e32 v26, 1.0, v26
	v_add_f32_e32 v31, 1.0, v31
	v_add_f32_e32 v28, 1.0, v28
	v_rcp_f32_e32 v24, v24
	v_rcp_f32_e32 v29, v29
	v_rcp_f32_e32 v25, v25
	v_rcp_f32_e32 v30, v30
	v_rcp_f32_e32 v26, v26
	v_rcp_f32_e32 v31, v31
	v_rcp_f32_e32 v28, v28
	v_add_f32_e32 v27, 1.0, v27
	v_lshlrev_b32_e32 v44, 16, v36
	v_and_b32_e32 v36, 0xffff0000, v36
	v_lshlrev_b32_e32 v45, 16, v37
	v_and_b32_e32 v37, 0xffff0000, v37
	v_lshlrev_b32_e32 v46, 16, v38
	v_and_b32_e32 v38, 0xffff0000, v38
	v_lshlrev_b32_e32 v47, 16, v39
	v_rcp_f32_e32 v27, v27
	v_mul_f32_e32 v32, v24, v46
	v_mul_f32_e32 v24, v29, v36
	v_mul_f32_e32 v29, v25, v38
	v_mul_f32_e32 v25, v30, v45
	v_mul_f32_e32 v30, v26, v47
	v_mul_f32_e32 v26, v31, v37
	v_mul_f32_e32 v28, v28, v44
	v_cvt_pk_bf16_f32 v24, v28, v24
	v_cvt_pk_bf16_f32 v25, v25, v26
	v_cvt_pk_bf16_f32 v26, v32, v29
	v_lshlrev_b64 v[32:33], 11, v[54:55]
	v_and_b32_e32 v39, 0xffff0000, v39
	v_lshl_add_u64 v[32:33], s[26:27], 0, v[32:33]
	v_mul_f32_e32 v27, v27, v39
	v_lshl_add_u64 v[36:37], v[32:33], 0, v[130:131]
	v_cvt_pk_bf16_f32 v27, v30, v27
	global_store_dwordx4 v[36:37], v[24:27], off offset:1024
; __device__ __forceinline__ unsigned cvt_pk_bf16(float lo, float hi) { unsigned r; asm volatile("v_cvt_pk_bf16_f32 %0, %1, %2" : "=v"(r) : "v"(lo), "v"(hi)); return r; }
; __device__ __forceinline__ float sigm(float x) { return __builtin_amdgcn_rcpf(1.0f + __expf(-x)); }
; __device__ __forceinline__ void UNPACK8(const u32x4 q, float (&f)[8]) { f[0] = bflo(q.x); f[1] = bfhi(q.x); f[2] = bflo(q.y); f[3] = bfhi(q.y); f[4] = bflo(q.z); f[5] = bfhi(q.z); f[6] = bflo(q.w); f[7] = bfhi(q.w); }
; #define EPI_FOR_ROWS() _Pragma("unroll") for (int ai = 0; ai < 2; ++ai) _Pragma("unroll") for (int m = 0; m < 4; ++m)
;     __device__ __forceinline__ void operator()(const f32x4 (&acc)[2][2][4][2], const Unit& u, int wr, int wc, int fr, int fq) const {
;         EPI_ROWCOL();
;         EPI_FOR_ROWS() {
;             const int row = row0 + ai * 128 + m * 16;
; #pragma unroll
;             for (int bj = 0; bj < 2; ++bj) { const int col = col0 + bj * 128;
;                 const f32x4 b0 = *(const f32x4*)(gb + col), b1 = *(const f32x4*)(gb + col + 4);
;                 const u32x4 yw = *(const u32x4*)(yg + (size_t)row * 512 + col); float y[8]; UNPACK8(yw, y);
;                 const f32x4 a0 = acc[ai][bj][m][0] + b0, a1 = acc[ai][bj][m][1] + b1; float o[8];
; #pragma unroll
;                 for (int e = 0; e < 4; ++e) { o[e] = y[e] * sigm(a0[e]); o[4 + e] = y[4 + e] * sigm(a1[e]); }
;                 u32x4 w; w.x = cvt_pk_bf16(o[0], o[1]); w.y = cvt_pk_bf16(o[2], o[3]); w.z = cvt_pk_bf16(o[4], o[5]); w.w = cvt_pk_bf16(o[6], o[7]);
;                 *(u32x4*)(mix + (size_t)row * 1024 + 512 + col) = w; }
;         }
;     }
	v_mov_b32_e32 v28, v230
	v_mov_b32_e32 v29, v231
	v_mov_b32_e32 v30, v232
	v_mov_b32_e32 v31, v233
	s_nop 0
	v_mov_b32_e32 v24, v194
	v_mov_b32_e32 v25, v195
	v_mov_b32_e32 v26, v196
	v_mov_b32_e32 v27, v197
	v_mov_b32_e32 v32, v198
	v_mov_b32_e32 v33, v199
	v_mov_b32_e32 v34, v200
	v_mov_b32_e32 v35, v201
	v_add_u32_e32 v38, 0xb0, v132
	v_ashrrev_i32_e32 v39, 31, v38
	v_lshlrev_b64 v[40:41], 10, v[38:39]
	v_lshl_add_u64 v[40:41], s[30:31], 0, v[40:41]
	v_lshl_add_u64 v[40:41], v[40:41], 0, v[130:131]
	v_add_f32_e32 v21, v21, v25
	v_add_f32_e32 v16, v16, v32
	v_add_f32_e32 v17, v17, v33
	v_add_f32_e32 v22, v22, v26
	v_add_f32_e32 v18, v18, v34
	v_add_f32_e32 v23, v23, v27
	v_add_f32_e32 v19, v19, v35
	v_add_f32_e32 v20, v20, v24
	v_mul_f32_e32 v16, 0xbfb8aa3b, v16
	v_mul_f32_e32 v21, 0xbfb8aa3b, v21
	v_mul_f32_e32 v17, 0xbfb8aa3b, v17
	v_mul_f32_e32 v22, 0xbfb8aa3b, v22
	v_mul_f32_e32 v18, 0xbfb8aa3b, v18
	v_mul_f32_e32 v23, 0xbfb8aa3b, v23
	v_mul_f32_e32 v19, 0xbfb8aa3b, v19
	v_mul_f32_e32 v20, 0xbfb8aa3b, v20
	v_exp_f32_e32 v16, v16
	v_exp_f32_e32 v21, v21
	v_exp_f32_e32 v17, v17
	v_exp_f32_e32 v22, v22
	v_exp_f32_e32 v18, v18
	v_exp_f32_e32 v23, v23
	v_exp_f32_e32 v19, v19
	v_exp_f32_e32 v20, v20
	v_add_f32_e32 v16, 1.0, v16
	v_add_f32_e32 v21, 1.0, v21
	v_add_f32_e32 v17, 1.0, v17
	v_add_f32_e32 v22, 1.0, v22
	v_add_f32_e32 v18, 1.0, v18
	v_add_f32_e32 v23, 1.0, v23
	v_add_f32_e32 v19, 1.0, v19
	v_add_f32_e32 v20, 1.0, v20
	v_rcp_f32_e32 v16, v16
	v_rcp_f32_e32 v21, v21
	v_rcp_f32_e32 v17, v17
	v_rcp_f32_e32 v22, v22
	v_rcp_f32_e32 v18, v18
	v_rcp_f32_e32 v23, v23
	v_rcp_f32_e32 v19, v19
	v_rcp_f32_e32 v20, v20
	v_lshlrev_b32_e32 v42, 16, v28
	v_and_b32_e32 v28, 0xffff0000, v28
	v_lshlrev_b32_e32 v43, 16, v29
	v_and_b32_e32 v29, 0xffff0000, v29
	v_lshlrev_b32_e32 v44, 16, v30
	v_and_b32_e32 v30, 0xffff0000, v30
	v_lshlrev_b32_e32 v45, 16, v31
	v_and_b32_e32 v31, 0xffff0000, v31
	v_mul_f32_e32 v24, v16, v44
	v_mul_f32_e32 v16, v21, v28
	v_mul_f32_e32 v21, v17, v30
	v_mul_f32_e32 v17, v22, v43
	v_mul_f32_e32 v22, v18, v45
	v_mul_f32_e32 v18, v23, v29
	v_mul_f32_e32 v19, v19, v31
	v_mul_f32_e32 v20, v20, v42
	v_cvt_pk_bf16_f32 v16, v20, v16
	v_cvt_pk_bf16_f32 v17, v17, v18
	v_cvt_pk_bf16_f32 v18, v24, v21
	v_cvt_pk_bf16_f32 v19, v22, v19
	global_store_dwordx4 v[36:37], v[16:19], off offset:1280
	v_mov_b32_e32 v20, v234
	v_mov_b32_e32 v21, v235
	v_mov_b32_e32 v22, v236
	v_mov_b32_e32 v23, v237
	s_nop 0
	v_mov_b32_e32 v16, v166
	v_mov_b32_e32 v17, v167
	v_mov_b32_e32 v18, v168
	v_mov_b32_e32 v19, v169
	v_mov_b32_e32 v24, v190
	v_mov_b32_e32 v25, v191
	v_mov_b32_e32 v26, v192
	v_mov_b32_e32 v27, v193
	v_add_f32_e32 v13, v13, v17
	v_add_f32_e32 v8, v8, v24
	v_add_f32_e32 v9, v9, v25
	v_add_f32_e32 v14, v14, v18
	v_add_f32_e32 v10, v10, v26
	v_add_f32_e32 v15, v15, v19
	v_add_f32_e32 v12, v12, v16
	v_mul_f32_e32 v8, 0xbfb8aa3b, v8
	v_mul_f32_e32 v13, 0xbfb8aa3b, v13
	v_mul_f32_e32 v9, 0xbfb8aa3b, v9
	v_mul_f32_e32 v14, 0xbfb8aa3b, v14
	v_mul_f32_e32 v10, 0xbfb8aa3b, v10
	v_mul_f32_e32 v15, 0xbfb8aa3b, v15
	v_mul_f32_e32 v12, 0xbfb8aa3b, v12
	v_exp_f32_e32 v8, v8
	v_exp_f32_e32 v13, v13
	v_exp_f32_e32 v9, v9
	v_exp_f32_e32 v14, v14
	v_exp_f32_e32 v10, v10
	v_exp_f32_e32 v15, v15
	v_add_f32_e32 v11, v11, v27
	v_exp_f32_e32 v12, v12
	v_mul_f32_e32 v11, 0xbfb8aa3b, v11
	v_exp_f32_e32 v11, v11
	v_add_f32_e32 v8, 1.0, v8
	v_add_f32_e32 v13, 1.0, v13
	v_add_f32_e32 v9, 1.0, v9
	v_add_f32_e32 v14, 1.0, v14
	v_add_f32_e32 v10, 1.0, v10
	v_add_f32_e32 v15, 1.0, v15
	v_add_f32_e32 v12, 1.0, v12
	v_rcp_f32_e32 v8, v8
	v_rcp_f32_e32 v13, v13
	v_rcp_f32_e32 v9, v9
	v_rcp_f32_e32 v14, v14
	v_rcp_f32_e32 v10, v10
	v_rcp_f32_e32 v15, v15
	v_rcp_f32_e32 v12, v12
	v_add_f32_e32 v11, 1.0, v11
	v_lshlrev_b32_e32 v28, 16, v20
	v_and_b32_e32 v20, 0xffff0000, v20
	v_lshlrev_b32_e32 v29, 16, v21
	v_and_b32_e32 v21, 0xffff0000, v21
	v_lshlrev_b32_e32 v30, 16, v22
	v_and_b32_e32 v22, 0xffff0000, v22
	v_lshlrev_b32_e32 v31, 16, v23
	v_rcp_f32_e32 v11, v11
	v_mul_f32_e32 v16, v8, v30
	v_mul_f32_e32 v8, v13, v20
	v_mul_f32_e32 v13, v9, v22
	v_mul_f32_e32 v9, v14, v29
	v_mul_f32_e32 v14, v10, v31
	v_mul_f32_e32 v10, v15, v21
	v_mul_f32_e32 v12, v12, v28
	v_cvt_pk_bf16_f32 v8, v12, v8
	v_cvt_pk_bf16_f32 v9, v9, v10
	v_cvt_pk_bf16_f32 v10, v16, v13
	v_lshlrev_b64 v[16:17], 11, v[38:39]
	v_and_b32_e32 v23, 0xffff0000, v23
	v_lshl_add_u64 v[16:17], s[26:27], 0, v[16:17]
	v_mul_f32_e32 v11, v11, v23
	v_lshl_add_u64 v[20:21], v[16:17], 0, v[130:131]
	v_cvt_pk_bf16_f32 v11, v14, v11
	global_store_dwordx4 v[20:21], v[8:11], off offset:1024
	v_mov_b32_e32 v12, v238
	v_mov_b32_e32 v13, v239
	v_mov_b32_e32 v14, v240
	v_mov_b32_e32 v15, v241
	s_nop 0
	v_mov_b32_e32 v8, v194
	v_mov_b32_e32 v9, v195
	v_mov_b32_e32 v10, v196
	v_mov_b32_e32 v11, v197
	v_mov_b32_e32 v16, v198
	v_mov_b32_e32 v17, v199
	v_mov_b32_e32 v18, v200
	v_mov_b32_e32 v19, v201
	v_add_f32_e32 v5, v5, v9
	v_add_f32_e32 v0, v0, v16
	v_add_f32_e32 v1, v1, v17
	v_add_f32_e32 v6, v6, v10
	v_add_f32_e32 v2, v2, v18
	v_add_f32_e32 v7, v7, v11
	v_add_f32_e32 v3, v3, v19
	v_add_f32_e32 v4, v4, v8
	v_mul_f32_e32 v0, 0xbfb8aa3b, v0
	v_mul_f32_e32 v5, 0xbfb8aa3b, v5
	v_mul_f32_e32 v1, 0xbfb8aa3b, v1
	v_mul_f32_e32 v6, 0xbfb8aa3b, v6
	v_mul_f32_e32 v2, 0xbfb8aa3b, v2
	v_mul_f32_e32 v7, 0xbfb8aa3b, v7
	v_mul_f32_e32 v3, 0xbfb8aa3b, v3
	v_mul_f32_e32 v4, 0xbfb8aa3b, v4
	v_exp_f32_e32 v0, v0
	v_exp_f32_e32 v5, v5
	v_exp_f32_e32 v1, v1
	v_exp_f32_e32 v6, v6
	v_exp_f32_e32 v2, v2
	v_exp_f32_e32 v7, v7
	v_exp_f32_e32 v3, v3
	v_exp_f32_e32 v4, v4
	v_add_f32_e32 v0, 1.0, v0
	v_add_f32_e32 v5, 1.0, v5
	v_add_f32_e32 v1, 1.0, v1
	v_add_f32_e32 v6, 1.0, v6
	v_add_f32_e32 v2, 1.0, v2
	v_add_f32_e32 v7, 1.0, v7
	v_add_f32_e32 v3, 1.0, v3
	v_add_f32_e32 v4, 1.0, v4
	v_rcp_f32_e32 v0, v0
	v_rcp_f32_e32 v5, v5
	v_rcp_f32_e32 v1, v1
	v_rcp_f32_e32 v6, v6
	v_rcp_f32_e32 v2, v2
	v_rcp_f32_e32 v7, v7
	v_rcp_f32_e32 v3, v3
	v_rcp_f32_e32 v4, v4
	v_lshlrev_b32_e32 v22, 16, v12
	v_and_b32_e32 v12, 0xffff0000, v12
	v_lshlrev_b32_e32 v23, 16, v13
	v_and_b32_e32 v13, 0xffff0000, v13
	v_lshlrev_b32_e32 v24, 16, v14
	v_and_b32_e32 v14, 0xffff0000, v14
	v_lshlrev_b32_e32 v25, 16, v15
	v_and_b32_e32 v15, 0xffff0000, v15
	v_mul_f32_e32 v8, v0, v24
	v_mul_f32_e32 v0, v5, v12
	v_mul_f32_e32 v5, v1, v14
	v_mul_f32_e32 v1, v6, v23
	v_mul_f32_e32 v6, v2, v25
	v_mul_f32_e32 v2, v7, v13
	v_mul_f32_e32 v3, v3, v15
	v_mul_f32_e32 v4, v4, v22
	v_cvt_pk_bf16_f32 v0, v4, v0
	v_cvt_pk_bf16_f32 v1, v1, v2
	v_cvt_pk_bf16_f32 v2, v8, v5
	v_cvt_pk_bf16_f32 v3, v6, v3
	global_store_dwordx4 v[20:21], v[0:3], off offset:1280
	s_cbranch_vccnz .LBB0_862
	s_andn2_b64 vcc, exec, s[0:1]
	s_cbranch_vccnz .LBB0_861
	s_barrier
	s_branch .LBB0_861
